# v29 + GEMM k-loop layout rotated: the post-barrier block (trailing MFMAs + first reads of the next tile) is the loop head, one conditional back branch per iteration instead of cond + unconditional
# baseline (speedup 1.0000x reference)
; DI f32x4 mfma16(bf16x8 a, bf16x8 b, f32x4 c) { return __builtin_amdgcn_mfma_f32_16x16x32_bf16(a, b, c, 0, 0, 0); }
; template <int MI, int NJ, bool SWAP, class AP, class BP>
; DI void gemm_main(f32x4 (&acc)[MI][NJ], const AP& ap, int a_kstep, const BP& bp, int b_kstep, int nk, bf16_t* smem) {
;     ...
;   gload(0); sstore(0); gload(nk > 1 ? 1 : 0); __syncthreads();
; #pragma unroll 1
;   for (int kt = 0; kt < nk; ++kt) {
;     const int buf = kt & 1;
;     sstore(buf ^ 1);
;     gload(kt + 2 < nk ? kt + 2 : nk - 1);
;     __builtin_amdgcn_sched_barrier(0);
;     const bf16_t* As = smem + buf * L::STAGE + (wm * 16 * MI + l15) * LDT + quad * 8;
;     const bf16_t* Bs = smem + buf * L::STAGE + L::A_ELEMS + (wn * 16 * NJ + l15) * LDT + quad * 8;
; #pragma unroll
;     for (int ks = 0; ks < 2; ++ks) {
;       if (MI * NJ >= 32 && ks == 1) asm volatile("" ::: "memory");
;       bf16x8 b[NJ];
; #pragma unroll
;       for (int j = 0; j < NJ; ++j) b[j] = *(const bf16x8*)(Bs + j * 16 * LDT + ks * 32);
; #pragma unroll
;       for (int i = 0; i < MI; ++i) {
;         const bf16x8 a = *(const bf16x8*)(As + i * 16 * LDT + ks * 32);
; #pragma unroll
;         for (int j = 0; j < NJ; ++j) acc[i][j] = SWAP ? mfma16(b[j], a, acc[i][j]) : mfma16(a, b[j], acc[i][j]);
;       }
;     }
;     __syncthreads();
;   }
.LBB0_174:
	s_and_b32 s98, s4, 1
	s_mul_i32 s98, s98, 0x12000
	v_add3_u32 v182, s98, v168, v172
	v_add3_u32 v176, s98, v170, v172
	ds_read_b128 v[212:215], v176
	ds_read_b128 v[216:219], v176 offset:2304
	ds_read_b128 v[178:181], v182 offset:36864
	ds_read_b128 v[200:203], v182 offset:39168
	ds_read_b128 v[204:207], v182 offset:41472
	ds_read_b128 v[208:211], v182 offset:43776
	s_branch .Lgm0_main
.Lgm0_top:
	ds_read_b128 v[212:215], v176
	ds_read_b128 v[216:219], v176 offset:2304
	v_mfma_f32_16x16x32_bf16 v[28:31], v[178:181], v[242:245], v[28:31]
	v_mfma_f32_16x16x32_bf16 v[12:15], v[178:181], v[246:249], v[12:15]
	ds_read_b128 v[178:181], v182 offset:36864
	v_mfma_f32_16x16x32_bf16 v[24:27], v[200:203], v[242:245], v[24:27]
	v_mfma_f32_16x16x32_bf16 v[8:11], v[200:203], v[246:249], v[8:11]
	ds_read_b128 v[200:203], v182 offset:39168
	v_mfma_f32_16x16x32_bf16 v[20:23], v[204:207], v[242:245], v[20:23]
	v_mfma_f32_16x16x32_bf16 v[0:3], v[204:207], v[246:249], v[0:3]
	ds_read_b128 v[204:207], v182 offset:41472
	v_mfma_f32_16x16x32_bf16 v[16:19], v[208:211], v[242:245], v[16:19]
	v_mfma_f32_16x16x32_bf16 v[4:7], v[208:211], v[246:249], v[4:7]
	ds_read_b128 v[208:211], v182 offset:43776
.Lgm0_main:
	ds_read_b128 v[242:245], v176 offset:4608
	s_waitcnt lgkmcnt(4)
	v_mfma_f32_16x16x32_bf16 v[124:127], v[178:181], v[212:215], v[124:127]
	s_waitcnt lgkmcnt(3)
	v_mfma_f32_16x16x32_bf16 v[120:123], v[200:203], v[212:215], v[120:123]
	s_waitcnt lgkmcnt(2)
	v_mfma_f32_16x16x32_bf16 v[116:119], v[204:207], v[212:215], v[116:119]
	s_and_b32 s5, s4, 1
	s_min_u32 s6, s4, 13
	s_xor_b32 s7, s5, 1
	s_mul_i32 s7, s7, 0x12000
	v_add3_u32 v250, s7, v171, v169
	s_waitcnt vmcnt(7)
	ds_write_b128 v250, v[128:131]
	s_waitcnt lgkmcnt(2)
	v_mfma_f32_16x16x32_bf16 v[112:115], v[208:211], v[212:215], v[112:115]
	ds_read_b128 v[246:249], v176 offset:6912
	v_mfma_f32_16x16x32_bf16 v[108:111], v[178:181], v[216:219], v[108:111]
	s_lshl_b32 s33, s6, 7
	s_add_u32 s6, s0, s33
	v_add3_u32 v251, s7, v173, v169
	v_add3_u32 v252, s7, v174, v169
	v_add3_u32 v253, s7, v175, v169
	s_addc_u32 s7, s1, 0
	v_lshl_add_u64 v[128:129], s[6:7], 0, v[160:161]
	s_nop 0
	global_load_dwordx4 v[128:131], v[128:129], off offset:256
	v_mfma_f32_16x16x32_bf16 v[104:107], v[200:203], v[216:219], v[104:107]
	v_mfma_f32_16x16x32_bf16 v[100:103], v[204:207], v[216:219], v[100:103]
	v_mfma_f32_16x16x32_bf16 v[96:99], v[208:211], v[216:219], v[96:99]
	ds_read_b128 v[212:215], v176 offset:9216
	s_waitcnt lgkmcnt(3)
	v_mfma_f32_16x16x32_bf16 v[92:95], v[178:181], v[242:245], v[92:95]
	s_waitcnt vmcnt(7)
	ds_write_b128 v251, v[132:135]
	v_mfma_f32_16x16x32_bf16 v[88:91], v[200:203], v[242:245], v[88:91]
	v_mfma_f32_16x16x32_bf16 v[84:87], v[204:207], v[242:245], v[84:87]
	v_lshl_add_u64 v[132:133], s[6:7], 0, v[162:163]
	s_nop 0
	global_load_dwordx4 v[132:135], v[132:133], off offset:256
	v_mfma_f32_16x16x32_bf16 v[80:83], v[208:211], v[242:245], v[80:83]
	ds_read_b128 v[216:219], v176 offset:11520
	s_waitcnt lgkmcnt(3)
	v_mfma_f32_16x16x32_bf16 v[76:79], v[178:181], v[246:249], v[76:79]
	v_mfma_f32_16x16x32_bf16 v[72:75], v[200:203], v[246:249], v[72:75]
	v_mfma_f32_16x16x32_bf16 v[68:71], v[204:207], v[246:249], v[68:71]
	s_waitcnt vmcnt(7)
	ds_write_b128 v252, v[136:139]
	v_mfma_f32_16x16x32_bf16 v[64:67], v[208:211], v[246:249], v[64:67]
	ds_read_b128 v[242:245], v176 offset:13824
	s_waitcnt lgkmcnt(4)
	v_mfma_f32_16x16x32_bf16 v[60:63], v[178:181], v[212:215], v[60:63]
	v_lshl_add_u64 v[136:137], s[6:7], 0, v[164:165]
	s_nop 0
	global_load_dwordx4 v[136:139], v[136:137], off offset:256
	v_mfma_f32_16x16x32_bf16 v[56:59], v[200:203], v[212:215], v[56:59]
	v_mfma_f32_16x16x32_bf16 v[52:55], v[204:207], v[212:215], v[52:55]
	v_mfma_f32_16x16x32_bf16 v[48:51], v[208:211], v[212:215], v[48:51]
	ds_read_b128 v[246:249], v176 offset:16128
	s_waitcnt lgkmcnt(3)
	v_mfma_f32_16x16x32_bf16 v[44:47], v[178:181], v[216:219], v[44:47]
	s_waitcnt vmcnt(7)
; DI f32x4 mfma16(bf16x8 a, bf16x8 b, f32x4 c) { return __builtin_amdgcn_mfma_f32_16x16x32_bf16(a, b, c, 0, 0, 0); }
; template <int MI, int NJ, bool SWAP, class AP, class BP>
; DI void gemm_main(f32x4 (&acc)[MI][NJ], const AP& ap, int a_kstep, const BP& bp, int b_kstep, int nk, bf16_t* smem) {
;     ...
;   for (int kt = 0; kt < nk; ++kt) {
;     const int buf = kt & 1;
;     sstore(buf ^ 1);
;     gload(kt + 2 < nk ? kt + 2 : nk - 1);
;     __builtin_amdgcn_sched_barrier(0);
;     const bf16_t* As = smem + buf * L::STAGE + (wm * 16 * MI + l15) * LDT + quad * 8;
;     const bf16_t* Bs = smem + buf * L::STAGE + L::A_ELEMS + (wn * 16 * NJ + l15) * LDT + quad * 8;
; #pragma unroll
;     for (int ks = 0; ks < 2; ++ks) {
;       if (MI * NJ >= 32 && ks == 1) asm volatile("" ::: "memory");
;       bf16x8 b[NJ];
; #pragma unroll
;       for (int j = 0; j < NJ; ++j) b[j] = *(const bf16x8*)(Bs + j * 16 * LDT + ks * 32);
; #pragma unroll
;       for (int i = 0; i < MI; ++i) {
;         const bf16x8 a = *(const bf16x8*)(As + i * 16 * LDT + ks * 32);
; #pragma unroll
;         for (int j = 0; j < NJ; ++j) acc[i][j] = SWAP ? mfma16(b[j], a, acc[i][j]) : mfma16(a, b[j], acc[i][j]);
;       }
;     }
;     __syncthreads();
;   }
	ds_write_b128 v253, v[140:143]
	v_mfma_f32_16x16x32_bf16 v[40:43], v[200:203], v[216:219], v[40:43]
	v_mfma_f32_16x16x32_bf16 v[36:39], v[204:207], v[216:219], v[36:39]
	v_lshl_add_u64 v[140:141], s[6:7], 0, v[166:167]
	s_nop 0
	global_load_dwordx4 v[140:143], v[140:141], off offset:256
	v_mfma_f32_16x16x32_bf16 v[32:35], v[208:211], v[216:219], v[32:35]
	ds_read_b128 v[212:215], v176 offset:64
	s_waitcnt lgkmcnt(3)
	v_mfma_f32_16x16x32_bf16 v[28:31], v[178:181], v[242:245], v[28:31]
	v_mfma_f32_16x16x32_bf16 v[24:27], v[200:203], v[242:245], v[24:27]
	v_mfma_f32_16x16x32_bf16 v[20:23], v[204:207], v[242:245], v[20:23]
	s_waitcnt vmcnt(7)
	ds_write_b128 v250, v[144:147] offset:36864
	v_mfma_f32_16x16x32_bf16 v[16:19], v[208:211], v[242:245], v[16:19]
	ds_read_b128 v[216:219], v176 offset:2368
	s_waitcnt lgkmcnt(4)
	v_mfma_f32_16x16x32_bf16 v[12:15], v[178:181], v[246:249], v[12:15]
	ds_read_b128 v[178:181], v182 offset:36928
	s_add_u32 s6, s2, s33
	s_addc_u32 s7, s3, 0
	v_lshl_add_u64 v[144:145], s[6:7], 0, v[160:161]
	s_nop 0
	global_load_dwordx4 v[144:147], v[144:145], off offset:256
	v_mfma_f32_16x16x32_bf16 v[8:11], v[200:203], v[246:249], v[8:11]
	ds_read_b128 v[200:203], v182 offset:39232
	v_mfma_f32_16x16x32_bf16 v[0:3], v[204:207], v[246:249], v[0:3]
	ds_read_b128 v[204:207], v182 offset:41536
	v_mfma_f32_16x16x32_bf16 v[4:7], v[208:211], v[246:249], v[4:7]
	ds_read_b128 v[208:211], v182 offset:43840
	ds_read_b128 v[242:245], v176 offset:4672
	s_waitcnt lgkmcnt(4)
	v_mfma_f32_16x16x32_bf16 v[124:127], v[178:181], v[212:215], v[124:127]
	s_waitcnt vmcnt(7)
	ds_write_b128 v251, v[148:151] offset:36864
	s_waitcnt lgkmcnt(4)
	v_mfma_f32_16x16x32_bf16 v[120:123], v[200:203], v[212:215], v[120:123]
	s_waitcnt lgkmcnt(3)
	v_mfma_f32_16x16x32_bf16 v[116:119], v[204:207], v[212:215], v[116:119]
	v_lshl_add_u64 v[148:149], s[6:7], 0, v[162:163]
	s_nop 0
	global_load_dwordx4 v[148:151], v[148:149], off offset:256
	s_waitcnt lgkmcnt(2)
	v_mfma_f32_16x16x32_bf16 v[112:115], v[208:211], v[212:215], v[112:115]
	ds_read_b128 v[246:249], v176 offset:6976
	v_mfma_f32_16x16x32_bf16 v[108:111], v[178:181], v[216:219], v[108:111]
	v_mfma_f32_16x16x32_bf16 v[104:107], v[200:203], v[216:219], v[104:107]
	v_mfma_f32_16x16x32_bf16 v[100:103], v[204:207], v[216:219], v[100:103]
	s_waitcnt vmcnt(7)
	ds_write_b128 v252, v[152:155] offset:36864
	v_mfma_f32_16x16x32_bf16 v[96:99], v[208:211], v[216:219], v[96:99]
	ds_read_b128 v[212:215], v176 offset:9280
	s_waitcnt lgkmcnt(4)
	v_mfma_f32_16x16x32_bf16 v[92:95], v[178:181], v[242:245], v[92:95]
	v_lshl_add_u64 v[152:153], s[6:7], 0, v[164:165]
	s_nop 0
	global_load_dwordx4 v[152:155], v[152:153], off offset:256
	v_mfma_f32_16x16x32_bf16 v[88:91], v[200:203], v[242:245], v[88:91]
	v_mfma_f32_16x16x32_bf16 v[84:87], v[204:207], v[242:245], v[84:87]
	v_mfma_f32_16x16x32_bf16 v[80:83], v[208:211], v[242:245], v[80:83]
	ds_read_b128 v[216:219], v176 offset:11584
	s_waitcnt lgkmcnt(3)
	v_mfma_f32_16x16x32_bf16 v[76:79], v[178:181], v[246:249], v[76:79]
	s_waitcnt vmcnt(7)
	ds_write_b128 v253, v[156:159] offset:36864
	v_mfma_f32_16x16x32_bf16 v[72:75], v[200:203], v[246:249], v[72:75]
	v_mfma_f32_16x16x32_bf16 v[68:71], v[204:207], v[246:249], v[68:71]
	v_lshl_add_u64 v[156:157], s[6:7], 0, v[166:167]
	s_nop 0
	global_load_dwordx4 v[156:159], v[156:157], off offset:256
	v_mfma_f32_16x16x32_bf16 v[64:67], v[208:211], v[246:249], v[64:67]
	ds_read_b128 v[242:245], v176 offset:13888
	s_waitcnt lgkmcnt(3)
	v_mfma_f32_16x16x32_bf16 v[60:63], v[178:181], v[212:215], v[60:63]
	v_mfma_f32_16x16x32_bf16 v[56:59], v[200:203], v[212:215], v[56:59]
	v_mfma_f32_16x16x32_bf16 v[52:55], v[204:207], v[212:215], v[52:55]
	v_mfma_f32_16x16x32_bf16 v[48:51], v[208:211], v[212:215], v[48:51]
	ds_read_b128 v[246:249], v176 offset:16192
	s_waitcnt lgkmcnt(3)
	v_mfma_f32_16x16x32_bf16 v[44:47], v[178:181], v[216:219], v[44:47]
	v_mfma_f32_16x16x32_bf16 v[40:43], v[200:203], v[216:219], v[40:43]
	v_mfma_f32_16x16x32_bf16 v[36:39], v[204:207], v[216:219], v[36:39]
	v_mfma_f32_16x16x32_bf16 v[32:35], v[208:211], v[216:219], v[32:35]
	s_add_i32 s4, s4, 1
	s_and_b32 s98, s4, 1
	s_mul_i32 s98, s98, 0x12000
	v_add3_u32 v182, s98, v168, v172
	v_add3_u32 v176, s98, v170, v172
	s_cmp_lg_u32 s4, 16
	s_waitcnt lgkmcnt(0)
	s_barrier
	s_cbranch_scc1 .Lgm0_top

; DI f32x4 mfma16(bf16x8 a, bf16x8 b, f32x4 c) { return __builtin_amdgcn_mfma_f32_16x16x32_bf16(a, b, c, 0, 0, 0); }
; template <int MI, int NJ, bool SWAP, class AP, class BP>
; DI void gemm_main(f32x4 (&acc)[MI][NJ], const AP& ap, int a_kstep, const BP& bp, int b_kstep, int nk, bf16_t* smem) {
;     ...
;   gload(0); sstore(0); gload(nk > 1 ? 1 : 0); __syncthreads();
; #pragma unroll 1
;   for (int kt = 0; kt < nk; ++kt) {
;     const int buf = kt & 1;
;     sstore(buf ^ 1);
;     gload(kt + 2 < nk ? kt + 2 : nk - 1);
;     __builtin_amdgcn_sched_barrier(0);
;     const bf16_t* As = smem + buf * L::STAGE + (wm * 16 * MI + l15) * LDT + quad * 8;
;     const bf16_t* Bs = smem + buf * L::STAGE + L::A_ELEMS + (wn * 16 * NJ + l15) * LDT + quad * 8;
; #pragma unroll
;     for (int ks = 0; ks < 2; ++ks) {
;       if (MI * NJ >= 32 && ks == 1) asm volatile("" ::: "memory");
;       bf16x8 b[NJ];
; #pragma unroll
;       for (int j = 0; j < NJ; ++j) b[j] = *(const bf16x8*)(Bs + j * 16 * LDT + ks * 32);
; #pragma unroll
;       for (int i = 0; i < MI; ++i) {
;         const bf16x8 a = *(const bf16x8*)(As + i * 16 * LDT + ks * 32);
; #pragma unroll
;         for (int j = 0; j < NJ; ++j) acc[i][j] = SWAP ? mfma16(b[j], a, acc[i][j]) : mfma16(a, b[j], acc[i][j]);
;       }
;     }
;     __syncthreads();
;   }
.LBB0_297:
	s_and_b32 s98, s4, 1
	s_mul_i32 s98, s98, 0x12000
	v_add3_u32 v176, s98, v174, v175
	v_add3_u32 v182, s98, v169, v175
	ds_read_b128 v[212:215], v176
	ds_read_b128 v[216:219], v176 offset:2304
	ds_read_b128 v[178:181], v182 offset:36864
	ds_read_b128 v[200:203], v182 offset:39168
	ds_read_b128 v[204:207], v182 offset:41472
	ds_read_b128 v[208:211], v182 offset:43776
	s_branch .Lgm1_main
.Lgm1_top:
	ds_read_b128 v[212:215], v176
	ds_read_b128 v[216:219], v176 offset:2304
	v_mfma_f32_16x16x32_bf16 v[28:31], v[242:245], v[178:181], v[28:31]
	v_mfma_f32_16x16x32_bf16 v[8:11], v[246:249], v[178:181], v[8:11]
	ds_read_b128 v[178:181], v182 offset:36864
	v_mfma_f32_16x16x32_bf16 v[24:27], v[242:245], v[200:203], v[24:27]
	v_mfma_f32_16x16x32_bf16 v[4:7], v[246:249], v[200:203], v[4:7]
	ds_read_b128 v[200:203], v182 offset:39168
	v_mfma_f32_16x16x32_bf16 v[20:23], v[242:245], v[204:207], v[20:23]
	v_mfma_f32_16x16x32_bf16 v[0:3], v[246:249], v[204:207], v[0:3]
	ds_read_b128 v[204:207], v182 offset:41472
	v_mfma_f32_16x16x32_bf16 v[16:19], v[242:245], v[208:211], v[16:19]
	v_mfma_f32_16x16x32_bf16 v[12:15], v[246:249], v[208:211], v[12:15]
	ds_read_b128 v[208:211], v182 offset:43776
.Lgm1_main:
	ds_read_b128 v[242:245], v176 offset:4608
	s_waitcnt lgkmcnt(4)
	v_mfma_f32_16x16x32_bf16 v[124:127], v[212:215], v[178:181], v[124:127]
	s_waitcnt lgkmcnt(3)
	v_mfma_f32_16x16x32_bf16 v[120:123], v[212:215], v[200:203], v[120:123]
	s_waitcnt lgkmcnt(2)
	v_mfma_f32_16x16x32_bf16 v[116:119], v[212:215], v[204:207], v[116:119]
	v_lshlrev_b32_e32 v250, 1, v168
	s_and_b32 s5, s4, 1
	s_min_u32 s6, s4, 13
	s_xor_b32 s7, s5, 1
	s_mul_i32 s7, s7, 0x12000
	v_add3_u32 v250, s7, v250, v170
	s_waitcnt vmcnt(7)
	ds_write_b128 v250, v[128:131]
	s_waitcnt lgkmcnt(2)
	v_mfma_f32_16x16x32_bf16 v[112:115], v[212:215], v[208:211], v[112:115]
	ds_read_b128 v[246:249], v176 offset:6912
	v_mfma_f32_16x16x32_bf16 v[108:111], v[216:219], v[178:181], v[108:111]
	s_lshl_b32 s33, s6, 7
	s_add_u32 s6, s0, s33
	v_lshlrev_b32_e32 v251, 1, v171
	v_add3_u32 v251, s7, v251, v170
	v_lshlrev_b32_e32 v252, 1, v172
	v_add3_u32 v252, s7, v252, v170
	v_lshlrev_b32_e32 v253, 1, v173
	v_add3_u32 v253, s7, v253, v170
	s_addc_u32 s7, s1, 0
	v_lshl_add_u64 v[128:129], s[6:7], 0, v[160:161]
	s_nop 0
	global_load_dwordx4 v[128:131], v[128:129], off offset:256
	v_mfma_f32_16x16x32_bf16 v[104:107], v[216:219], v[200:203], v[104:107]
	v_mfma_f32_16x16x32_bf16 v[100:103], v[216:219], v[204:207], v[100:103]
	v_mfma_f32_16x16x32_bf16 v[96:99], v[216:219], v[208:211], v[96:99]
	ds_read_b128 v[212:215], v176 offset:9216
	s_waitcnt lgkmcnt(3)
	v_mfma_f32_16x16x32_bf16 v[92:95], v[242:245], v[178:181], v[92:95]
	s_waitcnt vmcnt(7)
	ds_write_b128 v251, v[132:135]
	v_mfma_f32_16x16x32_bf16 v[88:91], v[242:245], v[200:203], v[88:91]
	v_mfma_f32_16x16x32_bf16 v[84:87], v[242:245], v[204:207], v[84:87]
	v_lshl_add_u64 v[132:133], s[6:7], 0, v[162:163]
	s_nop 0
	global_load_dwordx4 v[132:135], v[132:133], off offset:256
	v_mfma_f32_16x16x32_bf16 v[80:83], v[242:245], v[208:211], v[80:83]
	ds_read_b128 v[216:219], v176 offset:11520
	s_waitcnt lgkmcnt(3)
	v_mfma_f32_16x16x32_bf16 v[76:79], v[246:249], v[178:181], v[76:79]
	v_mfma_f32_16x16x32_bf16 v[72:75], v[246:249], v[200:203], v[72:75]
	v_mfma_f32_16x16x32_bf16 v[68:71], v[246:249], v[204:207], v[68:71]
	s_waitcnt vmcnt(7)
	ds_write_b128 v252, v[136:139]
	v_mfma_f32_16x16x32_bf16 v[64:67], v[246:249], v[208:211], v[64:67]
	ds_read_b128 v[242:245], v176 offset:13824
	s_waitcnt lgkmcnt(4)
	v_mfma_f32_16x16x32_bf16 v[60:63], v[212:215], v[178:181], v[60:63]
	v_lshl_add_u64 v[136:137], s[6:7], 0, v[164:165]
	s_nop 0
	global_load_dwordx4 v[136:139], v[136:137], off offset:256
	v_mfma_f32_16x16x32_bf16 v[56:59], v[212:215], v[200:203], v[56:59]
	v_mfma_f32_16x16x32_bf16 v[52:55], v[212:215], v[204:207], v[52:55]
	v_mfma_f32_16x16x32_bf16 v[48:51], v[212:215], v[208:211], v[48:51]
	ds_read_b128 v[246:249], v176 offset:16128
	s_waitcnt lgkmcnt(3)
	v_mfma_f32_16x16x32_bf16 v[44:47], v[216:219], v[178:181], v[44:47]
	s_waitcnt vmcnt(7)
; DI f32x4 mfma16(bf16x8 a, bf16x8 b, f32x4 c) { return __builtin_amdgcn_mfma_f32_16x16x32_bf16(a, b, c, 0, 0, 0); }
; template <int MI, int NJ, bool SWAP, class AP, class BP>
; DI void gemm_main(f32x4 (&acc)[MI][NJ], const AP& ap, int a_kstep, const BP& bp, int b_kstep, int nk, bf16_t* smem) {
;     ...
;   for (int kt = 0; kt < nk; ++kt) {
;     const int buf = kt & 1;
;     sstore(buf ^ 1);
;     gload(kt + 2 < nk ? kt + 2 : nk - 1);
;     __builtin_amdgcn_sched_barrier(0);
;     const bf16_t* As = smem + buf * L::STAGE + (wm * 16 * MI + l15) * LDT + quad * 8;
;     const bf16_t* Bs = smem + buf * L::STAGE + L::A_ELEMS + (wn * 16 * NJ + l15) * LDT + quad * 8;
; #pragma unroll
;     for (int ks = 0; ks < 2; ++ks) {
;       if (MI * NJ >= 32 && ks == 1) asm volatile("" ::: "memory");
;       bf16x8 b[NJ];
; #pragma unroll
;       for (int j = 0; j < NJ; ++j) b[j] = *(const bf16x8*)(Bs + j * 16 * LDT + ks * 32);
; #pragma unroll
;       for (int i = 0; i < MI; ++i) {
;         const bf16x8 a = *(const bf16x8*)(As + i * 16 * LDT + ks * 32);
; #pragma unroll
;         for (int j = 0; j < NJ; ++j) acc[i][j] = SWAP ? mfma16(b[j], a, acc[i][j]) : mfma16(a, b[j], acc[i][j]);
;       }
;     }
;     __syncthreads();
;   }
	ds_write_b128 v253, v[140:143]
	v_mfma_f32_16x16x32_bf16 v[40:43], v[216:219], v[200:203], v[40:43]
	v_mfma_f32_16x16x32_bf16 v[36:39], v[216:219], v[204:207], v[36:39]
	v_lshl_add_u64 v[140:141], s[6:7], 0, v[166:167]
	s_nop 0
	global_load_dwordx4 v[140:143], v[140:141], off offset:256
	v_mfma_f32_16x16x32_bf16 v[32:35], v[216:219], v[208:211], v[32:35]
	ds_read_b128 v[212:215], v176 offset:64
	s_waitcnt lgkmcnt(3)
	v_mfma_f32_16x16x32_bf16 v[28:31], v[242:245], v[178:181], v[28:31]
	v_mfma_f32_16x16x32_bf16 v[24:27], v[242:245], v[200:203], v[24:27]
	v_mfma_f32_16x16x32_bf16 v[20:23], v[242:245], v[204:207], v[20:23]
	s_waitcnt vmcnt(7)
	ds_write_b128 v250, v[144:147] offset:36864
	v_mfma_f32_16x16x32_bf16 v[16:19], v[242:245], v[208:211], v[16:19]
	ds_read_b128 v[216:219], v176 offset:2368
	s_waitcnt lgkmcnt(4)
	v_mfma_f32_16x16x32_bf16 v[8:11], v[246:249], v[178:181], v[8:11]
	ds_read_b128 v[178:181], v182 offset:36928
	s_add_u32 s6, s2, s33
	s_addc_u32 s7, s3, 0
	v_lshl_add_u64 v[144:145], s[6:7], 0, v[160:161]
	s_nop 0
	global_load_dwordx4 v[144:147], v[144:145], off offset:256
	v_mfma_f32_16x16x32_bf16 v[4:7], v[246:249], v[200:203], v[4:7]
	ds_read_b128 v[200:203], v182 offset:39232
	v_mfma_f32_16x16x32_bf16 v[0:3], v[246:249], v[204:207], v[0:3]
	ds_read_b128 v[204:207], v182 offset:41536
	v_mfma_f32_16x16x32_bf16 v[12:15], v[246:249], v[208:211], v[12:15]
	ds_read_b128 v[208:211], v182 offset:43840
	ds_read_b128 v[242:245], v176 offset:4672
	s_waitcnt lgkmcnt(4)
	v_mfma_f32_16x16x32_bf16 v[124:127], v[212:215], v[178:181], v[124:127]
	s_waitcnt vmcnt(7)
	ds_write_b128 v251, v[148:151] offset:36864
	s_waitcnt lgkmcnt(4)
	v_mfma_f32_16x16x32_bf16 v[120:123], v[212:215], v[200:203], v[120:123]
	s_waitcnt lgkmcnt(3)
	v_mfma_f32_16x16x32_bf16 v[116:119], v[212:215], v[204:207], v[116:119]
	v_lshl_add_u64 v[148:149], s[6:7], 0, v[162:163]
	s_nop 0
	global_load_dwordx4 v[148:151], v[148:149], off offset:256
	s_waitcnt lgkmcnt(2)
	v_mfma_f32_16x16x32_bf16 v[112:115], v[212:215], v[208:211], v[112:115]
	ds_read_b128 v[246:249], v176 offset:6976
	v_mfma_f32_16x16x32_bf16 v[108:111], v[216:219], v[178:181], v[108:111]
	v_mfma_f32_16x16x32_bf16 v[104:107], v[216:219], v[200:203], v[104:107]
	v_mfma_f32_16x16x32_bf16 v[100:103], v[216:219], v[204:207], v[100:103]
	s_waitcnt vmcnt(7)
	ds_write_b128 v252, v[152:155] offset:36864
	v_mfma_f32_16x16x32_bf16 v[96:99], v[216:219], v[208:211], v[96:99]
	ds_read_b128 v[212:215], v176 offset:9280
	s_waitcnt lgkmcnt(4)
	v_mfma_f32_16x16x32_bf16 v[92:95], v[242:245], v[178:181], v[92:95]
	v_lshl_add_u64 v[152:153], s[6:7], 0, v[164:165]
	s_nop 0
	global_load_dwordx4 v[152:155], v[152:153], off offset:256
	v_mfma_f32_16x16x32_bf16 v[88:91], v[242:245], v[200:203], v[88:91]
	v_mfma_f32_16x16x32_bf16 v[84:87], v[242:245], v[204:207], v[84:87]
	v_mfma_f32_16x16x32_bf16 v[80:83], v[242:245], v[208:211], v[80:83]
	ds_read_b128 v[216:219], v176 offset:11584
	s_waitcnt lgkmcnt(3)
	v_mfma_f32_16x16x32_bf16 v[76:79], v[246:249], v[178:181], v[76:79]
	s_waitcnt vmcnt(7)
	ds_write_b128 v253, v[156:159] offset:36864
	v_mfma_f32_16x16x32_bf16 v[72:75], v[246:249], v[200:203], v[72:75]
	v_mfma_f32_16x16x32_bf16 v[68:71], v[246:249], v[204:207], v[68:71]
	v_lshl_add_u64 v[156:157], s[6:7], 0, v[166:167]
	s_nop 0
	global_load_dwordx4 v[156:159], v[156:157], off offset:256
	v_mfma_f32_16x16x32_bf16 v[64:67], v[246:249], v[208:211], v[64:67]
	ds_read_b128 v[242:245], v176 offset:13888
	s_waitcnt lgkmcnt(3)
	v_mfma_f32_16x16x32_bf16 v[60:63], v[212:215], v[178:181], v[60:63]
	v_mfma_f32_16x16x32_bf16 v[56:59], v[212:215], v[200:203], v[56:59]
	v_mfma_f32_16x16x32_bf16 v[52:55], v[212:215], v[204:207], v[52:55]
	v_mfma_f32_16x16x32_bf16 v[48:51], v[212:215], v[208:211], v[48:51]
	ds_read_b128 v[246:249], v176 offset:16192
	s_waitcnt lgkmcnt(3)
	v_mfma_f32_16x16x32_bf16 v[44:47], v[216:219], v[178:181], v[44:47]
	v_mfma_f32_16x16x32_bf16 v[40:43], v[216:219], v[200:203], v[40:43]
	v_mfma_f32_16x16x32_bf16 v[36:39], v[216:219], v[204:207], v[36:39]
	v_mfma_f32_16x16x32_bf16 v[32:35], v[216:219], v[208:211], v[32:35]
	s_add_i32 s4, s4, 1
	s_and_b32 s98, s4, 1
	s_mul_i32 s98, s98, 0x12000
	v_add3_u32 v176, s98, v174, v175
	v_add3_u32 v182, s98, v169, v175
	s_cmp_lg_u32 s4, 16
	s_waitcnt lgkmcnt(0)
	s_barrier
	s_cbranch_scc1 .Lgm1_top

; DI f32x4 mfma16(bf16x8 a, bf16x8 b, f32x4 c) { return __builtin_amdgcn_mfma_f32_16x16x32_bf16(a, b, c, 0, 0, 0); }
; template <int MI, int NJ, bool SWAP, class AP, class BP>
; DI void gemm_main(f32x4 (&acc)[MI][NJ], const AP& ap, int a_kstep, const BP& bp, int b_kstep, int nk, bf16_t* smem) {
;     ...
;   gload(0); sstore(0); gload(nk > 1 ? 1 : 0); __syncthreads();
; #pragma unroll 1
;   for (int kt = 0; kt < nk; ++kt) {
;     const int buf = kt & 1;
;     sstore(buf ^ 1);
;     gload(kt + 2 < nk ? kt + 2 : nk - 1);
;     __builtin_amdgcn_sched_barrier(0);
;     const bf16_t* As = smem + buf * L::STAGE + (wm * 16 * MI + l15) * LDT + quad * 8;
;     const bf16_t* Bs = smem + buf * L::STAGE + L::A_ELEMS + (wn * 16 * NJ + l15) * LDT + quad * 8;
; #pragma unroll
;     for (int ks = 0; ks < 2; ++ks) {
;       if (MI * NJ >= 32 && ks == 1) asm volatile("" ::: "memory");
;       bf16x8 b[NJ];
; #pragma unroll
;       for (int j = 0; j < NJ; ++j) b[j] = *(const bf16x8*)(Bs + j * 16 * LDT + ks * 32);
; #pragma unroll
;       for (int i = 0; i < MI; ++i) {
;         const bf16x8 a = *(const bf16x8*)(As + i * 16 * LDT + ks * 32);
; #pragma unroll
;         for (int j = 0; j < NJ; ++j) acc[i][j] = SWAP ? mfma16(b[j], a, acc[i][j]) : mfma16(a, b[j], acc[i][j]);
;       }
;     }
;     __syncthreads();
;   }
.LBB0_376:
	s_and_b32 s98, s16, 1
	s_mul_i32 s98, s98, 0x12000
	v_add3_u32 v183, s98, v160, v177
	v_add3_u32 v182, s98, v172, v177
	ds_read_b128 v[198:201], v182
	ds_read_b128 v[202:205], v182 offset:2304
	ds_read_b128 v[178:181], v183 offset:36864
	ds_read_b128 v[186:189], v183 offset:39168
	ds_read_b128 v[190:193], v183 offset:41472
	ds_read_b128 v[194:197], v183 offset:43776
	s_branch .Lgm2_main
.Lgm2_top:
	ds_read_b128 v[198:201], v182
	ds_read_b128 v[202:205], v182 offset:2304
	v_mfma_f32_16x16x32_bf16 v[28:31], v[178:181], v[242:245], v[28:31]
	v_mfma_f32_16x16x32_bf16 v[8:11], v[178:181], v[246:249], v[8:11]
	ds_read_b128 v[178:181], v183 offset:36864
	v_mfma_f32_16x16x32_bf16 v[24:27], v[186:189], v[242:245], v[24:27]
	v_mfma_f32_16x16x32_bf16 v[4:7], v[186:189], v[246:249], v[4:7]
	ds_read_b128 v[186:189], v183 offset:39168
	v_mfma_f32_16x16x32_bf16 v[20:23], v[190:193], v[242:245], v[20:23]
	v_mfma_f32_16x16x32_bf16 v[0:3], v[190:193], v[246:249], v[0:3]
	ds_read_b128 v[190:193], v183 offset:41472
	v_mfma_f32_16x16x32_bf16 v[16:19], v[194:197], v[242:245], v[16:19]
	v_mfma_f32_16x16x32_bf16 v[12:15], v[194:197], v[246:249], v[12:15]
	ds_read_b128 v[194:197], v183 offset:43776
.Lgm2_main:
	ds_read_b128 v[242:245], v182 offset:4608
	s_waitcnt lgkmcnt(4)
	v_mfma_f32_16x16x32_bf16 v[156:159], v[178:181], v[198:201], v[156:159]
	s_waitcnt lgkmcnt(3)
	v_mfma_f32_16x16x32_bf16 v[152:155], v[186:189], v[198:201], v[152:155]
	s_waitcnt lgkmcnt(2)
	v_mfma_f32_16x16x32_bf16 v[148:151], v[190:193], v[198:201], v[148:151]
	s_and_b32 s33, s16, 1
	s_min_u32 s52, s16, 3
	s_xor_b32 s53, s33, 1
	s_mul_i32 s53, s53, 0x12000
	v_add3_u32 v250, s53, v173, v171
	s_waitcnt vmcnt(7)
	ds_write_b128 v250, v[112:115]
	s_waitcnt lgkmcnt(2)
	v_mfma_f32_16x16x32_bf16 v[144:147], v[194:197], v[198:201], v[144:147]
	ds_read_b128 v[246:249], v182 offset:6912
	v_mfma_f32_16x16x32_bf16 v[108:111], v[178:181], v[202:205], v[108:111]
	s_lshl_b32 s54, s52, 7
	s_add_u32 s52, s0, s54
	v_add3_u32 v251, s53, v174, v171
	v_add3_u32 v252, s53, v175, v171
	v_add3_u32 v253, s53, v176, v171
	s_addc_u32 s53, s1, 0
	v_lshl_add_u64 v[112:113], s[52:53], 0, v[162:163]
	s_nop 0
	global_load_dwordx4 v[112:115], v[112:113], off offset:256
	v_mfma_f32_16x16x32_bf16 v[104:107], v[186:189], v[202:205], v[104:107]
	v_mfma_f32_16x16x32_bf16 v[100:103], v[190:193], v[202:205], v[100:103]
	v_mfma_f32_16x16x32_bf16 v[96:99], v[194:197], v[202:205], v[96:99]
	ds_read_b128 v[198:201], v182 offset:9216
	s_waitcnt lgkmcnt(3)
	v_mfma_f32_16x16x32_bf16 v[92:95], v[178:181], v[242:245], v[92:95]
	s_waitcnt vmcnt(6)
	ds_write_b128 v251, v[116:119]
	v_mfma_f32_16x16x32_bf16 v[88:91], v[186:189], v[242:245], v[88:91]
	v_mfma_f32_16x16x32_bf16 v[84:87], v[190:193], v[242:245], v[84:87]
	v_lshl_add_u64 v[116:117], s[52:53], 0, v[164:165]
	s_nop 0
	global_load_dwordx4 v[116:119], v[116:117], off offset:256
	v_mfma_f32_16x16x32_bf16 v[80:83], v[194:197], v[242:245], v[80:83]
	ds_read_b128 v[202:205], v182 offset:11520
	s_waitcnt lgkmcnt(3)
	v_mfma_f32_16x16x32_bf16 v[76:79], v[178:181], v[246:249], v[76:79]
	v_mfma_f32_16x16x32_bf16 v[72:75], v[186:189], v[246:249], v[72:75]
	v_mfma_f32_16x16x32_bf16 v[68:71], v[190:193], v[246:249], v[68:71]
	s_waitcnt vmcnt(6)
	ds_write_b128 v252, v[120:123]
	v_mfma_f32_16x16x32_bf16 v[64:67], v[194:197], v[246:249], v[64:67]
	ds_read_b128 v[242:245], v182 offset:13824
	s_waitcnt lgkmcnt(4)
	v_mfma_f32_16x16x32_bf16 v[60:63], v[178:181], v[198:201], v[60:63]
	v_lshl_add_u64 v[120:121], s[52:53], 0, v[166:167]
	s_nop 0
	global_load_dwordx4 v[120:123], v[120:121], off offset:256
	v_mfma_f32_16x16x32_bf16 v[56:59], v[186:189], v[198:201], v[56:59]
	v_mfma_f32_16x16x32_bf16 v[52:55], v[190:193], v[198:201], v[52:55]
	v_mfma_f32_16x16x32_bf16 v[48:51], v[194:197], v[198:201], v[48:51]
	ds_read_b128 v[246:249], v182 offset:16128
	s_waitcnt lgkmcnt(3)
	v_mfma_f32_16x16x32_bf16 v[44:47], v[178:181], v[202:205], v[44:47]
	s_waitcnt vmcnt(6)
; DI f32x4 mfma16(bf16x8 a, bf16x8 b, f32x4 c) { return __builtin_amdgcn_mfma_f32_16x16x32_bf16(a, b, c, 0, 0, 0); }
; template <int MI, int NJ, bool SWAP, class AP, class BP>
; DI void gemm_main(f32x4 (&acc)[MI][NJ], const AP& ap, int a_kstep, const BP& bp, int b_kstep, int nk, bf16_t* smem) {
;     ...
;   for (int kt = 0; kt < nk; ++kt) {
;     const int buf = kt & 1;
;     sstore(buf ^ 1);
;     gload(kt + 2 < nk ? kt + 2 : nk - 1);
;     __builtin_amdgcn_sched_barrier(0);
;     const bf16_t* As = smem + buf * L::STAGE + (wm * 16 * MI + l15) * LDT + quad * 8;
;     const bf16_t* Bs = smem + buf * L::STAGE + L::A_ELEMS + (wn * 16 * NJ + l15) * LDT + quad * 8;
; #pragma unroll
;     for (int ks = 0; ks < 2; ++ks) {
;       if (MI * NJ >= 32 && ks == 1) asm volatile("" ::: "memory");
;       bf16x8 b[NJ];
; #pragma unroll
;       for (int j = 0; j < NJ; ++j) b[j] = *(const bf16x8*)(Bs + j * 16 * LDT + ks * 32);
; #pragma unroll
;       for (int i = 0; i < MI; ++i) {
;         const bf16x8 a = *(const bf16x8*)(As + i * 16 * LDT + ks * 32);
; #pragma unroll
;         for (int j = 0; j < NJ; ++j) acc[i][j] = SWAP ? mfma16(b[j], a, acc[i][j]) : mfma16(a, b[j], acc[i][j]);
;       }
;     }
;     __syncthreads();
;   }
	ds_write_b128 v253, v[124:127]
	v_mfma_f32_16x16x32_bf16 v[40:43], v[186:189], v[202:205], v[40:43]
	v_mfma_f32_16x16x32_bf16 v[36:39], v[190:193], v[202:205], v[36:39]
	v_lshl_add_u64 v[124:125], s[52:53], 0, v[168:169]
	s_nop 0
	global_load_dwordx4 v[124:127], v[124:125], off offset:256
	v_mfma_f32_16x16x32_bf16 v[32:35], v[194:197], v[202:205], v[32:35]
	ds_read_b128 v[198:201], v182 offset:64
	s_waitcnt lgkmcnt(3)
	v_mfma_f32_16x16x32_bf16 v[28:31], v[178:181], v[242:245], v[28:31]
	v_mfma_f32_16x16x32_bf16 v[24:27], v[186:189], v[242:245], v[24:27]
	v_mfma_f32_16x16x32_bf16 v[20:23], v[190:193], v[242:245], v[20:23]
	ds_write_b128 v250, v[128:131] offset:36864
	v_mfma_f32_16x16x32_bf16 v[16:19], v[194:197], v[242:245], v[16:19]
	ds_read_b128 v[202:205], v182 offset:2368
	s_waitcnt lgkmcnt(4)
	v_mfma_f32_16x16x32_bf16 v[8:11], v[178:181], v[246:249], v[8:11]
	ds_read_b128 v[178:181], v183 offset:36928
	s_add_u32 s52, s2, s54
	s_addc_u32 s53, s3, 0
	v_lshl_add_u64 v[128:129], s[52:53], 0, v[162:163]
	s_nop 0
	global_load_dwordx4 v[128:131], v[128:129], off offset:256
	v_mfma_f32_16x16x32_bf16 v[4:7], v[186:189], v[246:249], v[4:7]
	ds_read_b128 v[186:189], v183 offset:39232
	v_mfma_f32_16x16x32_bf16 v[0:3], v[190:193], v[246:249], v[0:3]
	ds_read_b128 v[190:193], v183 offset:41536
	v_mfma_f32_16x16x32_bf16 v[12:15], v[194:197], v[246:249], v[12:15]
	ds_read_b128 v[194:197], v183 offset:43840
	ds_read_b128 v[242:245], v182 offset:4672
	s_waitcnt lgkmcnt(4)
	v_mfma_f32_16x16x32_bf16 v[156:159], v[178:181], v[198:201], v[156:159]
	s_waitcnt vmcnt(7)
	ds_write_b128 v251, v[132:135] offset:36864
	s_waitcnt lgkmcnt(4)
	v_mfma_f32_16x16x32_bf16 v[152:155], v[186:189], v[198:201], v[152:155]
	s_waitcnt lgkmcnt(3)
	v_mfma_f32_16x16x32_bf16 v[148:151], v[190:193], v[198:201], v[148:151]
	v_lshl_add_u64 v[132:133], s[52:53], 0, v[164:165]
	s_nop 0
	global_load_dwordx4 v[132:135], v[132:133], off offset:256
	s_waitcnt lgkmcnt(2)
	v_mfma_f32_16x16x32_bf16 v[144:147], v[194:197], v[198:201], v[144:147]
	ds_read_b128 v[246:249], v182 offset:6976
	v_mfma_f32_16x16x32_bf16 v[108:111], v[178:181], v[202:205], v[108:111]
	v_mfma_f32_16x16x32_bf16 v[104:107], v[186:189], v[202:205], v[104:107]
	v_mfma_f32_16x16x32_bf16 v[100:103], v[190:193], v[202:205], v[100:103]
	s_waitcnt vmcnt(7)
	ds_write_b128 v252, v[136:139] offset:36864
	v_mfma_f32_16x16x32_bf16 v[96:99], v[194:197], v[202:205], v[96:99]
	ds_read_b128 v[198:201], v182 offset:9280
	s_waitcnt lgkmcnt(4)
	v_mfma_f32_16x16x32_bf16 v[92:95], v[178:181], v[242:245], v[92:95]
	v_lshl_add_u64 v[136:137], s[52:53], 0, v[166:167]
	s_nop 0
	global_load_dwordx4 v[136:139], v[136:137], off offset:256
	v_mfma_f32_16x16x32_bf16 v[88:91], v[186:189], v[242:245], v[88:91]
	v_mfma_f32_16x16x32_bf16 v[84:87], v[190:193], v[242:245], v[84:87]
	v_mfma_f32_16x16x32_bf16 v[80:83], v[194:197], v[242:245], v[80:83]
	ds_read_b128 v[202:205], v182 offset:11584
	s_waitcnt lgkmcnt(3)
	v_mfma_f32_16x16x32_bf16 v[76:79], v[178:181], v[246:249], v[76:79]
	s_waitcnt vmcnt(7)
	ds_write_b128 v253, v[140:143] offset:36864
	v_mfma_f32_16x16x32_bf16 v[72:75], v[186:189], v[246:249], v[72:75]
	v_mfma_f32_16x16x32_bf16 v[68:71], v[190:193], v[246:249], v[68:71]
	v_lshl_add_u64 v[140:141], s[52:53], 0, v[168:169]
	s_nop 0
	global_load_dwordx4 v[140:143], v[140:141], off offset:256
	v_mfma_f32_16x16x32_bf16 v[64:67], v[194:197], v[246:249], v[64:67]
	ds_read_b128 v[242:245], v182 offset:13888
	s_waitcnt lgkmcnt(3)
	v_mfma_f32_16x16x32_bf16 v[60:63], v[178:181], v[198:201], v[60:63]
	v_mfma_f32_16x16x32_bf16 v[56:59], v[186:189], v[198:201], v[56:59]
	v_mfma_f32_16x16x32_bf16 v[52:55], v[190:193], v[198:201], v[52:55]
	v_mfma_f32_16x16x32_bf16 v[48:51], v[194:197], v[198:201], v[48:51]
	ds_read_b128 v[246:249], v182 offset:16192
	s_waitcnt lgkmcnt(3)
	v_mfma_f32_16x16x32_bf16 v[44:47], v[178:181], v[202:205], v[44:47]
	v_mfma_f32_16x16x32_bf16 v[40:43], v[186:189], v[202:205], v[40:43]
	v_mfma_f32_16x16x32_bf16 v[36:39], v[190:193], v[202:205], v[36:39]
	v_mfma_f32_16x16x32_bf16 v[32:35], v[194:197], v[202:205], v[32:35]
	s_add_i32 s16, s16, 1
	s_and_b32 s98, s16, 1
	s_mul_i32 s98, s98, 0x12000
	v_add3_u32 v183, s98, v160, v177
	v_add3_u32 v182, s98, v172, v177
	s_cmp_lg_u32 s16, 6
	s_waitcnt lgkmcnt(0)
	s_barrier
	s_cbranch_scc1 .Lgm2_top

; template <int MI, int NJ, bool SWAP, class AP, class BP>
; DI void gemm_main(f32x4 (&acc)[MI][NJ], const AP& ap, int a_kstep, const BP& bp, int b_kstep, int nk, bf16_t* smem) {
;     ...
;   gload(0); sstore(0); gload(nk > 1 ? 1 : 0); __syncthreads();
.LBB0_396:
	s_and_b32 s98, s33, 1
	s_mul_i32 s98, s98, 0x12000
	v_add3_u32 v183, s98, v171, v177
	v_add3_u32 v182, s98, v176, v177
	ds_read_b128 v[198:201], v182
	ds_read_b128 v[202:205], v182 offset:2304
	ds_read_b128 v[178:181], v183 offset:36864
	ds_read_b128 v[186:189], v183 offset:39168
	ds_read_b128 v[190:193], v183 offset:41472
	ds_read_b128 v[194:197], v183 offset:43776
	s_branch .Lgm3_main

; DI f32x4 mfma16(bf16x8 a, bf16x8 b, f32x4 c) { return __builtin_amdgcn_mfma_f32_16x16x32_bf16(a, b, c, 0, 0, 0); }
; template <int MI, int NJ, bool SWAP, class AP, class BP>
; DI void gemm_main(f32x4 (&acc)[MI][NJ], const AP& ap, int a_kstep, const BP& bp, int b_kstep, int nk, bf16_t* smem) {
;     ...
;   for (int kt = 0; kt < nk; ++kt) {
;     const int buf = kt & 1;
;     sstore(buf ^ 1);
;     gload(kt + 2 < nk ? kt + 2 : nk - 1);
;     __builtin_amdgcn_sched_barrier(0);
;     const bf16_t* As = smem + buf * L::STAGE + (wm * 16 * MI + l15) * LDT + quad * 8;
;     const bf16_t* Bs = smem + buf * L::STAGE + L::A_ELEMS + (wn * 16 * NJ + l15) * LDT + quad * 8;
; #pragma unroll
;     for (int ks = 0; ks < 2; ++ks) {
;       if (MI * NJ >= 32 && ks == 1) asm volatile("" ::: "memory");
;       bf16x8 b[NJ];
; #pragma unroll
;       for (int j = 0; j < NJ; ++j) b[j] = *(const bf16x8*)(Bs + j * 16 * LDT + ks * 32);
; #pragma unroll
;       for (int i = 0; i < MI; ++i) {
;         const bf16x8 a = *(const bf16x8*)(As + i * 16 * LDT + ks * 32);
; #pragma unroll
;         for (int j = 0; j < NJ; ++j) acc[i][j] = SWAP ? mfma16(b[j], a, acc[i][j]) : mfma16(a, b[j], acc[i][j]);
;       }
.Lgm3_main:
	ds_read_b128 v[242:245], v182 offset:4608
	s_waitcnt lgkmcnt(4)
	v_mfma_f32_16x16x32_bf16 v[156:159], v[178:181], v[198:201], v[156:159]
	s_waitcnt lgkmcnt(3)
	v_mfma_f32_16x16x32_bf16 v[152:155], v[186:189], v[198:201], v[152:155]
	s_waitcnt lgkmcnt(2)
	v_mfma_f32_16x16x32_bf16 v[148:151], v[190:193], v[198:201], v[148:151]
	v_lshlrev_b32_e32 v250, 1, v160
	s_and_b32 s54, s33, 1
	s_xor_b32 s52, s54, 1
	s_mul_i32 s52, s52, 0x12000
	v_add3_u32 v250, s52, v250, v172
	s_waitcnt vmcnt(7)
	ds_write_b128 v250, v[112:115]
	s_waitcnt lgkmcnt(2)
	v_mfma_f32_16x16x32_bf16 v[144:147], v[194:197], v[198:201], v[144:147]
	ds_read_b128 v[246:249], v182 offset:6912
	v_mfma_f32_16x16x32_bf16 v[108:111], v[178:181], v[202:205], v[108:111]
	s_cmp_eq_u32 s33, 0
	s_cselect_b32 s55, s48, 0x180
	v_lshlrev_b32_e32 v251, 1, v173
	v_add3_u32 v251, s52, v251, v172
	v_lshlrev_b32_e32 v252, 1, v174
	v_add3_u32 v252, s52, v252, v172
	v_lshlrev_b32_e32 v253, 1, v175
	v_add3_u32 v253, s52, v253, v172
	s_add_u32 s52, s0, s55
	s_addc_u32 s53, s1, 0
	v_lshl_add_u64 v[112:113], s[52:53], 0, v[162:163]
	s_nop 0
	global_load_dwordx4 v[112:115], v[112:113], off
	v_mfma_f32_16x16x32_bf16 v[104:107], v[186:189], v[202:205], v[104:107]
	v_mfma_f32_16x16x32_bf16 v[100:103], v[190:193], v[202:205], v[100:103]
	v_mfma_f32_16x16x32_bf16 v[96:99], v[194:197], v[202:205], v[96:99]
	ds_read_b128 v[198:201], v182 offset:9216
	s_waitcnt lgkmcnt(3)
	v_mfma_f32_16x16x32_bf16 v[92:95], v[178:181], v[242:245], v[92:95]
	s_waitcnt vmcnt(7)
	ds_write_b128 v251, v[116:119]
	v_mfma_f32_16x16x32_bf16 v[88:91], v[186:189], v[242:245], v[88:91]
	v_mfma_f32_16x16x32_bf16 v[84:87], v[190:193], v[242:245], v[84:87]
	v_lshl_add_u64 v[116:117], s[52:53], 0, v[164:165]
	s_nop 0
	global_load_dwordx4 v[116:119], v[116:117], off
	v_mfma_f32_16x16x32_bf16 v[80:83], v[194:197], v[242:245], v[80:83]
	ds_read_b128 v[202:205], v182 offset:11520
	s_waitcnt lgkmcnt(3)
	v_mfma_f32_16x16x32_bf16 v[76:79], v[178:181], v[246:249], v[76:79]
	v_mfma_f32_16x16x32_bf16 v[72:75], v[186:189], v[246:249], v[72:75]
	v_mfma_f32_16x16x32_bf16 v[68:71], v[190:193], v[246:249], v[68:71]
	s_waitcnt vmcnt(7)
	ds_write_b128 v252, v[120:123]
	v_mfma_f32_16x16x32_bf16 v[64:67], v[194:197], v[246:249], v[64:67]
	ds_read_b128 v[242:245], v182 offset:13824
	s_waitcnt lgkmcnt(4)
	v_mfma_f32_16x16x32_bf16 v[60:63], v[178:181], v[198:201], v[60:63]
	v_lshl_add_u64 v[120:121], s[52:53], 0, v[166:167]
	s_nop 0
	global_load_dwordx4 v[120:123], v[120:121], off
	v_mfma_f32_16x16x32_bf16 v[56:59], v[186:189], v[198:201], v[56:59]
	v_mfma_f32_16x16x32_bf16 v[52:55], v[190:193], v[198:201], v[52:55]
	v_mfma_f32_16x16x32_bf16 v[48:51], v[194:197], v[198:201], v[48:51]
	ds_read_b128 v[246:249], v182 offset:16128
	s_waitcnt lgkmcnt(3)
	v_mfma_f32_16x16x32_bf16 v[44:47], v[178:181], v[202:205], v[44:47]
	s_waitcnt vmcnt(7)
	ds_write_b128 v253, v[124:127]
	v_mfma_f32_16x16x32_bf16 v[40:43], v[186:189], v[202:205], v[40:43]
	v_mfma_f32_16x16x32_bf16 v[36:39], v[190:193], v[202:205], v[36:39]
	v_lshl_add_u64 v[124:125], s[52:53], 0, v[168:169]
	s_nop 0
	global_load_dwordx4 v[124:127], v[124:125], off
	v_mfma_f32_16x16x32_bf16 v[32:35], v[194:197], v[202:205], v[32:35]
	ds_read_b128 v[198:201], v182 offset:64
	s_waitcnt lgkmcnt(3)
	v_mfma_f32_16x16x32_bf16 v[28:31], v[178:181], v[242:245], v[28:31]
	v_mfma_f32_16x16x32_bf16 v[24:27], v[186:189], v[242:245], v[24:27]
	v_mfma_f32_16x16x32_bf16 v[20:23], v[190:193], v[242:245], v[20:23]
	s_waitcnt vmcnt(7)
; DI f32x4 mfma16(bf16x8 a, bf16x8 b, f32x4 c) { return __builtin_amdgcn_mfma_f32_16x16x32_bf16(a, b, c, 0, 0, 0); }
; template <int MI, int NJ, bool SWAP, class AP, class BP>
; DI void gemm_main(f32x4 (&acc)[MI][NJ], const AP& ap, int a_kstep, const BP& bp, int b_kstep, int nk, bf16_t* smem) {
;     ...
;   for (int kt = 0; kt < nk; ++kt) {
;     const int buf = kt & 1;
;     sstore(buf ^ 1);
;     gload(kt + 2 < nk ? kt + 2 : nk - 1);
;     __builtin_amdgcn_sched_barrier(0);
;     const bf16_t* As = smem + buf * L::STAGE + (wm * 16 * MI + l15) * LDT + quad * 8;
;     const bf16_t* Bs = smem + buf * L::STAGE + L::A_ELEMS + (wn * 16 * NJ + l15) * LDT + quad * 8;
; #pragma unroll
;     for (int ks = 0; ks < 2; ++ks) {
;       if (MI * NJ >= 32 && ks == 1) asm volatile("" ::: "memory");
;       bf16x8 b[NJ];
; #pragma unroll
;       for (int j = 0; j < NJ; ++j) b[j] = *(const bf16x8*)(Bs + j * 16 * LDT + ks * 32);
; #pragma unroll
;       for (int i = 0; i < MI; ++i) {
;         const bf16x8 a = *(const bf16x8*)(As + i * 16 * LDT + ks * 32);
; #pragma unroll
;         for (int j = 0; j < NJ; ++j) acc[i][j] = SWAP ? mfma16(b[j], a, acc[i][j]) : mfma16(a, b[j], acc[i][j]);
;       }
;     }
;     __syncthreads();
;   }
	ds_write_b128 v250, v[128:131] offset:36864
	v_mfma_f32_16x16x32_bf16 v[16:19], v[194:197], v[242:245], v[16:19]
	ds_read_b128 v[202:205], v182 offset:2368
	s_waitcnt lgkmcnt(4)
	v_mfma_f32_16x16x32_bf16 v[8:11], v[178:181], v[246:249], v[8:11]
	ds_read_b128 v[178:181], v183 offset:36928
	s_add_u32 s52, s2, s55
	s_addc_u32 s53, s3, 0
	v_lshl_add_u64 v[128:129], s[52:53], 0, v[162:163]
	s_nop 0
	global_load_dwordx4 v[128:131], v[128:129], off
	v_mfma_f32_16x16x32_bf16 v[4:7], v[186:189], v[246:249], v[4:7]
	ds_read_b128 v[186:189], v183 offset:39232
	v_mfma_f32_16x16x32_bf16 v[0:3], v[190:193], v[246:249], v[0:3]
	ds_read_b128 v[190:193], v183 offset:41536
	v_mfma_f32_16x16x32_bf16 v[12:15], v[194:197], v[246:249], v[12:15]
	ds_read_b128 v[194:197], v183 offset:43840
	ds_read_b128 v[242:245], v182 offset:4672
	s_waitcnt lgkmcnt(4)
	v_mfma_f32_16x16x32_bf16 v[156:159], v[178:181], v[198:201], v[156:159]
	s_waitcnt vmcnt(7)
	ds_write_b128 v251, v[132:135] offset:36864
	s_waitcnt lgkmcnt(4)
	v_mfma_f32_16x16x32_bf16 v[152:155], v[186:189], v[198:201], v[152:155]
	s_waitcnt lgkmcnt(3)
	v_mfma_f32_16x16x32_bf16 v[148:151], v[190:193], v[198:201], v[148:151]
	v_lshl_add_u64 v[132:133], s[52:53], 0, v[164:165]
	s_nop 0
	global_load_dwordx4 v[132:135], v[132:133], off
	s_waitcnt lgkmcnt(2)
	v_mfma_f32_16x16x32_bf16 v[144:147], v[194:197], v[198:201], v[144:147]
	ds_read_b128 v[246:249], v182 offset:6976
	v_mfma_f32_16x16x32_bf16 v[108:111], v[178:181], v[202:205], v[108:111]
	v_mfma_f32_16x16x32_bf16 v[104:107], v[186:189], v[202:205], v[104:107]
	v_mfma_f32_16x16x32_bf16 v[100:103], v[190:193], v[202:205], v[100:103]
	s_waitcnt vmcnt(7)
	ds_write_b128 v252, v[136:139] offset:36864
	v_mfma_f32_16x16x32_bf16 v[96:99], v[194:197], v[202:205], v[96:99]
	ds_read_b128 v[198:201], v182 offset:9280
	s_waitcnt lgkmcnt(4)
	v_mfma_f32_16x16x32_bf16 v[92:95], v[178:181], v[242:245], v[92:95]
	v_lshl_add_u64 v[136:137], s[52:53], 0, v[166:167]
	s_nop 0
	global_load_dwordx4 v[136:139], v[136:137], off
	v_mfma_f32_16x16x32_bf16 v[88:91], v[186:189], v[242:245], v[88:91]
	v_mfma_f32_16x16x32_bf16 v[84:87], v[190:193], v[242:245], v[84:87]
	v_mfma_f32_16x16x32_bf16 v[80:83], v[194:197], v[242:245], v[80:83]
	ds_read_b128 v[202:205], v182 offset:11584
	s_waitcnt lgkmcnt(3)
	v_mfma_f32_16x16x32_bf16 v[76:79], v[178:181], v[246:249], v[76:79]
	s_waitcnt vmcnt(7)
	ds_write_b128 v253, v[140:143] offset:36864
	v_mfma_f32_16x16x32_bf16 v[72:75], v[186:189], v[246:249], v[72:75]
	v_mfma_f32_16x16x32_bf16 v[68:71], v[190:193], v[246:249], v[68:71]
	v_lshl_add_u64 v[140:141], s[52:53], 0, v[168:169]
	s_nop 0
	global_load_dwordx4 v[140:143], v[140:141], off
	v_mfma_f32_16x16x32_bf16 v[64:67], v[194:197], v[246:249], v[64:67]
	ds_read_b128 v[242:245], v182 offset:13888
	s_waitcnt lgkmcnt(3)
	v_mfma_f32_16x16x32_bf16 v[60:63], v[178:181], v[198:201], v[60:63]
	v_mfma_f32_16x16x32_bf16 v[56:59], v[186:189], v[198:201], v[56:59]
	v_mfma_f32_16x16x32_bf16 v[52:55], v[190:193], v[198:201], v[52:55]
	v_mfma_f32_16x16x32_bf16 v[48:51], v[194:197], v[198:201], v[48:51]
	ds_read_b128 v[246:249], v182 offset:16192
	s_waitcnt lgkmcnt(3)
	v_mfma_f32_16x16x32_bf16 v[44:47], v[178:181], v[202:205], v[44:47]
	v_mfma_f32_16x16x32_bf16 v[40:43], v[186:189], v[202:205], v[40:43]
	v_mfma_f32_16x16x32_bf16 v[36:39], v[190:193], v[202:205], v[36:39]
	v_mfma_f32_16x16x32_bf16 v[32:35], v[194:197], v[202:205], v[32:35]
	s_add_i32 s33, s33, 1
	s_and_b32 s98, s33, 1
	s_mul_i32 s98, s98, 0x12000
	v_add3_u32 v183, s98, v171, v177
	v_add3_u32 v182, s98, v176, v177
	s_cmp_lg_u32 s33, 4
	s_waitcnt lgkmcnt(0)
	s_barrier
	s_cbranch_scc1 .Lgm3_top

; DI f32x4 mfma16(bf16x8 a, bf16x8 b, f32x4 c) { return __builtin_amdgcn_mfma_f32_16x16x32_bf16(a, b, c, 0, 0, 0); }
; template <int MI, int NJ, bool SWAP, class AP, class BP>
; DI void gemm_main(f32x4 (&acc)[MI][NJ], const AP& ap, int a_kstep, const BP& bp, int b_kstep, int nk, bf16_t* smem) {
;     ...
;   gload(0); sstore(0); gload(nk > 1 ? 1 : 0); __syncthreads();
; #pragma unroll 1
;   for (int kt = 0; kt < nk; ++kt) {
;     const int buf = kt & 1;
;     sstore(buf ^ 1);
;     gload(kt + 2 < nk ? kt + 2 : nk - 1);
;     __builtin_amdgcn_sched_barrier(0);
;     const bf16_t* As = smem + buf * L::STAGE + (wm * 16 * MI + l15) * LDT + quad * 8;
;     const bf16_t* Bs = smem + buf * L::STAGE + L::A_ELEMS + (wn * 16 * NJ + l15) * LDT + quad * 8;
; #pragma unroll
;     for (int ks = 0; ks < 2; ++ks) {
;       if (MI * NJ >= 32 && ks == 1) asm volatile("" ::: "memory");
;       bf16x8 b[NJ];
; #pragma unroll
;       for (int j = 0; j < NJ; ++j) b[j] = *(const bf16x8*)(Bs + j * 16 * LDT + ks * 32);
; #pragma unroll
;       for (int i = 0; i < MI; ++i) {
;         const bf16x8 a = *(const bf16x8*)(As + i * 16 * LDT + ks * 32);
; #pragma unroll
;         for (int j = 0; j < NJ; ++j) acc[i][j] = SWAP ? mfma16(b[j], a, acc[i][j]) : mfma16(a, b[j], acc[i][j]);
;       }
;     }
;     __syncthreads();
;   }
.LBB0_400:
	s_and_b32 s98, s5, 1
	s_mul_i32 s98, s98, 0x12000
	v_add3_u32 v182, s98, v176, v177
	v_add3_u32 v183, s98, v171, v177
	ds_read_b128 v[198:201], v182
	ds_read_b128 v[202:205], v182 offset:2304
	ds_read_b128 v[178:181], v183 offset:36864
	ds_read_b128 v[186:189], v183 offset:39168
	ds_read_b128 v[190:193], v183 offset:41472
	ds_read_b128 v[194:197], v183 offset:43776
	s_branch .Lgm4_main
.Lgm4_top:
	ds_read_b128 v[198:201], v182
	ds_read_b128 v[202:205], v182 offset:2304
	v_mfma_f32_16x16x32_bf16 v[28:31], v[242:245], v[178:181], v[28:31]
	v_mfma_f32_16x16x32_bf16 v[8:11], v[246:249], v[178:181], v[8:11]
	ds_read_b128 v[178:181], v183 offset:36864
	v_mfma_f32_16x16x32_bf16 v[24:27], v[242:245], v[186:189], v[24:27]
	v_mfma_f32_16x16x32_bf16 v[4:7], v[246:249], v[186:189], v[4:7]
	ds_read_b128 v[186:189], v183 offset:39168
	v_mfma_f32_16x16x32_bf16 v[20:23], v[242:245], v[190:193], v[20:23]
	v_mfma_f32_16x16x32_bf16 v[0:3], v[246:249], v[190:193], v[0:3]
	ds_read_b128 v[190:193], v183 offset:41472
	v_mfma_f32_16x16x32_bf16 v[16:19], v[242:245], v[194:197], v[16:19]
	v_mfma_f32_16x16x32_bf16 v[12:15], v[246:249], v[194:197], v[12:15]
	ds_read_b128 v[194:197], v183 offset:43776
.Lgm4_main:
	ds_read_b128 v[242:245], v182 offset:4608
	s_waitcnt lgkmcnt(4)
	v_mfma_f32_16x16x32_bf16 v[140:143], v[198:201], v[178:181], v[140:143]
	s_waitcnt lgkmcnt(3)
	v_mfma_f32_16x16x32_bf16 v[120:123], v[198:201], v[186:189], v[120:123]
	s_waitcnt lgkmcnt(2)
	v_mfma_f32_16x16x32_bf16 v[116:119], v[198:201], v[190:193], v[116:119]
	v_lshlrev_b32_e32 v250, 1, v160
	s_and_b32 s16, s5, 1
	s_xor_b32 s33, s16, 1
	s_mul_i32 s33, s33, 0x12000
	v_add3_u32 v250, s33, v250, v172
	s_waitcnt vmcnt(7)
	ds_write_b128 v250, v[124:127]
	s_waitcnt lgkmcnt(2)
	v_mfma_f32_16x16x32_bf16 v[112:115], v[198:201], v[194:197], v[112:115]
	ds_read_b128 v[246:249], v182 offset:6912
	v_mfma_f32_16x16x32_bf16 v[108:111], v[202:205], v[178:181], v[108:111]
	s_cmp_eq_u32 s5, 0
	v_lshlrev_b32_e32 v251, 1, v173
	v_add3_u32 v251, s33, v251, v172
	v_lshlrev_b32_e32 v252, 1, v174
	v_add3_u32 v252, s33, v252, v172
	v_lshlrev_b32_e32 v253, 1, v175
	v_add3_u32 v253, s33, v253, v172
	s_cselect_b32 s33, s48, 0x180
	s_add_u32 s52, s0, s33
	s_addc_u32 s53, s1, 0
	v_lshl_add_u64 v[124:125], s[52:53], 0, v[162:163]
	s_nop 0
	global_load_dwordx4 v[124:127], v[124:125], off
	v_mfma_f32_16x16x32_bf16 v[104:107], v[202:205], v[186:189], v[104:107]
	v_mfma_f32_16x16x32_bf16 v[100:103], v[202:205], v[190:193], v[100:103]
	v_mfma_f32_16x16x32_bf16 v[96:99], v[202:205], v[194:197], v[96:99]
	ds_read_b128 v[198:201], v182 offset:9216
	s_waitcnt lgkmcnt(3)
	v_mfma_f32_16x16x32_bf16 v[92:95], v[242:245], v[178:181], v[92:95]
	s_waitcnt vmcnt(7)
	ds_write_b128 v251, v[128:131]
	v_mfma_f32_16x16x32_bf16 v[88:91], v[242:245], v[186:189], v[88:91]
	v_mfma_f32_16x16x32_bf16 v[84:87], v[242:245], v[190:193], v[84:87]
	v_lshl_add_u64 v[128:129], s[52:53], 0, v[164:165]
	s_nop 0
	global_load_dwordx4 v[128:131], v[128:129], off
	v_mfma_f32_16x16x32_bf16 v[80:83], v[242:245], v[194:197], v[80:83]
	ds_read_b128 v[202:205], v182 offset:11520
	s_waitcnt lgkmcnt(3)
	v_mfma_f32_16x16x32_bf16 v[76:79], v[246:249], v[178:181], v[76:79]
	v_mfma_f32_16x16x32_bf16 v[72:75], v[246:249], v[186:189], v[72:75]
	v_mfma_f32_16x16x32_bf16 v[68:71], v[246:249], v[190:193], v[68:71]
	s_waitcnt vmcnt(7)
	ds_write_b128 v252, v[132:135]
	v_mfma_f32_16x16x32_bf16 v[64:67], v[246:249], v[194:197], v[64:67]
	ds_read_b128 v[242:245], v182 offset:13824
	s_waitcnt lgkmcnt(4)
	v_mfma_f32_16x16x32_bf16 v[60:63], v[198:201], v[178:181], v[60:63]
	v_lshl_add_u64 v[132:133], s[52:53], 0, v[166:167]
	s_nop 0
	global_load_dwordx4 v[132:135], v[132:133], off
	v_mfma_f32_16x16x32_bf16 v[56:59], v[198:201], v[186:189], v[56:59]
	v_mfma_f32_16x16x32_bf16 v[52:55], v[198:201], v[190:193], v[52:55]
	v_mfma_f32_16x16x32_bf16 v[48:51], v[198:201], v[194:197], v[48:51]
	ds_read_b128 v[246:249], v182 offset:16128
	s_waitcnt lgkmcnt(3)
	v_mfma_f32_16x16x32_bf16 v[44:47], v[202:205], v[178:181], v[44:47]
	s_waitcnt vmcnt(7)
; DI f32x4 mfma16(bf16x8 a, bf16x8 b, f32x4 c) { return __builtin_amdgcn_mfma_f32_16x16x32_bf16(a, b, c, 0, 0, 0); }
; template <int MI, int NJ, bool SWAP, class AP, class BP>
; DI void gemm_main(f32x4 (&acc)[MI][NJ], const AP& ap, int a_kstep, const BP& bp, int b_kstep, int nk, bf16_t* smem) {
;     ...
;   for (int kt = 0; kt < nk; ++kt) {
;     const int buf = kt & 1;
;     sstore(buf ^ 1);
;     gload(kt + 2 < nk ? kt + 2 : nk - 1);
;     __builtin_amdgcn_sched_barrier(0);
;     const bf16_t* As = smem + buf * L::STAGE + (wm * 16 * MI + l15) * LDT + quad * 8;
;     const bf16_t* Bs = smem + buf * L::STAGE + L::A_ELEMS + (wn * 16 * NJ + l15) * LDT + quad * 8;
; #pragma unroll
;     for (int ks = 0; ks < 2; ++ks) {
;       if (MI * NJ >= 32 && ks == 1) asm volatile("" ::: "memory");
;       bf16x8 b[NJ];
; #pragma unroll
;       for (int j = 0; j < NJ; ++j) b[j] = *(const bf16x8*)(Bs + j * 16 * LDT + ks * 32);
; #pragma unroll
;       for (int i = 0; i < MI; ++i) {
;         const bf16x8 a = *(const bf16x8*)(As + i * 16 * LDT + ks * 32);
; #pragma unroll
;         for (int j = 0; j < NJ; ++j) acc[i][j] = SWAP ? mfma16(b[j], a, acc[i][j]) : mfma16(a, b[j], acc[i][j]);
;       }
;     }
;     __syncthreads();
;   }
	ds_write_b128 v253, v[136:139]
	v_mfma_f32_16x16x32_bf16 v[40:43], v[202:205], v[186:189], v[40:43]
	v_mfma_f32_16x16x32_bf16 v[36:39], v[202:205], v[190:193], v[36:39]
	v_lshl_add_u64 v[136:137], s[52:53], 0, v[168:169]
	s_nop 0
	global_load_dwordx4 v[136:139], v[136:137], off
	v_mfma_f32_16x16x32_bf16 v[32:35], v[202:205], v[194:197], v[32:35]
	ds_read_b128 v[198:201], v182 offset:64
	s_waitcnt lgkmcnt(3)
	v_mfma_f32_16x16x32_bf16 v[28:31], v[242:245], v[178:181], v[28:31]
	v_mfma_f32_16x16x32_bf16 v[24:27], v[242:245], v[186:189], v[24:27]
	v_mfma_f32_16x16x32_bf16 v[20:23], v[242:245], v[190:193], v[20:23]
	s_waitcnt vmcnt(7)
	ds_write_b128 v250, v[144:147] offset:36864
	v_mfma_f32_16x16x32_bf16 v[16:19], v[242:245], v[194:197], v[16:19]
	ds_read_b128 v[202:205], v182 offset:2368
	s_waitcnt lgkmcnt(4)
	v_mfma_f32_16x16x32_bf16 v[8:11], v[246:249], v[178:181], v[8:11]
	ds_read_b128 v[178:181], v183 offset:36928
	s_add_u32 s52, s2, s33
	s_addc_u32 s53, s3, 0
	v_lshl_add_u64 v[144:145], s[52:53], 0, v[162:163]
	s_nop 0
	global_load_dwordx4 v[144:147], v[144:145], off
	v_mfma_f32_16x16x32_bf16 v[4:7], v[246:249], v[186:189], v[4:7]
	ds_read_b128 v[186:189], v183 offset:39232
	v_mfma_f32_16x16x32_bf16 v[0:3], v[246:249], v[190:193], v[0:3]
	ds_read_b128 v[190:193], v183 offset:41536
	v_mfma_f32_16x16x32_bf16 v[12:15], v[246:249], v[194:197], v[12:15]
	ds_read_b128 v[194:197], v183 offset:43840
	ds_read_b128 v[242:245], v182 offset:4672
	s_waitcnt lgkmcnt(4)
	v_mfma_f32_16x16x32_bf16 v[140:143], v[198:201], v[178:181], v[140:143]
	s_waitcnt vmcnt(7)
	ds_write_b128 v251, v[148:151] offset:36864
	s_waitcnt lgkmcnt(4)
	v_mfma_f32_16x16x32_bf16 v[120:123], v[198:201], v[186:189], v[120:123]
	s_waitcnt lgkmcnt(3)
	v_mfma_f32_16x16x32_bf16 v[116:119], v[198:201], v[190:193], v[116:119]
	v_lshl_add_u64 v[148:149], s[52:53], 0, v[164:165]
	s_nop 0
	global_load_dwordx4 v[148:151], v[148:149], off
	s_waitcnt lgkmcnt(2)
	v_mfma_f32_16x16x32_bf16 v[112:115], v[198:201], v[194:197], v[112:115]
	ds_read_b128 v[246:249], v182 offset:6976
	v_mfma_f32_16x16x32_bf16 v[108:111], v[202:205], v[178:181], v[108:111]
	v_mfma_f32_16x16x32_bf16 v[104:107], v[202:205], v[186:189], v[104:107]
	v_mfma_f32_16x16x32_bf16 v[100:103], v[202:205], v[190:193], v[100:103]
	s_waitcnt vmcnt(7)
	ds_write_b128 v252, v[152:155] offset:36864
	v_mfma_f32_16x16x32_bf16 v[96:99], v[202:205], v[194:197], v[96:99]
	ds_read_b128 v[198:201], v182 offset:9280
	s_waitcnt lgkmcnt(4)
	v_mfma_f32_16x16x32_bf16 v[92:95], v[242:245], v[178:181], v[92:95]
	v_lshl_add_u64 v[152:153], s[52:53], 0, v[166:167]
	s_nop 0
	global_load_dwordx4 v[152:155], v[152:153], off
	v_mfma_f32_16x16x32_bf16 v[88:91], v[242:245], v[186:189], v[88:91]
	v_mfma_f32_16x16x32_bf16 v[84:87], v[242:245], v[190:193], v[84:87]
	v_mfma_f32_16x16x32_bf16 v[80:83], v[242:245], v[194:197], v[80:83]
	ds_read_b128 v[202:205], v182 offset:11584
	s_waitcnt lgkmcnt(3)
	v_mfma_f32_16x16x32_bf16 v[76:79], v[246:249], v[178:181], v[76:79]
	s_waitcnt vmcnt(7)
	ds_write_b128 v253, v[156:159] offset:36864
	v_mfma_f32_16x16x32_bf16 v[72:75], v[246:249], v[186:189], v[72:75]
	v_mfma_f32_16x16x32_bf16 v[68:71], v[246:249], v[190:193], v[68:71]
	v_lshl_add_u64 v[156:157], s[52:53], 0, v[168:169]
	s_nop 0
	global_load_dwordx4 v[156:159], v[156:157], off
	v_mfma_f32_16x16x32_bf16 v[64:67], v[246:249], v[194:197], v[64:67]
	ds_read_b128 v[242:245], v182 offset:13888
	s_waitcnt lgkmcnt(3)
	v_mfma_f32_16x16x32_bf16 v[60:63], v[198:201], v[178:181], v[60:63]
	v_mfma_f32_16x16x32_bf16 v[56:59], v[198:201], v[186:189], v[56:59]
	v_mfma_f32_16x16x32_bf16 v[52:55], v[198:201], v[190:193], v[52:55]
	v_mfma_f32_16x16x32_bf16 v[48:51], v[198:201], v[194:197], v[48:51]
	ds_read_b128 v[246:249], v182 offset:16192
	s_waitcnt lgkmcnt(3)
	v_mfma_f32_16x16x32_bf16 v[44:47], v[202:205], v[178:181], v[44:47]
	v_mfma_f32_16x16x32_bf16 v[40:43], v[202:205], v[186:189], v[40:43]
	v_mfma_f32_16x16x32_bf16 v[36:39], v[202:205], v[190:193], v[36:39]
	v_mfma_f32_16x16x32_bf16 v[32:35], v[202:205], v[194:197], v[32:35]
	s_add_i32 s5, s5, 1
	s_and_b32 s98, s5, 1
	s_mul_i32 s98, s98, 0x12000
	v_add3_u32 v182, s98, v176, v177
	v_add3_u32 v183, s98, v171, v177
	s_cmp_lg_u32 s5, 4
	s_waitcnt lgkmcnt(0)
	s_barrier
	s_cbranch_scc1 .Lgm4_top

; DI f32x4 mfma16(bf16x8 a, bf16x8 b, f32x4 c) { return __builtin_amdgcn_mfma_f32_16x16x32_bf16(a, b, c, 0, 0, 0); }
; DI void merge_tile(const Params& p, int layer, int tm, int tn, bf16_t* smem) {
;     ...
;   for (int sg = 0; sg < 6; ++sg) {
;     const int nk = (sg & 1) ? 8 : 16;
; #pragma unroll 1
;     for (int kt = 0; kt < nk; ++kt) {
;       sstore(buf ^ 1);
;       gload_next();
;       __builtin_amdgcn_sched_barrier(0);
;       const bf16_t* As = smem + buf * L::STAGE + (wm * 128 + l15) * LDT + quad * 8;
;       const bf16_t* Bs = smem + buf * L::STAGE + L::A_ELEMS + (wn * 32 + l15) * LDT + quad * 8;
; #pragma unroll
;       for (int ks = 0; ks < 2; ++ks) {
;         if (ks == 1) asm volatile("" ::: "memory");
;         bf16x8 b[2];
; #pragma unroll
;         for (int j = 0; j < 2; ++j) b[j] = *(const bf16x8*)(Bs + j * 16 * LDT + ks * 32);
; #pragma unroll
;         for (int i = 0; i < 8; ++i) {
;           const bf16x8 a = *(const bf16x8*)(As + i * 16 * LDT + ks * 32);
; #pragma unroll
;           for (int j = 0; j < 2; ++j) acc[i][j] = mfma16(b[j], a, acc[i][j]);
;         }
;       }
;       __syncthreads();
;       buf ^= 1;
;     }
.LBB0_836:
	s_mul_i32 s98, s45, 0xd800
	v_add3_u32 v164, s98, v231, v236
	v_add3_u32 v165, s98, v230, v236
	ds_read_b128 v[156:159], v165
	ds_read_b128 v[166:169], v165 offset:2304
	ds_read_b128 v[170:173], v165 offset:4608
	ds_read_b128 v[174:177], v165 offset:6912
	ds_read_b128 v[152:155], v164 offset:36864
	ds_read_b128 v[160:163], v164 offset:39168
	s_branch .Lmg0_main
.Lmg0_top:
	ds_read_b128 v[156:159], v165
	ds_read_b128 v[166:169], v165 offset:2304
	ds_read_b128 v[170:173], v165 offset:4608
	ds_read_b128 v[174:177], v165 offset:6912
	ds_read_b128 v[152:155], v164 offset:36864
	ds_read_b128 v[160:163], v164 offset:39168
	v_mfma_f32_16x16x32_bf16 v[116:119], v[194:197], v[178:181], v[116:119]
	v_mfma_f32_16x16x32_bf16 v[108:111], v[194:197], v[182:185], v[108:111]
	v_mfma_f32_16x16x32_bf16 v[100:103], v[194:197], v[186:189], v[100:103]
	v_mfma_f32_16x16x32_bf16 v[92:95], v[194:197], v[190:193], v[92:95]
	v_mfma_f32_16x16x32_bf16 v[112:115], v[198:201], v[178:181], v[112:115]
	v_mfma_f32_16x16x32_bf16 v[104:107], v[198:201], v[182:185], v[104:107]
	v_mfma_f32_16x16x32_bf16 v[96:99], v[198:201], v[186:189], v[96:99]
	v_mfma_f32_16x16x32_bf16 v[88:91], v[198:201], v[190:193], v[88:91]

; DI f32x4 mfma16(bf16x8 a, bf16x8 b, f32x4 c) { return __builtin_amdgcn_mfma_f32_16x16x32_bf16(a, b, c, 0, 0, 0); }
; DI void merge_tile(const Params& p, int layer, int tm, int tn, bf16_t* smem) {
;     ...
;   for (int sg = 0; sg < 6; ++sg) {
;     const int nk = (sg & 1) ? 8 : 16;
; #pragma unroll 1
;     for (int kt = 0; kt < nk; ++kt) {
;       sstore(buf ^ 1);
;       gload_next();
;       __builtin_amdgcn_sched_barrier(0);
;       const bf16_t* As = smem + buf * L::STAGE + (wm * 128 + l15) * LDT + quad * 8;
;       const bf16_t* Bs = smem + buf * L::STAGE + L::A_ELEMS + (wn * 32 + l15) * LDT + quad * 8;
; #pragma unroll
;       for (int ks = 0; ks < 2; ++ks) {
;         if (ks == 1) asm volatile("" ::: "memory");
;         bf16x8 b[2];
; #pragma unroll
;         for (int j = 0; j < 2; ++j) b[j] = *(const bf16x8*)(Bs + j * 16 * LDT + ks * 32);
; #pragma unroll
;         for (int i = 0; i < 8; ++i) {
;           const bf16x8 a = *(const bf16x8*)(As + i * 16 * LDT + ks * 32);
; #pragma unroll
;           for (int j = 0; j < 2; ++j) acc[i][j] = mfma16(b[j], a, acc[i][j]);
;         }
;       }
;       __syncthreads();
;       buf ^= 1;
;     }
.LBB0_845:
	s_add_i32 s33, s33, -1
	s_mov_b32 s45, s44
	s_mul_i32 s98, s45, 0xd800
	v_add3_u32 v164, s98, v231, v236
	v_add3_u32 v165, s98, v230, v236
	s_cmp_eq_u32 s33, 0
	s_waitcnt lgkmcnt(0)
	s_barrier
	s_cbranch_scc0 .Lmg0_top

; DI f32x4 mfma16(bf16x8 a, bf16x8 b, f32x4 c) { return __builtin_amdgcn_mfma_f32_16x16x32_bf16(a, b, c, 0, 0, 0); }
; template <int MI, int NJ, bool SWAP, class AP, class BP>
; DI void gemm_main(f32x4 (&acc)[MI][NJ], const AP& ap, int a_kstep, const BP& bp, int b_kstep, int nk, bf16_t* smem) {
;     ...
;   gload(0); sstore(0); gload(nk > 1 ? 1 : 0); __syncthreads();
; #pragma unroll 1
;   for (int kt = 0; kt < nk; ++kt) {
;     const int buf = kt & 1;
;     sstore(buf ^ 1);
;     gload(kt + 2 < nk ? kt + 2 : nk - 1);
;     __builtin_amdgcn_sched_barrier(0);
;     const bf16_t* As = smem + buf * L::STAGE + (wm * 16 * MI + l15) * LDT + quad * 8;
;     const bf16_t* Bs = smem + buf * L::STAGE + L::A_ELEMS + (wn * 16 * NJ + l15) * LDT + quad * 8;
; #pragma unroll
;     for (int ks = 0; ks < 2; ++ks) {
;       if (MI * NJ >= 32 && ks == 1) asm volatile("" ::: "memory");
;       bf16x8 b[NJ];
; #pragma unroll
;       for (int j = 0; j < NJ; ++j) b[j] = *(const bf16x8*)(Bs + j * 16 * LDT + ks * 32);
; #pragma unroll
;       for (int i = 0; i < MI; ++i) {
;         const bf16x8 a = *(const bf16x8*)(As + i * 16 * LDT + ks * 32);
; #pragma unroll
;         for (int j = 0; j < NJ; ++j) acc[i][j] = SWAP ? mfma16(b[j], a, acc[i][j]) : mfma16(a, b[j], acc[i][j]);
;       }
;     }
;     __syncthreads();
;   }
.LBB0_910:
	s_and_b32 s98, s1, 1
	s_mul_i32 s98, s98, 0x12000
	v_add3_u32 v202, s98, v160, v173
	v_add3_u32 v177, s98, v171, v173
	ds_read_b128 v[194:197], v177
	ds_read_b128 v[198:201], v177 offset:2304
	ds_read_b128 v[178:181], v202 offset:36864
	ds_read_b128 v[182:185], v202 offset:39168
	ds_read_b128 v[186:189], v202 offset:41472
	ds_read_b128 v[190:193], v202 offset:43776
	s_branch .Lgm5_main
.Lgm5_top:
	ds_read_b128 v[194:197], v177
	ds_read_b128 v[198:201], v177 offset:2304
	v_mfma_f32_16x16x32_bf16 v[28:31], v[178:181], v[242:245], v[28:31]
	v_mfma_f32_16x16x32_bf16 v[8:11], v[178:181], v[246:249], v[8:11]
	ds_read_b128 v[178:181], v202 offset:36864
	v_mfma_f32_16x16x32_bf16 v[24:27], v[182:185], v[242:245], v[24:27]
	v_mfma_f32_16x16x32_bf16 v[4:7], v[182:185], v[246:249], v[4:7]
	ds_read_b128 v[182:185], v202 offset:39168
	v_mfma_f32_16x16x32_bf16 v[20:23], v[186:189], v[242:245], v[20:23]
	v_mfma_f32_16x16x32_bf16 v[0:3], v[186:189], v[246:249], v[0:3]
	ds_read_b128 v[186:189], v202 offset:41472
	v_mfma_f32_16x16x32_bf16 v[16:19], v[190:193], v[242:245], v[16:19]
	v_mfma_f32_16x16x32_bf16 v[12:15], v[190:193], v[246:249], v[12:15]
	ds_read_b128 v[190:193], v202 offset:43776
.Lgm5_main:
	ds_read_b128 v[242:245], v177 offset:4608
	s_waitcnt lgkmcnt(4)
	v_mfma_f32_16x16x32_bf16 v[156:159], v[178:181], v[194:197], v[156:159]
	s_waitcnt lgkmcnt(3)
	v_mfma_f32_16x16x32_bf16 v[152:155], v[182:185], v[194:197], v[152:155]
	s_waitcnt lgkmcnt(2)
	v_mfma_f32_16x16x32_bf16 v[148:151], v[186:189], v[194:197], v[148:151]
	s_and_b32 s15, s1, 1
	s_min_u32 s16, s1, 13
	s_xor_b32 s17, s15, 1
	s_mul_i32 s17, s17, 0x12000
	v_add3_u32 v250, s17, v172, v170
	s_waitcnt vmcnt(7)
	ds_write_b128 v250, v[112:115]
	s_waitcnt lgkmcnt(2)
	v_mfma_f32_16x16x32_bf16 v[128:131], v[190:193], v[194:197], v[128:131]
	ds_read_b128 v[246:249], v177 offset:6912
	v_mfma_f32_16x16x32_bf16 v[108:111], v[178:181], v[198:201], v[108:111]
	s_lshl_b32 s26, s16, 7
	s_add_u32 s16, s2, s26
	v_add3_u32 v251, s17, v174, v170
	v_add3_u32 v252, s17, v175, v170
	v_add3_u32 v253, s17, v176, v170
	s_addc_u32 s17, s3, 0
	v_lshl_add_u64 v[112:113], s[16:17], 0, v[162:163]
	s_nop 0
	global_load_dwordx4 v[112:115], v[112:113], off offset:256
	v_mfma_f32_16x16x32_bf16 v[104:107], v[182:185], v[198:201], v[104:107]
	v_mfma_f32_16x16x32_bf16 v[100:103], v[186:189], v[198:201], v[100:103]
	v_mfma_f32_16x16x32_bf16 v[96:99], v[190:193], v[198:201], v[96:99]
	ds_read_b128 v[194:197], v177 offset:9216
	s_waitcnt lgkmcnt(3)
	v_mfma_f32_16x16x32_bf16 v[92:95], v[178:181], v[242:245], v[92:95]
	s_waitcnt vmcnt(7)
	ds_write_b128 v251, v[116:119]
	v_mfma_f32_16x16x32_bf16 v[88:91], v[182:185], v[242:245], v[88:91]
	v_mfma_f32_16x16x32_bf16 v[84:87], v[186:189], v[242:245], v[84:87]
	v_lshl_add_u64 v[116:117], s[16:17], 0, v[164:165]
	s_nop 0
	global_load_dwordx4 v[116:119], v[116:117], off offset:256
	v_mfma_f32_16x16x32_bf16 v[80:83], v[190:193], v[242:245], v[80:83]
	ds_read_b128 v[198:201], v177 offset:11520
	s_waitcnt lgkmcnt(3)
	v_mfma_f32_16x16x32_bf16 v[76:79], v[178:181], v[246:249], v[76:79]
	v_mfma_f32_16x16x32_bf16 v[72:75], v[182:185], v[246:249], v[72:75]
	v_mfma_f32_16x16x32_bf16 v[68:71], v[186:189], v[246:249], v[68:71]
	s_waitcnt vmcnt(7)
	ds_write_b128 v252, v[120:123]
	v_mfma_f32_16x16x32_bf16 v[64:67], v[190:193], v[246:249], v[64:67]
	ds_read_b128 v[242:245], v177 offset:13824
	s_waitcnt lgkmcnt(4)
	v_mfma_f32_16x16x32_bf16 v[60:63], v[178:181], v[194:197], v[60:63]
	v_lshl_add_u64 v[120:121], s[16:17], 0, v[166:167]
	s_nop 0
	global_load_dwordx4 v[120:123], v[120:121], off offset:256
	v_mfma_f32_16x16x32_bf16 v[56:59], v[182:185], v[194:197], v[56:59]
	v_mfma_f32_16x16x32_bf16 v[52:55], v[186:189], v[194:197], v[52:55]
	v_mfma_f32_16x16x32_bf16 v[48:51], v[190:193], v[194:197], v[48:51]
	ds_read_b128 v[246:249], v177 offset:16128
	s_waitcnt lgkmcnt(3)
	v_mfma_f32_16x16x32_bf16 v[44:47], v[178:181], v[198:201], v[44:47]
	s_waitcnt vmcnt(7)
; DI f32x4 mfma16(bf16x8 a, bf16x8 b, f32x4 c) { return __builtin_amdgcn_mfma_f32_16x16x32_bf16(a, b, c, 0, 0, 0); }
; template <int MI, int NJ, bool SWAP, class AP, class BP>
; DI void gemm_main(f32x4 (&acc)[MI][NJ], const AP& ap, int a_kstep, const BP& bp, int b_kstep, int nk, bf16_t* smem) {
;     ...
;   for (int kt = 0; kt < nk; ++kt) {
;     const int buf = kt & 1;
;     sstore(buf ^ 1);
;     gload(kt + 2 < nk ? kt + 2 : nk - 1);
;     __builtin_amdgcn_sched_barrier(0);
;     const bf16_t* As = smem + buf * L::STAGE + (wm * 16 * MI + l15) * LDT + quad * 8;
;     const bf16_t* Bs = smem + buf * L::STAGE + L::A_ELEMS + (wn * 16 * NJ + l15) * LDT + quad * 8;
; #pragma unroll
;     for (int ks = 0; ks < 2; ++ks) {
;       if (MI * NJ >= 32 && ks == 1) asm volatile("" ::: "memory");
;       bf16x8 b[NJ];
; #pragma unroll
;       for (int j = 0; j < NJ; ++j) b[j] = *(const bf16x8*)(Bs + j * 16 * LDT + ks * 32);
; #pragma unroll
;       for (int i = 0; i < MI; ++i) {
;         const bf16x8 a = *(const bf16x8*)(As + i * 16 * LDT + ks * 32);
; #pragma unroll
;         for (int j = 0; j < NJ; ++j) acc[i][j] = SWAP ? mfma16(b[j], a, acc[i][j]) : mfma16(a, b[j], acc[i][j]);
;       }
;     }
;     __syncthreads();
;   }
	ds_write_b128 v253, v[124:127]
	v_mfma_f32_16x16x32_bf16 v[40:43], v[182:185], v[198:201], v[40:43]
	v_mfma_f32_16x16x32_bf16 v[36:39], v[186:189], v[198:201], v[36:39]
	v_lshl_add_u64 v[124:125], s[16:17], 0, v[168:169]
	s_nop 0
	global_load_dwordx4 v[124:127], v[124:125], off offset:256
	v_mfma_f32_16x16x32_bf16 v[32:35], v[190:193], v[198:201], v[32:35]
	ds_read_b128 v[194:197], v177 offset:64
	s_waitcnt lgkmcnt(3)
	v_mfma_f32_16x16x32_bf16 v[28:31], v[178:181], v[242:245], v[28:31]
	v_mfma_f32_16x16x32_bf16 v[24:27], v[182:185], v[242:245], v[24:27]
	v_mfma_f32_16x16x32_bf16 v[20:23], v[186:189], v[242:245], v[20:23]
	s_waitcnt vmcnt(7)
	ds_write_b128 v250, v[132:135] offset:36864
	v_mfma_f32_16x16x32_bf16 v[16:19], v[190:193], v[242:245], v[16:19]
	ds_read_b128 v[198:201], v177 offset:2368
	s_waitcnt lgkmcnt(4)
	v_mfma_f32_16x16x32_bf16 v[8:11], v[178:181], v[246:249], v[8:11]
	ds_read_b128 v[178:181], v202 offset:36928
	s_add_u32 s16, s12, s26
	s_addc_u32 s17, s13, 0
	v_lshl_add_u64 v[132:133], s[16:17], 0, v[162:163]
	s_nop 0
	global_load_dwordx4 v[132:135], v[132:133], off offset:256
	v_mfma_f32_16x16x32_bf16 v[4:7], v[182:185], v[246:249], v[4:7]
	ds_read_b128 v[182:185], v202 offset:39232
	v_mfma_f32_16x16x32_bf16 v[0:3], v[186:189], v[246:249], v[0:3]
	ds_read_b128 v[186:189], v202 offset:41536
	v_mfma_f32_16x16x32_bf16 v[12:15], v[190:193], v[246:249], v[12:15]
	ds_read_b128 v[190:193], v202 offset:43840
	ds_read_b128 v[242:245], v177 offset:4672
	s_waitcnt lgkmcnt(4)
	v_mfma_f32_16x16x32_bf16 v[156:159], v[178:181], v[194:197], v[156:159]
	s_waitcnt vmcnt(7)
	ds_write_b128 v251, v[136:139] offset:36864
	s_waitcnt lgkmcnt(4)
	v_mfma_f32_16x16x32_bf16 v[152:155], v[182:185], v[194:197], v[152:155]
	s_waitcnt lgkmcnt(3)
	v_mfma_f32_16x16x32_bf16 v[148:151], v[186:189], v[194:197], v[148:151]
	v_lshl_add_u64 v[136:137], s[16:17], 0, v[164:165]
	s_nop 0
	global_load_dwordx4 v[136:139], v[136:137], off offset:256
	s_waitcnt lgkmcnt(2)
	v_mfma_f32_16x16x32_bf16 v[128:131], v[190:193], v[194:197], v[128:131]
	ds_read_b128 v[246:249], v177 offset:6976
	v_mfma_f32_16x16x32_bf16 v[108:111], v[178:181], v[198:201], v[108:111]
	v_mfma_f32_16x16x32_bf16 v[104:107], v[182:185], v[198:201], v[104:107]
	v_mfma_f32_16x16x32_bf16 v[100:103], v[186:189], v[198:201], v[100:103]
	s_waitcnt vmcnt(7)
	ds_write_b128 v252, v[140:143] offset:36864
	v_mfma_f32_16x16x32_bf16 v[96:99], v[190:193], v[198:201], v[96:99]
	ds_read_b128 v[194:197], v177 offset:9280
	s_waitcnt lgkmcnt(4)
	v_mfma_f32_16x16x32_bf16 v[92:95], v[178:181], v[242:245], v[92:95]
	v_lshl_add_u64 v[140:141], s[16:17], 0, v[166:167]
	s_nop 0
	global_load_dwordx4 v[140:143], v[140:141], off offset:256
	v_mfma_f32_16x16x32_bf16 v[88:91], v[182:185], v[242:245], v[88:91]
	v_mfma_f32_16x16x32_bf16 v[84:87], v[186:189], v[242:245], v[84:87]
	v_mfma_f32_16x16x32_bf16 v[80:83], v[190:193], v[242:245], v[80:83]
	ds_read_b128 v[198:201], v177 offset:11584
	s_waitcnt lgkmcnt(3)
	v_mfma_f32_16x16x32_bf16 v[76:79], v[178:181], v[246:249], v[76:79]
	s_waitcnt vmcnt(7)
	ds_write_b128 v253, v[144:147] offset:36864
	v_mfma_f32_16x16x32_bf16 v[72:75], v[182:185], v[246:249], v[72:75]
	v_mfma_f32_16x16x32_bf16 v[68:71], v[186:189], v[246:249], v[68:71]
	v_lshl_add_u64 v[144:145], s[16:17], 0, v[168:169]
	s_nop 0
	global_load_dwordx4 v[144:147], v[144:145], off offset:256
	v_mfma_f32_16x16x32_bf16 v[64:67], v[190:193], v[246:249], v[64:67]
	ds_read_b128 v[242:245], v177 offset:13888
	s_waitcnt lgkmcnt(3)
	v_mfma_f32_16x16x32_bf16 v[60:63], v[178:181], v[194:197], v[60:63]
	v_mfma_f32_16x16x32_bf16 v[56:59], v[182:185], v[194:197], v[56:59]
	v_mfma_f32_16x16x32_bf16 v[52:55], v[186:189], v[194:197], v[52:55]
	v_mfma_f32_16x16x32_bf16 v[48:51], v[190:193], v[194:197], v[48:51]
	ds_read_b128 v[246:249], v177 offset:16192
	s_waitcnt lgkmcnt(3)
	v_mfma_f32_16x16x32_bf16 v[44:47], v[178:181], v[198:201], v[44:47]
	v_mfma_f32_16x16x32_bf16 v[40:43], v[182:185], v[198:201], v[40:43]
	v_mfma_f32_16x16x32_bf16 v[36:39], v[186:189], v[198:201], v[36:39]
	v_mfma_f32_16x16x32_bf16 v[32:35], v[190:193], v[198:201], v[32:35]
	s_add_i32 s1, s1, 1
	s_and_b32 s98, s1, 1
	s_mul_i32 s98, s98, 0x12000
	v_add3_u32 v202, s98, v160, v173
	v_add3_u32 v177, s98, v171, v173
	s_cmp_lg_u32 s1, 16
	s_waitcnt lgkmcnt(0)
	s_barrier
	s_cbranch_scc1 .Lgm5_top

; DI f32x4 mfma16(bf16x8 a, bf16x8 b, f32x4 c) { return __builtin_amdgcn_mfma_f32_16x16x32_bf16(a, b, c, 0, 0, 0); }
; template <int MI, int NJ, bool SWAP, class AP, class BP>
; DI void gemm_main(f32x4 (&acc)[MI][NJ], const AP& ap, int a_kstep, const BP& bp, int b_kstep, int nk, bf16_t* smem) {
;     ...
;   gload(0); sstore(0); gload(nk > 1 ? 1 : 0); __syncthreads();
; #pragma unroll 1
;   for (int kt = 0; kt < nk; ++kt) {
;     const int buf = kt & 1;
;     sstore(buf ^ 1);
;     gload(kt + 2 < nk ? kt + 2 : nk - 1);
;     __builtin_amdgcn_sched_barrier(0);
;     const bf16_t* As = smem + buf * L::STAGE + (wm * 16 * MI + l15) * LDT + quad * 8;
;     const bf16_t* Bs = smem + buf * L::STAGE + L::A_ELEMS + (wn * 16 * NJ + l15) * LDT + quad * 8;
; #pragma unroll
;     for (int ks = 0; ks < 2; ++ks) {
;       if (MI * NJ >= 32 && ks == 1) asm volatile("" ::: "memory");
;       bf16x8 b[NJ];
; #pragma unroll
;       for (int j = 0; j < NJ; ++j) b[j] = *(const bf16x8*)(Bs + j * 16 * LDT + ks * 32);
; #pragma unroll
;       for (int i = 0; i < MI; ++i) {
;         const bf16x8 a = *(const bf16x8*)(As + i * 16 * LDT + ks * 32);
; #pragma unroll
;         for (int j = 0; j < NJ; ++j) acc[i][j] = SWAP ? mfma16(b[j], a, acc[i][j]) : mfma16(a, b[j], acc[i][j]);
;       }
;     }
;     __syncthreads();
;   }
.LBB0_1049:
	s_cmp_eq_u32 s29, 0xfde
	s_cbranch_scc1 .Lgm6r_main
	s_and_b32 s98, s30, 1
	s_mul_i32 s98, s98, 0x12000
	v_add3_u32 v181, s98, v170, v180
	v_add3_u32 v202, s98, v171, v180
	ds_read_b128 v[198:201], v181
	ds_read_b128 v[242:245], v181 offset:2304
	ds_read_b128 v[182:185], v202 offset:36864
	ds_read_b128 v[186:189], v202 offset:39168
	ds_read_b128 v[190:193], v202 offset:41472
	ds_read_b128 v[194:197], v202 offset:43776
	s_branch .Lgm6_main
.Lgm6_top:
	ds_read_b128 v[198:201], v181
	ds_read_b128 v[242:245], v181 offset:2304
	v_mfma_f32_16x16x32_bf16 v[28:31], v[182:185], v[246:249], v[28:31]
	v_mfma_f32_16x16x32_bf16 v[12:15], v[182:185], v[250:253], v[12:15]
	ds_read_b128 v[182:185], v202 offset:36864
	v_mfma_f32_16x16x32_bf16 v[24:27], v[186:189], v[246:249], v[24:27]
	v_mfma_f32_16x16x32_bf16 v[8:11], v[186:189], v[250:253], v[8:11]
	ds_read_b128 v[186:189], v202 offset:39168
	v_mfma_f32_16x16x32_bf16 v[20:23], v[190:193], v[246:249], v[20:23]
	v_mfma_f32_16x16x32_bf16 v[4:7], v[190:193], v[250:253], v[4:7]
	ds_read_b128 v[190:193], v202 offset:41472
	v_mfma_f32_16x16x32_bf16 v[16:19], v[194:197], v[246:249], v[16:19]
	v_mfma_f32_16x16x32_bf16 v[0:3], v[194:197], v[250:253], v[0:3]
	ds_read_b128 v[194:197], v202 offset:43776
.Lgm6_main:
	ds_read_b128 v[246:249], v181 offset:4608
	s_waitcnt lgkmcnt(4)
	v_mfma_f32_16x16x32_bf16 v[156:159], v[182:185], v[198:201], v[156:159]
	s_waitcnt lgkmcnt(3)
	v_mfma_f32_16x16x32_bf16 v[152:155], v[186:189], v[198:201], v[152:155]
	s_waitcnt lgkmcnt(2)
	v_mfma_f32_16x16x32_bf16 v[148:151], v[190:193], v[198:201], v[148:151]
	s_waitcnt vmcnt(7)
	v_cndmask_b32_e32 v139, 0, v139, vcc
	v_cndmask_b32_e32 v138, 0, v138, vcc
	v_cndmask_b32_e32 v137, 0, v137, vcc
	v_cndmask_b32_e32 v136, 0, v136, vcc
	s_and_b32 s31, s30, 1
	s_xor_b32 s33, s31, 1
	s_mul_i32 s33, s33, 0x12000
	v_add3_u32 v254, s33, v172, v169
	ds_write_b128 v254, v[136:139]
	s_waitcnt lgkmcnt(2)
	v_mfma_f32_16x16x32_bf16 v[144:147], v[194:197], v[198:201], v[144:147]
	ds_read_b128 v[250:253], v181 offset:6912
	v_mfma_f32_16x16x32_bf16 v[108:111], v[182:185], v[242:245], v[108:111]
	v_add3_u32 v238, s33, v173, v169
	v_add3_u32 v239, s33, v174, v169
	v_add3_u32 v255, s33, v175, v169
	s_min_u32 s33, s30, 13
	s_lshl_b32 s33, s33, 7
	s_add_u32 s34, s12, s33
	s_addc_u32 s35, s13, 0
	s_nop 0
	global_load_dwordx4 v[136:139], v176, s[34:35] offset:256
	v_mfma_f32_16x16x32_bf16 v[104:107], v[186:189], v[242:245], v[104:107]
	v_mfma_f32_16x16x32_bf16 v[100:103], v[190:193], v[242:245], v[100:103]
	v_mfma_f32_16x16x32_bf16 v[96:99], v[194:197], v[242:245], v[96:99]
	ds_read_b128 v[198:201], v181 offset:9216
	s_waitcnt lgkmcnt(3)
	v_mfma_f32_16x16x32_bf16 v[92:95], v[182:185], v[246:249], v[92:95]
	s_waitcnt vmcnt(7)
	v_cndmask_b32_e64 v127, 0, v127, s[0:1]
	v_cndmask_b32_e64 v126, 0, v126, s[0:1]
	v_cndmask_b32_e64 v125, 0, v125, s[0:1]
	v_cndmask_b32_e64 v124, 0, v124, s[0:1]
	ds_write_b128 v238, v[124:127]
	v_mfma_f32_16x16x32_bf16 v[88:91], v[186:189], v[246:249], v[88:91]
	v_mfma_f32_16x16x32_bf16 v[84:87], v[190:193], v[246:249], v[84:87]
	s_nop 0
	global_load_dwordx4 v[124:127], v177, s[34:35] offset:256
	v_mfma_f32_16x16x32_bf16 v[80:83], v[194:197], v[246:249], v[80:83]
	ds_read_b128 v[242:245], v181 offset:11520
	s_waitcnt lgkmcnt(3)
	v_mfma_f32_16x16x32_bf16 v[76:79], v[182:185], v[250:253], v[76:79]
	v_mfma_f32_16x16x32_bf16 v[72:75], v[186:189], v[250:253], v[72:75]
	v_mfma_f32_16x16x32_bf16 v[68:71], v[190:193], v[250:253], v[68:71]
	s_waitcnt vmcnt(7)
	v_cndmask_b32_e64 v115, 0, v115, s[2:3]
	v_cndmask_b32_e64 v114, 0, v114, s[2:3]
	v_cndmask_b32_e64 v113, 0, v113, s[2:3]
	v_cndmask_b32_e64 v112, 0, v112, s[2:3]
	ds_write_b128 v239, v[112:115]
	v_mfma_f32_16x16x32_bf16 v[64:67], v[194:197], v[250:253], v[64:67]
	ds_read_b128 v[246:249], v181 offset:13824
	s_waitcnt lgkmcnt(4)
	v_mfma_f32_16x16x32_bf16 v[60:63], v[182:185], v[198:201], v[60:63]
	v_mfma_f32_16x16x32_bf16 v[56:59], v[186:189], v[198:201], v[56:59]
	v_mfma_f32_16x16x32_bf16 v[52:55], v[190:193], v[198:201], v[52:55]
	v_mfma_f32_16x16x32_bf16 v[48:51], v[194:197], v[198:201], v[48:51]
	ds_read_b128 v[250:253], v181 offset:16128
	s_waitcnt lgkmcnt(3)
	v_mfma_f32_16x16x32_bf16 v[44:47], v[182:185], v[242:245], v[44:47]
	s_waitcnt vmcnt(6)
; DI f32x4 mfma16(bf16x8 a, bf16x8 b, f32x4 c) { return __builtin_amdgcn_mfma_f32_16x16x32_bf16(a, b, c, 0, 0, 0); }
; template <int MI, int NJ, bool SWAP, class AP, class BP>
; DI void gemm_main(f32x4 (&acc)[MI][NJ], const AP& ap, int a_kstep, const BP& bp, int b_kstep, int nk, bf16_t* smem) {
;     ...
;   for (int kt = 0; kt < nk; ++kt) {
;     const int buf = kt & 1;
;     sstore(buf ^ 1);
;     gload(kt + 2 < nk ? kt + 2 : nk - 1);
;     __builtin_amdgcn_sched_barrier(0);
;     const bf16_t* As = smem + buf * L::STAGE + (wm * 16 * MI + l15) * LDT + quad * 8;
;     const bf16_t* Bs = smem + buf * L::STAGE + L::A_ELEMS + (wn * 16 * NJ + l15) * LDT + quad * 8;
; #pragma unroll
;     for (int ks = 0; ks < 2; ++ks) {
;       if (MI * NJ >= 32 && ks == 1) asm volatile("" ::: "memory");
;       bf16x8 b[NJ];
; #pragma unroll
;       for (int j = 0; j < NJ; ++j) b[j] = *(const bf16x8*)(Bs + j * 16 * LDT + ks * 32);
; #pragma unroll
;       for (int i = 0; i < MI; ++i) {
;         const bf16x8 a = *(const bf16x8*)(As + i * 16 * LDT + ks * 32);
; #pragma unroll
;         for (int j = 0; j < NJ; ++j) acc[i][j] = SWAP ? mfma16(b[j], a, acc[i][j]) : mfma16(a, b[j], acc[i][j]);
;       }
;     }
;     __syncthreads();
;   }
	v_cndmask_b32_e64 v112, 0, v116, s[4:5]
	v_cndmask_b32_e64 v115, 0, v119, s[4:5]
	v_cndmask_b32_e64 v114, 0, v118, s[4:5]
	v_cndmask_b32_e64 v113, 0, v117, s[4:5]
	ds_write_b128 v255, v[112:115]
	v_mfma_f32_16x16x32_bf16 v[40:43], v[186:189], v[242:245], v[40:43]
	v_mfma_f32_16x16x32_bf16 v[36:39], v[190:193], v[242:245], v[36:39]
	s_nop 0
	global_load_dwordx4 v[112:115], v178, s[34:35] offset:256
	s_nop 0
	global_load_dwordx4 v[116:119], v179, s[34:35] offset:256
	v_mfma_f32_16x16x32_bf16 v[32:35], v[194:197], v[242:245], v[32:35]
	ds_read_b128 v[198:201], v181 offset:64
	s_waitcnt lgkmcnt(3)
	v_mfma_f32_16x16x32_bf16 v[28:31], v[182:185], v[246:249], v[28:31]
	v_mfma_f32_16x16x32_bf16 v[24:27], v[186:189], v[246:249], v[24:27]
	v_mfma_f32_16x16x32_bf16 v[20:23], v[190:193], v[246:249], v[20:23]
	s_waitcnt vmcnt(7)
	ds_write_b128 v254, v[120:123] offset:36864
	v_mfma_f32_16x16x32_bf16 v[16:19], v[194:197], v[246:249], v[16:19]
	ds_read_b128 v[242:245], v181 offset:2368
	s_waitcnt lgkmcnt(4)
	v_mfma_f32_16x16x32_bf16 v[12:15], v[182:185], v[250:253], v[12:15]
	ds_read_b128 v[182:185], v202 offset:36928
	s_add_u32 s34, s14, s33
	s_addc_u32 s35, s15, 0
	v_lshl_add_u64 v[120:121], v[160:161], 1, s[34:35]
	s_nop 0
	global_load_dwordx4 v[120:123], v[120:121], off offset:256
	v_mfma_f32_16x16x32_bf16 v[8:11], v[186:189], v[250:253], v[8:11]
	ds_read_b128 v[186:189], v202 offset:39232
	v_mfma_f32_16x16x32_bf16 v[4:7], v[190:193], v[250:253], v[4:7]
	ds_read_b128 v[190:193], v202 offset:41536
	v_mfma_f32_16x16x32_bf16 v[0:3], v[194:197], v[250:253], v[0:3]
	ds_read_b128 v[194:197], v202 offset:43840
	ds_read_b128 v[246:249], v181 offset:4672
	s_waitcnt lgkmcnt(4)
	v_mfma_f32_16x16x32_bf16 v[156:159], v[182:185], v[198:201], v[156:159]
	s_waitcnt vmcnt(7)
	ds_write_b128 v238, v[128:131] offset:36864
	s_waitcnt lgkmcnt(4)
	v_mfma_f32_16x16x32_bf16 v[152:155], v[186:189], v[198:201], v[152:155]
	s_waitcnt lgkmcnt(3)
	v_mfma_f32_16x16x32_bf16 v[148:151], v[190:193], v[198:201], v[148:151]
	v_lshl_add_u64 v[128:129], v[162:163], 1, s[34:35]
	s_nop 0
	global_load_dwordx4 v[128:131], v[128:129], off offset:256
	s_waitcnt lgkmcnt(2)
	v_mfma_f32_16x16x32_bf16 v[144:147], v[194:197], v[198:201], v[144:147]
	ds_read_b128 v[250:253], v181 offset:6976
	v_mfma_f32_16x16x32_bf16 v[108:111], v[182:185], v[242:245], v[108:111]
	v_mfma_f32_16x16x32_bf16 v[104:107], v[186:189], v[242:245], v[104:107]
	v_mfma_f32_16x16x32_bf16 v[100:103], v[190:193], v[242:245], v[100:103]
	s_waitcnt vmcnt(7)
	ds_write_b128 v239, v[132:135] offset:36864
	v_mfma_f32_16x16x32_bf16 v[96:99], v[194:197], v[242:245], v[96:99]
	ds_read_b128 v[198:201], v181 offset:9280
	s_waitcnt lgkmcnt(4)
	v_mfma_f32_16x16x32_bf16 v[92:95], v[182:185], v[246:249], v[92:95]
	v_lshl_add_u64 v[132:133], v[164:165], 1, s[34:35]
	s_nop 0
	global_load_dwordx4 v[132:135], v[132:133], off offset:256
	v_mfma_f32_16x16x32_bf16 v[88:91], v[186:189], v[246:249], v[88:91]
	v_mfma_f32_16x16x32_bf16 v[84:87], v[190:193], v[246:249], v[84:87]
	v_mfma_f32_16x16x32_bf16 v[80:83], v[194:197], v[246:249], v[80:83]
	ds_read_b128 v[242:245], v181 offset:11584
	s_waitcnt lgkmcnt(3)
	v_mfma_f32_16x16x32_bf16 v[76:79], v[182:185], v[250:253], v[76:79]
	s_waitcnt vmcnt(7)
	ds_write_b128 v255, v[140:143] offset:36864
	v_mfma_f32_16x16x32_bf16 v[72:75], v[186:189], v[250:253], v[72:75]
	v_mfma_f32_16x16x32_bf16 v[68:71], v[190:193], v[250:253], v[68:71]
	v_lshl_add_u64 v[140:141], v[166:167], 1, s[34:35]
	s_nop 0
	global_load_dwordx4 v[140:143], v[140:141], off offset:256
	v_mfma_f32_16x16x32_bf16 v[64:67], v[194:197], v[250:253], v[64:67]
	ds_read_b128 v[246:249], v181 offset:13888
	s_waitcnt lgkmcnt(3)
	v_mfma_f32_16x16x32_bf16 v[60:63], v[182:185], v[198:201], v[60:63]
	v_mfma_f32_16x16x32_bf16 v[56:59], v[186:189], v[198:201], v[56:59]
	v_mfma_f32_16x16x32_bf16 v[52:55], v[190:193], v[198:201], v[52:55]
	v_mfma_f32_16x16x32_bf16 v[48:51], v[194:197], v[198:201], v[48:51]
	ds_read_b128 v[250:253], v181 offset:16192
	s_waitcnt lgkmcnt(3)
	v_mfma_f32_16x16x32_bf16 v[44:47], v[182:185], v[242:245], v[44:47]
	v_mfma_f32_16x16x32_bf16 v[40:43], v[186:189], v[242:245], v[40:43]
	v_mfma_f32_16x16x32_bf16 v[36:39], v[190:193], v[242:245], v[36:39]
	v_mfma_f32_16x16x32_bf16 v[32:35], v[194:197], v[242:245], v[32:35]
	s_add_i32 s30, s30, 1
	s_and_b32 s98, s30, 1
	s_mul_i32 s98, s98, 0x12000
	v_add3_u32 v181, s98, v170, v180
	v_add3_u32 v202, s98, v171, v180
	s_cmp_lg_u32 s30, 16
	s_waitcnt lgkmcnt(0)
	s_barrier
	s_cbranch_scc1 .Lgm6_top

; template <int MI, int NJ, bool SWAP, class AP, class BP>
; DI void gemm_main(f32x4 (&acc)[MI][NJ], const AP& ap, int a_kstep, const BP& bp, int b_kstep, int nk, bf16_t* smem) {
;     ...
;   gload(0); sstore(0); gload(nk > 1 ? 1 : 0); __syncthreads();
.LBB0_1128:
	s_and_b32 s98, s21, 1
	s_mul_i32 s98, s98, 0x12000
	v_add3_u32 v202, s98, v160, v176
	v_add3_u32 v177, s98, v171, v176
	ds_read_b128 v[194:197], v177
	ds_read_b128 v[198:201], v177 offset:2304
	ds_read_b128 v[178:181], v202 offset:36864
	ds_read_b128 v[182:185], v202 offset:39168
	ds_read_b128 v[186:189], v202 offset:41472
	ds_read_b128 v[190:193], v202 offset:43776
	s_branch .Lgm7_main

; DI f32x4 mfma16(bf16x8 a, bf16x8 b, f32x4 c) { return __builtin_amdgcn_mfma_f32_16x16x32_bf16(a, b, c, 0, 0, 0); }
; template <int MI, int NJ, bool SWAP, class AP, class BP>
; DI void gemm_main(f32x4 (&acc)[MI][NJ], const AP& ap, int a_kstep, const BP& bp, int b_kstep, int nk, bf16_t* smem) {
;     ...
;   auto gload = [&](int kt) {
;     const bf16_t* ab = ap.base + (size_t)kt * a_kstep; const bf16_t* bb = bp.base + (size_t)kt * b_kstep;
; #pragma unroll
;     for (int i = 0; i < CA; ++i) ra[i] = *(const u32x4*)(ab + pa[i]);
; #pragma unroll
;     for (int i = 0; i < CB; ++i) rb[i] = *(const u32x4*)(bb + pb[i]);
;   };
;   auto sstore = [&](int buf) {
;     bf16_t* As = smem + buf * L::STAGE; bf16_t* Bs = As + L::A_ELEMS;
; #pragma unroll
;     for (int i = 0; i < CA; ++i) { const int c = tid + NTHR * i; *(u32x4*)(As + (c >> 3) * LDT + (c & 7) * 8) = oka[i] ? ra[i] : (u32x4){0u, 0u, 0u, 0u}; }
; #pragma unroll
;     for (int i = 0; i < CB; ++i) { const int c = tid + NTHR * i; *(u32x4*)(Bs + (c >> 3) * LDT + (c & 7) * 8) = rb[i]; }
;   };
;   gload(0); sstore(0); gload(nk > 1 ? 1 : 0); __syncthreads();
; #pragma unroll 1
;   for (int kt = 0; kt < nk; ++kt) {
;     const int buf = kt & 1;
;     sstore(buf ^ 1);
;     gload(kt + 2 < nk ? kt + 2 : nk - 1);
;     __builtin_amdgcn_sched_barrier(0);
;     const bf16_t* As = smem + buf * L::STAGE + (wm * 16 * MI + l15) * LDT + quad * 8;
;     const bf16_t* Bs = smem + buf * L::STAGE + L::A_ELEMS + (wn * 16 * NJ + l15) * LDT + quad * 8;
; #pragma unroll
;     for (int ks = 0; ks < 2; ++ks) {
;       if (MI * NJ >= 32 && ks == 1) asm volatile("" ::: "memory");
;       bf16x8 b[NJ];
; #pragma unroll
;       for (int j = 0; j < NJ; ++j) b[j] = *(const bf16x8*)(Bs + j * 16 * LDT + ks * 32);
; #pragma unroll
;       for (int i = 0; i < MI; ++i) {
;         const bf16x8 a = *(const bf16x8*)(As + i * 16 * LDT + ks * 32);
; #pragma unroll
;         for (int j = 0; j < NJ; ++j) acc[i][j] = SWAP ? mfma16(b[j], a, acc[i][j]) : mfma16(a, b[j], acc[i][j]);
.Lgm7_main:
	ds_read_b128 v[242:245], v177 offset:4608
	s_waitcnt lgkmcnt(4)
	v_mfma_f32_16x16x32_bf16 v[156:159], v[178:181], v[194:197], v[156:159]
	s_waitcnt lgkmcnt(3)
	v_mfma_f32_16x16x32_bf16 v[152:155], v[182:185], v[194:197], v[152:155]
	s_waitcnt lgkmcnt(2)
	v_mfma_f32_16x16x32_bf16 v[148:151], v[186:189], v[194:197], v[148:151]
	s_and_b32 s24, s21, 1
	s_min_u32 s22, s21, 41
	s_xor_b32 s23, s24, 1
	s_mul_i32 s23, s23, 0x12000
	v_add3_u32 v250, s23, v172, v170
	s_waitcnt vmcnt(7)
	ds_write_b128 v250, v[112:115]
	s_waitcnt lgkmcnt(2)
	v_mfma_f32_16x16x32_bf16 v[144:147], v[190:193], v[194:197], v[144:147]
	ds_read_b128 v[246:249], v177 offset:6912
	v_mfma_f32_16x16x32_bf16 v[108:111], v[178:181], v[198:201], v[108:111]
	s_lshl_b32 s25, s22, 7
	s_add_u32 s22, s6, s25
	v_add3_u32 v251, s23, v173, v170
	v_add3_u32 v252, s23, v174, v170
	v_add3_u32 v253, s23, v175, v170
	s_addc_u32 s23, s7, 0
	v_lshl_add_u64 v[112:113], s[22:23], 0, v[162:163]
	s_nop 0
	global_load_dwordx4 v[112:115], v[112:113], off offset:256
	v_mfma_f32_16x16x32_bf16 v[104:107], v[182:185], v[198:201], v[104:107]
	v_mfma_f32_16x16x32_bf16 v[100:103], v[186:189], v[198:201], v[100:103]
	v_mfma_f32_16x16x32_bf16 v[96:99], v[190:193], v[198:201], v[96:99]
	ds_read_b128 v[194:197], v177 offset:9216
	s_waitcnt lgkmcnt(3)
	v_mfma_f32_16x16x32_bf16 v[92:95], v[178:181], v[242:245], v[92:95]
	s_waitcnt vmcnt(7)
	ds_write_b128 v251, v[116:119]
	v_mfma_f32_16x16x32_bf16 v[88:91], v[182:185], v[242:245], v[88:91]
	v_mfma_f32_16x16x32_bf16 v[84:87], v[186:189], v[242:245], v[84:87]
	v_lshl_add_u64 v[116:117], s[22:23], 0, v[164:165]
	s_nop 0
	global_load_dwordx4 v[116:119], v[116:117], off offset:256
	v_mfma_f32_16x16x32_bf16 v[80:83], v[190:193], v[242:245], v[80:83]
	ds_read_b128 v[198:201], v177 offset:11520
	s_waitcnt lgkmcnt(3)
	v_mfma_f32_16x16x32_bf16 v[76:79], v[178:181], v[246:249], v[76:79]
	v_mfma_f32_16x16x32_bf16 v[72:75], v[182:185], v[246:249], v[72:75]
	v_mfma_f32_16x16x32_bf16 v[68:71], v[186:189], v[246:249], v[68:71]
	s_waitcnt vmcnt(7)
	ds_write_b128 v252, v[120:123]
	v_mfma_f32_16x16x32_bf16 v[64:67], v[190:193], v[246:249], v[64:67]
	ds_read_b128 v[242:245], v177 offset:13824
	s_waitcnt lgkmcnt(4)
	v_mfma_f32_16x16x32_bf16 v[60:63], v[178:181], v[194:197], v[60:63]
	v_lshl_add_u64 v[120:121], s[22:23], 0, v[166:167]
	s_nop 0
	global_load_dwordx4 v[120:123], v[120:121], off offset:256
	v_mfma_f32_16x16x32_bf16 v[56:59], v[182:185], v[194:197], v[56:59]
	v_mfma_f32_16x16x32_bf16 v[52:55], v[186:189], v[194:197], v[52:55]
	v_mfma_f32_16x16x32_bf16 v[48:51], v[190:193], v[194:197], v[48:51]
	ds_read_b128 v[246:249], v177 offset:16128
	s_waitcnt lgkmcnt(3)
	v_mfma_f32_16x16x32_bf16 v[44:47], v[178:181], v[198:201], v[44:47]
	s_waitcnt vmcnt(7)
	ds_write_b128 v253, v[124:127]
	v_mfma_f32_16x16x32_bf16 v[40:43], v[182:185], v[198:201], v[40:43]
	v_mfma_f32_16x16x32_bf16 v[36:39], v[186:189], v[198:201], v[36:39]
	v_lshl_add_u64 v[124:125], s[22:23], 0, v[168:169]
	s_nop 0
	global_load_dwordx4 v[124:127], v[124:125], off offset:256
	v_mfma_f32_16x16x32_bf16 v[32:35], v[190:193], v[198:201], v[32:35]
	ds_read_b128 v[194:197], v177 offset:64
	s_waitcnt lgkmcnt(3)
	v_mfma_f32_16x16x32_bf16 v[28:31], v[178:181], v[242:245], v[28:31]
	v_mfma_f32_16x16x32_bf16 v[24:27], v[182:185], v[242:245], v[24:27]
	v_mfma_f32_16x16x32_bf16 v[20:23], v[186:189], v[242:245], v[20:23]
	s_waitcnt vmcnt(7)
	ds_write_b128 v250, v[128:131] offset:36864
	v_mfma_f32_16x16x32_bf16 v[16:19], v[190:193], v[242:245], v[16:19]
	ds_read_b128 v[198:201], v177 offset:2368
	s_waitcnt lgkmcnt(4)
; DI f32x4 mfma16(bf16x8 a, bf16x8 b, f32x4 c) { return __builtin_amdgcn_mfma_f32_16x16x32_bf16(a, b, c, 0, 0, 0); }
; template <int MI, int NJ, bool SWAP, class AP, class BP>
; DI void gemm_main(f32x4 (&acc)[MI][NJ], const AP& ap, int a_kstep, const BP& bp, int b_kstep, int nk, bf16_t* smem) {
;     ...
;   for (int kt = 0; kt < nk; ++kt) {
;     const int buf = kt & 1;
;     sstore(buf ^ 1);
;     gload(kt + 2 < nk ? kt + 2 : nk - 1);
;     __builtin_amdgcn_sched_barrier(0);
;     const bf16_t* As = smem + buf * L::STAGE + (wm * 16 * MI + l15) * LDT + quad * 8;
;     const bf16_t* Bs = smem + buf * L::STAGE + L::A_ELEMS + (wn * 16 * NJ + l15) * LDT + quad * 8;
; #pragma unroll
;     for (int ks = 0; ks < 2; ++ks) {
;       if (MI * NJ >= 32 && ks == 1) asm volatile("" ::: "memory");
;       bf16x8 b[NJ];
; #pragma unroll
;       for (int j = 0; j < NJ; ++j) b[j] = *(const bf16x8*)(Bs + j * 16 * LDT + ks * 32);
; #pragma unroll
;       for (int i = 0; i < MI; ++i) {
;         const bf16x8 a = *(const bf16x8*)(As + i * 16 * LDT + ks * 32);
; #pragma unroll
;         for (int j = 0; j < NJ; ++j) acc[i][j] = SWAP ? mfma16(b[j], a, acc[i][j]) : mfma16(a, b[j], acc[i][j]);
;       }
;     }
;     __syncthreads();
;   }
	v_mfma_f32_16x16x32_bf16 v[8:11], v[178:181], v[246:249], v[8:11]
	ds_read_b128 v[178:181], v202 offset:36928
	s_add_u32 s22, s8, s25
	s_addc_u32 s23, s9, 0
	v_lshl_add_u64 v[128:129], s[22:23], 0, v[162:163]
	s_nop 0
	global_load_dwordx4 v[128:131], v[128:129], off offset:256
	v_mfma_f32_16x16x32_bf16 v[4:7], v[182:185], v[246:249], v[4:7]
	ds_read_b128 v[182:185], v202 offset:39232
	v_mfma_f32_16x16x32_bf16 v[0:3], v[186:189], v[246:249], v[0:3]
	ds_read_b128 v[186:189], v202 offset:41536
	v_mfma_f32_16x16x32_bf16 v[12:15], v[190:193], v[246:249], v[12:15]
	ds_read_b128 v[190:193], v202 offset:43840
	ds_read_b128 v[242:245], v177 offset:4672
	s_waitcnt lgkmcnt(4)
	v_mfma_f32_16x16x32_bf16 v[156:159], v[178:181], v[194:197], v[156:159]
	s_waitcnt vmcnt(7)
	ds_write_b128 v251, v[132:135] offset:36864
	s_waitcnt lgkmcnt(4)
	v_mfma_f32_16x16x32_bf16 v[152:155], v[182:185], v[194:197], v[152:155]
	s_waitcnt lgkmcnt(3)
	v_mfma_f32_16x16x32_bf16 v[148:151], v[186:189], v[194:197], v[148:151]
	v_lshl_add_u64 v[132:133], s[22:23], 0, v[164:165]
	s_nop 0
	global_load_dwordx4 v[132:135], v[132:133], off offset:256
	s_waitcnt lgkmcnt(2)
	v_mfma_f32_16x16x32_bf16 v[144:147], v[190:193], v[194:197], v[144:147]
	ds_read_b128 v[246:249], v177 offset:6976
	v_mfma_f32_16x16x32_bf16 v[108:111], v[178:181], v[198:201], v[108:111]
	v_mfma_f32_16x16x32_bf16 v[104:107], v[182:185], v[198:201], v[104:107]
	v_mfma_f32_16x16x32_bf16 v[100:103], v[186:189], v[198:201], v[100:103]
	s_waitcnt vmcnt(7)
	ds_write_b128 v252, v[136:139] offset:36864
	v_mfma_f32_16x16x32_bf16 v[96:99], v[190:193], v[198:201], v[96:99]
	ds_read_b128 v[194:197], v177 offset:9280
	s_waitcnt lgkmcnt(4)
	v_mfma_f32_16x16x32_bf16 v[92:95], v[178:181], v[242:245], v[92:95]
	v_lshl_add_u64 v[136:137], s[22:23], 0, v[166:167]
	s_nop 0
	global_load_dwordx4 v[136:139], v[136:137], off offset:256
	v_mfma_f32_16x16x32_bf16 v[88:91], v[182:185], v[242:245], v[88:91]
	v_mfma_f32_16x16x32_bf16 v[84:87], v[186:189], v[242:245], v[84:87]
	v_mfma_f32_16x16x32_bf16 v[80:83], v[190:193], v[242:245], v[80:83]
	ds_read_b128 v[198:201], v177 offset:11584
	s_waitcnt lgkmcnt(3)
	v_mfma_f32_16x16x32_bf16 v[76:79], v[178:181], v[246:249], v[76:79]
	s_waitcnt vmcnt(7)
	ds_write_b128 v253, v[140:143] offset:36864
	v_mfma_f32_16x16x32_bf16 v[72:75], v[182:185], v[246:249], v[72:75]
	v_mfma_f32_16x16x32_bf16 v[68:71], v[186:189], v[246:249], v[68:71]
	v_lshl_add_u64 v[140:141], s[22:23], 0, v[168:169]
	s_nop 0
	global_load_dwordx4 v[140:143], v[140:141], off offset:256
	v_mfma_f32_16x16x32_bf16 v[64:67], v[190:193], v[246:249], v[64:67]
	ds_read_b128 v[242:245], v177 offset:13888
	s_waitcnt lgkmcnt(3)
	v_mfma_f32_16x16x32_bf16 v[60:63], v[178:181], v[194:197], v[60:63]
	v_mfma_f32_16x16x32_bf16 v[56:59], v[182:185], v[194:197], v[56:59]
	v_mfma_f32_16x16x32_bf16 v[52:55], v[186:189], v[194:197], v[52:55]
	v_mfma_f32_16x16x32_bf16 v[48:51], v[190:193], v[194:197], v[48:51]
	ds_read_b128 v[246:249], v177 offset:16192
	s_waitcnt lgkmcnt(3)
	v_mfma_f32_16x16x32_bf16 v[44:47], v[178:181], v[198:201], v[44:47]
	v_mfma_f32_16x16x32_bf16 v[40:43], v[182:185], v[198:201], v[40:43]
	v_mfma_f32_16x16x32_bf16 v[36:39], v[186:189], v[198:201], v[36:39]
	v_mfma_f32_16x16x32_bf16 v[32:35], v[190:193], v[198:201], v[32:35]
	s_add_i32 s21, s21, 1
	s_and_b32 s98, s21, 1
	s_mul_i32 s98, s98, 0x12000
	v_add3_u32 v202, s98, v160, v176
	v_add3_u32 v177, s98, v171, v176
	s_cmp_lg_u32 s21, 44
	s_waitcnt lgkmcnt(0)
	s_barrier
	s_cbranch_scc1 .Lgm7_top

; DI f32x4 mfma16(bf16x8 a, bf16x8 b, f32x4 c) { return __builtin_amdgcn_mfma_f32_16x16x32_bf16(a, b, c, 0, 0, 0); }
; template <int MI, int NJ, bool SWAP, class AP, class BP>
; DI void gemm_main(f32x4 (&acc)[MI][NJ], const AP& ap, int a_kstep, const BP& bp, int b_kstep, int nk, bf16_t* smem) {
;     ...
;   for (int kt = 0; kt < nk; ++kt) {
;     const int buf = kt & 1;
;     sstore(buf ^ 1);
;     gload(kt + 2 < nk ? kt + 2 : nk - 1);
;     __builtin_amdgcn_sched_barrier(0);
;     const bf16_t* As = smem + buf * L::STAGE + (wm * 16 * MI + l15) * LDT + quad * 8;
;     const bf16_t* Bs = smem + buf * L::STAGE + L::A_ELEMS + (wn * 16 * NJ + l15) * LDT + quad * 8;
; #pragma unroll
;     for (int ks = 0; ks < 2; ++ks) {
;       if (MI * NJ >= 32 && ks == 1) asm volatile("" ::: "memory");
;       bf16x8 b[NJ];
; #pragma unroll
;       for (int j = 0; j < NJ; ++j) b[j] = *(const bf16x8*)(Bs + j * 16 * LDT + ks * 32);
; #pragma unroll
;       for (int i = 0; i < MI; ++i) {
;         const bf16x8 a = *(const bf16x8*)(As + i * 16 * LDT + ks * 32);
; #pragma unroll
;         for (int j = 0; j < NJ; ++j) acc[i][j] = SWAP ? mfma16(b[j], a, acc[i][j]) : mfma16(a, b[j], acc[i][j]);
.LBB0_1208:
	s_and_b32 s98, s4, 1
	s_mul_i32 s98, s98, 0x12000
	v_add3_u32 v210, s98, v184, v186
	v_add3_u32 v211, s98, v160, v186
	ds_read_b128 v[206:209], v210
	ds_read_b128 v[242:245], v210 offset:2304
	ds_read_b128 v[190:193], v211 offset:36864
	ds_read_b128 v[194:197], v211 offset:39168
	ds_read_b128 v[198:201], v211 offset:41472
	ds_read_b128 v[202:205], v211 offset:43776
	s_branch .Lgm8_main
.Lgm8_top:
	ds_read_b128 v[206:209], v210
	ds_read_b128 v[242:245], v210 offset:2304
	v_mfma_f32_16x16x32_bf16 v[28:31], v[190:193], v[246:249], v[28:31]
	v_mfma_f32_16x16x32_bf16 v[12:15], v[190:193], v[250:253], v[12:15]
	ds_read_b128 v[190:193], v211 offset:36864
	v_mfma_f32_16x16x32_bf16 v[24:27], v[194:197], v[246:249], v[24:27]
	v_mfma_f32_16x16x32_bf16 v[8:11], v[194:197], v[250:253], v[8:11]
	ds_read_b128 v[194:197], v211 offset:39168
	v_mfma_f32_16x16x32_bf16 v[20:23], v[198:201], v[246:249], v[20:23]
	v_mfma_f32_16x16x32_bf16 v[4:7], v[198:201], v[250:253], v[4:7]
	ds_read_b128 v[198:201], v211 offset:41472
	v_mfma_f32_16x16x32_bf16 v[16:19], v[202:205], v[246:249], v[16:19]
	v_mfma_f32_16x16x32_bf16 v[0:3], v[202:205], v[250:253], v[0:3]
	ds_read_b128 v[202:205], v211 offset:43776
.Lgm8_main:
	ds_read_b128 v[246:249], v210 offset:4608
	s_waitcnt lgkmcnt(4)
	v_mfma_f32_16x16x32_bf16 v[124:127], v[190:193], v[206:209], v[124:127]
	s_waitcnt lgkmcnt(3)
	v_mfma_f32_16x16x32_bf16 v[120:123], v[194:197], v[206:209], v[120:123]
	s_waitcnt lgkmcnt(2)
	v_mfma_f32_16x16x32_bf16 v[116:119], v[198:201], v[206:209], v[116:119]
	s_and_b32 s5, s4, 1
	s_xor_b32 s23, s5, 1
	s_mul_i32 s23, s23, 0x12000
	v_add3_u32 v254, s23, v185, v183
	s_waitcnt vmcnt(7)
	ds_write_b128 v254, v[128:131]
	s_waitcnt lgkmcnt(2)
	v_mfma_f32_16x16x32_bf16 v[112:115], v[202:205], v[206:209], v[112:115]
	ds_read_b128 v[250:253], v210 offset:6912
	v_mfma_f32_16x16x32_bf16 v[108:111], v[190:193], v[242:245], v[108:111]
	s_min_u32 s99, s4, 13
	s_lshl_b32 s99, s99, 7
	s_add_u32 s26, s0, s99
	s_addc_u32 s27, s1, 0
	v_lshl_add_u64 v[128:129], s[26:27], 0, v[162:163]
	s_nop 0
	global_load_dwordx4 v[128:131], v[128:129], off offset:256
	v_mfma_f32_16x16x32_bf16 v[104:107], v[194:197], v[242:245], v[104:107]
	v_mfma_f32_16x16x32_bf16 v[100:103], v[198:201], v[242:245], v[100:103]
	v_mfma_f32_16x16x32_bf16 v[96:99], v[202:205], v[242:245], v[96:99]
	ds_read_b128 v[206:209], v210 offset:9216
	s_waitcnt lgkmcnt(3)
	v_mfma_f32_16x16x32_bf16 v[92:95], v[190:193], v[246:249], v[92:95]
	v_add3_u32 v238, s23, v187, v183
	s_waitcnt vmcnt(7)
	ds_write_b128 v238, v[132:135]
	v_mfma_f32_16x16x32_bf16 v[88:91], v[194:197], v[246:249], v[88:91]
	v_mfma_f32_16x16x32_bf16 v[84:87], v[198:201], v[246:249], v[84:87]
	v_lshl_add_u64 v[132:133], s[26:27], 0, v[164:165]
	s_nop 0
	global_load_dwordx4 v[132:135], v[132:133], off offset:256
	v_mfma_f32_16x16x32_bf16 v[80:83], v[202:205], v[246:249], v[80:83]
	ds_read_b128 v[242:245], v210 offset:11520
	s_waitcnt lgkmcnt(3)
	v_mfma_f32_16x16x32_bf16 v[76:79], v[190:193], v[250:253], v[76:79]
	v_mfma_f32_16x16x32_bf16 v[72:75], v[194:197], v[250:253], v[72:75]
	v_mfma_f32_16x16x32_bf16 v[68:71], v[198:201], v[250:253], v[68:71]
	v_add3_u32 v239, s23, v188, v183
	s_waitcnt vmcnt(7)
	ds_write_b128 v239, v[136:139]
	v_mfma_f32_16x16x32_bf16 v[64:67], v[202:205], v[250:253], v[64:67]
	ds_read_b128 v[246:249], v210 offset:13824
	s_waitcnt lgkmcnt(4)
	v_mfma_f32_16x16x32_bf16 v[60:63], v[190:193], v[206:209], v[60:63]
	v_lshl_add_u64 v[136:137], s[26:27], 0, v[166:167]
	s_nop 0
	global_load_dwordx4 v[136:139], v[136:137], off offset:256
	v_mfma_f32_16x16x32_bf16 v[56:59], v[194:197], v[206:209], v[56:59]
	v_mfma_f32_16x16x32_bf16 v[52:55], v[198:201], v[206:209], v[52:55]
	v_mfma_f32_16x16x32_bf16 v[48:51], v[202:205], v[206:209], v[48:51]
	ds_read_b128 v[250:253], v210 offset:16128
	s_waitcnt lgkmcnt(3)
	v_mfma_f32_16x16x32_bf16 v[44:47], v[190:193], v[242:245], v[44:47]
	v_add3_u32 v255, s23, v189, v183
	s_waitcnt vmcnt(7)
; DI f32x4 mfma16(bf16x8 a, bf16x8 b, f32x4 c) { return __builtin_amdgcn_mfma_f32_16x16x32_bf16(a, b, c, 0, 0, 0); }
; template <int MI, int NJ, bool SWAP, class AP, class BP>
; DI void gemm_main(f32x4 (&acc)[MI][NJ], const AP& ap, int a_kstep, const BP& bp, int b_kstep, int nk, bf16_t* smem) {
;     ...
;   auto gload = [&](int kt) {
;     const bf16_t* ab = ap.base + (size_t)kt * a_kstep; const bf16_t* bb = bp.base + (size_t)kt * b_kstep;
; #pragma unroll
;     for (int i = 0; i < CA; ++i) ra[i] = *(const u32x4*)(ab + pa[i]);
; #pragma unroll
;     for (int i = 0; i < CB; ++i) rb[i] = *(const u32x4*)(bb + pb[i]);
;   };
;   auto sstore = [&](int buf) {
;     bf16_t* As = smem + buf * L::STAGE; bf16_t* Bs = As + L::A_ELEMS;
; #pragma unroll
;     for (int i = 0; i < CA; ++i) { const int c = tid + NTHR * i; *(u32x4*)(As + (c >> 3) * LDT + (c & 7) * 8) = oka[i] ? ra[i] : (u32x4){0u, 0u, 0u, 0u}; }
; #pragma unroll
;     for (int i = 0; i < CB; ++i) { const int c = tid + NTHR * i; *(u32x4*)(Bs + (c >> 3) * LDT + (c & 7) * 8) = rb[i]; }
;   };
;   gload(0); sstore(0); gload(nk > 1 ? 1 : 0); __syncthreads();
; #pragma unroll 1
;   for (int kt = 0; kt < nk; ++kt) {
;     const int buf = kt & 1;
;     sstore(buf ^ 1);
;     gload(kt + 2 < nk ? kt + 2 : nk - 1);
;     __builtin_amdgcn_sched_barrier(0);
;     const bf16_t* As = smem + buf * L::STAGE + (wm * 16 * MI + l15) * LDT + quad * 8;
;     const bf16_t* Bs = smem + buf * L::STAGE + L::A_ELEMS + (wn * 16 * NJ + l15) * LDT + quad * 8;
; #pragma unroll
;     for (int ks = 0; ks < 2; ++ks) {
;       if (MI * NJ >= 32 && ks == 1) asm volatile("" ::: "memory");
;       bf16x8 b[NJ];
; #pragma unroll
;       for (int j = 0; j < NJ; ++j) b[j] = *(const bf16x8*)(Bs + j * 16 * LDT + ks * 32);
; #pragma unroll
;       for (int i = 0; i < MI; ++i) {
;         const bf16x8 a = *(const bf16x8*)(As + i * 16 * LDT + ks * 32);
; #pragma unroll
;         for (int j = 0; j < NJ; ++j) acc[i][j] = SWAP ? mfma16(b[j], a, acc[i][j]) : mfma16(a, b[j], acc[i][j]);
;       }
;     }
;     __syncthreads();
;   }
	ds_write_b128 v255, v[140:143]
	v_mfma_f32_16x16x32_bf16 v[40:43], v[194:197], v[242:245], v[40:43]
	v_mfma_f32_16x16x32_bf16 v[36:39], v[198:201], v[242:245], v[36:39]
	v_lshl_add_u64 v[140:141], s[26:27], 0, v[168:169]
	s_nop 0
	global_load_dwordx4 v[140:143], v[140:141], off offset:256
	v_mfma_f32_16x16x32_bf16 v[32:35], v[202:205], v[242:245], v[32:35]
	ds_read_b128 v[206:209], v210 offset:64
	s_waitcnt lgkmcnt(3)
	v_mfma_f32_16x16x32_bf16 v[28:31], v[190:193], v[246:249], v[28:31]
	v_mfma_f32_16x16x32_bf16 v[24:27], v[194:197], v[246:249], v[24:27]
	v_mfma_f32_16x16x32_bf16 v[20:23], v[198:201], v[246:249], v[20:23]
	s_waitcnt vmcnt(7)
	ds_write_b128 v254, v[144:147] offset:36864
	v_mfma_f32_16x16x32_bf16 v[16:19], v[202:205], v[246:249], v[16:19]
	ds_read_b128 v[242:245], v210 offset:2368
	s_waitcnt lgkmcnt(4)
	v_mfma_f32_16x16x32_bf16 v[12:15], v[190:193], v[250:253], v[12:15]
	ds_read_b128 v[190:193], v211 offset:36928
	s_add_u32 s26, s2, s99
	s_addc_u32 s27, s3, 0
	v_lshl_add_u64 v[144:145], s[26:27], 0, v[162:163]
	s_nop 0
	global_load_dwordx4 v[144:147], v[144:145], off offset:256
	v_mfma_f32_16x16x32_bf16 v[8:11], v[194:197], v[250:253], v[8:11]
	ds_read_b128 v[194:197], v211 offset:39232
	v_mfma_f32_16x16x32_bf16 v[4:7], v[198:201], v[250:253], v[4:7]
	ds_read_b128 v[198:201], v211 offset:41536
	v_mfma_f32_16x16x32_bf16 v[0:3], v[202:205], v[250:253], v[0:3]
	ds_read_b128 v[202:205], v211 offset:43840
	ds_read_b128 v[246:249], v210 offset:4672
	s_waitcnt lgkmcnt(4)
	v_mfma_f32_16x16x32_bf16 v[124:127], v[190:193], v[206:209], v[124:127]
	s_waitcnt vmcnt(7)
	ds_write_b128 v238, v[148:151] offset:36864
	s_waitcnt lgkmcnt(4)
	v_mfma_f32_16x16x32_bf16 v[120:123], v[194:197], v[206:209], v[120:123]
	s_waitcnt lgkmcnt(3)
	v_mfma_f32_16x16x32_bf16 v[116:119], v[198:201], v[206:209], v[116:119]
	v_lshl_add_u64 v[148:149], s[26:27], 0, v[164:165]
	s_nop 0
	global_load_dwordx4 v[148:151], v[148:149], off offset:256
	s_waitcnt lgkmcnt(2)
	v_mfma_f32_16x16x32_bf16 v[112:115], v[202:205], v[206:209], v[112:115]
	ds_read_b128 v[250:253], v210 offset:6976
	v_mfma_f32_16x16x32_bf16 v[108:111], v[190:193], v[242:245], v[108:111]
	v_mfma_f32_16x16x32_bf16 v[104:107], v[194:197], v[242:245], v[104:107]
	v_mfma_f32_16x16x32_bf16 v[100:103], v[198:201], v[242:245], v[100:103]
	s_waitcnt vmcnt(7)
	ds_write_b128 v239, v[152:155] offset:36864
	v_mfma_f32_16x16x32_bf16 v[96:99], v[202:205], v[242:245], v[96:99]
	ds_read_b128 v[206:209], v210 offset:9280
	s_waitcnt lgkmcnt(4)
	v_mfma_f32_16x16x32_bf16 v[92:95], v[190:193], v[246:249], v[92:95]
	v_lshl_add_u64 v[152:153], s[26:27], 0, v[166:167]
	s_nop 0
	global_load_dwordx4 v[152:155], v[152:153], off offset:256
	v_mfma_f32_16x16x32_bf16 v[88:91], v[194:197], v[246:249], v[88:91]
	v_mfma_f32_16x16x32_bf16 v[84:87], v[198:201], v[246:249], v[84:87]
	v_mfma_f32_16x16x32_bf16 v[80:83], v[202:205], v[246:249], v[80:83]
	ds_read_b128 v[242:245], v210 offset:11584
	s_waitcnt lgkmcnt(3)
	v_mfma_f32_16x16x32_bf16 v[76:79], v[190:193], v[250:253], v[76:79]
	s_waitcnt vmcnt(7)
	ds_write_b128 v255, v[156:159] offset:36864
	v_mfma_f32_16x16x32_bf16 v[72:75], v[194:197], v[250:253], v[72:75]
	v_mfma_f32_16x16x32_bf16 v[68:71], v[198:201], v[250:253], v[68:71]
	v_lshl_add_u64 v[156:157], s[26:27], 0, v[168:169]
	s_nop 0
	global_load_dwordx4 v[156:159], v[156:157], off offset:256
	v_mfma_f32_16x16x32_bf16 v[64:67], v[202:205], v[250:253], v[64:67]
	ds_read_b128 v[246:249], v210 offset:13888
	s_waitcnt lgkmcnt(3)
	v_mfma_f32_16x16x32_bf16 v[60:63], v[190:193], v[206:209], v[60:63]
	v_mfma_f32_16x16x32_bf16 v[56:59], v[194:197], v[206:209], v[56:59]
	v_mfma_f32_16x16x32_bf16 v[52:55], v[198:201], v[206:209], v[52:55]
	v_mfma_f32_16x16x32_bf16 v[48:51], v[202:205], v[206:209], v[48:51]
	ds_read_b128 v[250:253], v210 offset:16192
	s_waitcnt lgkmcnt(3)
	v_mfma_f32_16x16x32_bf16 v[44:47], v[190:193], v[242:245], v[44:47]
	v_mfma_f32_16x16x32_bf16 v[40:43], v[194:197], v[242:245], v[40:43]
	v_mfma_f32_16x16x32_bf16 v[36:39], v[198:201], v[242:245], v[36:39]
	v_mfma_f32_16x16x32_bf16 v[32:35], v[202:205], v[242:245], v[32:35]
	s_add_i32 s4, s4, 1
	s_and_b32 s98, s4, 1
	s_mul_i32 s98, s98, 0x12000
	v_add3_u32 v210, s98, v184, v186
	v_add3_u32 v211, s98, v160, v186
	s_cmp_lg_u32 s4, 16
	s_waitcnt lgkmcnt(0)
	s_barrier
	s_cbranch_scc1 .Lgm8_top

; DI f32x4 mfma16(bf16x8 a, bf16x8 b, f32x4 c) { return __builtin_amdgcn_mfma_f32_16x16x32_bf16(a, b, c, 0, 0, 0); }
; template <int MI, int NJ, bool SWAP, class AP, class BP>
; DI void gemm_main(f32x4 (&acc)[MI][NJ], const AP& ap, int a_kstep, const BP& bp, int b_kstep, int nk, bf16_t* smem) {
;     ...
;   for (int kt = 0; kt < nk; ++kt) {
;     const int buf = kt & 1;
;     sstore(buf ^ 1);
;     gload(kt + 2 < nk ? kt + 2 : nk - 1);
;     __builtin_amdgcn_sched_barrier(0);
;     const bf16_t* As = smem + buf * L::STAGE + (wm * 16 * MI + l15) * LDT + quad * 8;
;     const bf16_t* Bs = smem + buf * L::STAGE + L::A_ELEMS + (wn * 16 * NJ + l15) * LDT + quad * 8;
; #pragma unroll
;     for (int ks = 0; ks < 2; ++ks) {
;       if (MI * NJ >= 32 && ks == 1) asm volatile("" ::: "memory");
;       bf16x8 b[NJ];
; #pragma unroll
;       for (int j = 0; j < NJ; ++j) b[j] = *(const bf16x8*)(Bs + j * 16 * LDT + ks * 32);
; #pragma unroll
;       for (int i = 0; i < MI; ++i) {
;         const bf16x8 a = *(const bf16x8*)(As + i * 16 * LDT + ks * 32);
; #pragma unroll
;         for (int j = 0; j < NJ; ++j) acc[i][j] = SWAP ? mfma16(b[j], a, acc[i][j]) : mfma16(a, b[j], acc[i][j]);
;       }
;     }
;     __syncthreads();
;   }
.LBB0_1331:
	s_and_b32 s98, s4, 1
	s_mul_i32 s98, s98, 0x12000
	v_add3_u32 v210, s98, v188, v189
	v_add3_u32 v211, s98, v183, v189
	ds_read_b128 v[206:209], v210
	ds_read_b128 v[242:245], v210 offset:2304
	ds_read_b128 v[190:193], v211 offset:36864
	ds_read_b128 v[194:197], v211 offset:39168
	ds_read_b128 v[198:201], v211 offset:41472
	ds_read_b128 v[202:205], v211 offset:43776
	s_branch .Lgm9_main
.Lgm9_top:
	ds_read_b128 v[206:209], v210
	ds_read_b128 v[242:245], v210 offset:2304
	v_mfma_f32_16x16x32_bf16 v[28:31], v[246:249], v[190:193], v[28:31]
	v_mfma_f32_16x16x32_bf16 v[12:15], v[250:253], v[190:193], v[12:15]
	ds_read_b128 v[190:193], v211 offset:36864
	v_mfma_f32_16x16x32_bf16 v[24:27], v[246:249], v[194:197], v[24:27]
	v_mfma_f32_16x16x32_bf16 v[8:11], v[250:253], v[194:197], v[8:11]
	ds_read_b128 v[194:197], v211 offset:39168
	v_mfma_f32_16x16x32_bf16 v[20:23], v[246:249], v[198:201], v[20:23]
	v_mfma_f32_16x16x32_bf16 v[4:7], v[250:253], v[198:201], v[4:7]
	ds_read_b128 v[198:201], v211 offset:41472
	v_mfma_f32_16x16x32_bf16 v[16:19], v[246:249], v[202:205], v[16:19]
	v_mfma_f32_16x16x32_bf16 v[0:3], v[250:253], v[202:205], v[0:3]
	ds_read_b128 v[202:205], v211 offset:43776
.Lgm9_main:
	ds_read_b128 v[246:249], v210 offset:4608
	s_waitcnt lgkmcnt(4)
	v_mfma_f32_16x16x32_bf16 v[124:127], v[206:209], v[190:193], v[124:127]
	s_waitcnt lgkmcnt(3)
	v_mfma_f32_16x16x32_bf16 v[120:123], v[206:209], v[194:197], v[120:123]
	s_waitcnt lgkmcnt(2)
	v_mfma_f32_16x16x32_bf16 v[116:119], v[206:209], v[198:201], v[116:119]
	s_waitcnt lgkmcnt(1)
	v_mfma_f32_16x16x32_bf16 v[112:115], v[206:209], v[202:205], v[112:115]
	s_and_b32 s5, s4, 1
	s_xor_b32 s23, s5, 1
	s_mul_i32 s23, s23, 0x12000
	v_lshlrev_b32_e32 v254, 1, v160
	v_add3_u32 v254, s23, v254, v184
	s_waitcnt vmcnt(7)
	ds_write_b128 v254, v[140:143]
	ds_read_b128 v[250:253], v210 offset:6912
	v_mfma_f32_16x16x32_bf16 v[108:111], v[242:245], v[190:193], v[108:111]
	v_mfma_f32_16x16x32_bf16 v[104:107], v[242:245], v[194:197], v[104:107]
	v_mfma_f32_16x16x32_bf16 v[100:103], v[242:245], v[198:201], v[100:103]
	v_mfma_f32_16x16x32_bf16 v[96:99], v[242:245], v[202:205], v[96:99]
	v_lshlrev_b32_e32 v140, 1, v185
	v_add3_u32 v140, s23, v140, v184
	s_waitcnt vmcnt(6)
	ds_write_b128 v140, v[136:139]
	ds_read_b128 v[206:209], v210 offset:9216
	s_waitcnt lgkmcnt(4)
	v_mfma_f32_16x16x32_bf16 v[92:95], v[246:249], v[190:193], v[92:95]
	v_mfma_f32_16x16x32_bf16 v[88:91], v[246:249], v[194:197], v[88:91]
	v_mfma_f32_16x16x32_bf16 v[84:87], v[246:249], v[198:201], v[84:87]
	v_mfma_f32_16x16x32_bf16 v[80:83], v[246:249], v[202:205], v[80:83]
	ds_read_b128 v[242:245], v210 offset:11520
	s_waitcnt lgkmcnt(3)
	v_mfma_f32_16x16x32_bf16 v[76:79], v[250:253], v[190:193], v[76:79]
	v_lshlrev_b32_e32 v136, 1, v186
	v_add3_u32 v136, s23, v136, v184
	s_waitcnt vmcnt(5)
	ds_write_b128 v136, v[132:135]
	v_mfma_f32_16x16x32_bf16 v[72:75], v[250:253], v[194:197], v[72:75]
	v_mfma_f32_16x16x32_bf16 v[68:71], v[250:253], v[198:201], v[68:71]
	v_mfma_f32_16x16x32_bf16 v[64:67], v[250:253], v[202:205], v[64:67]
	ds_read_b128 v[246:249], v210 offset:13824
	s_waitcnt lgkmcnt(3)
	v_mfma_f32_16x16x32_bf16 v[60:63], v[206:209], v[190:193], v[60:63]
	v_lshlrev_b32_e32 v132, 1, v187
	v_add3_u32 v132, s23, v132, v184
	s_min_u32 s23, s4, 13
	s_lshl_b32 s23, s23, 7
	s_add_u32 s26, s0, s23
	s_addc_u32 s27, s1, 0
	s_waitcnt vmcnt(4)
	ds_write_b128 v132, v[128:131]
	v_mfma_f32_16x16x32_bf16 v[56:59], v[206:209], v[194:197], v[56:59]
	v_mfma_f32_16x16x32_bf16 v[52:55], v[206:209], v[198:201], v[52:55]
	v_mfma_f32_16x16x32_bf16 v[48:51], v[206:209], v[202:205], v[48:51]
	ds_read_b128 v[250:253], v210 offset:16128
	s_waitcnt lgkmcnt(4)
	v_mfma_f32_16x16x32_bf16 v[44:47], v[242:245], v[190:193], v[44:47]
	s_waitcnt vmcnt(3)
	ds_write_b128 v254, v[144:147] offset:36864
	v_mfma_f32_16x16x32_bf16 v[40:43], v[242:245], v[194:197], v[40:43]
	v_mfma_f32_16x16x32_bf16 v[36:39], v[242:245], v[198:201], v[36:39]
	v_mfma_f32_16x16x32_bf16 v[32:35], v[242:245], v[202:205], v[32:35]
	ds_read_b128 v[206:209], v210 offset:64
	s_waitcnt lgkmcnt(4)
	v_mfma_f32_16x16x32_bf16 v[28:31], v[246:249], v[190:193], v[28:31]
	s_waitcnt vmcnt(2)
; DI f32x4 mfma16(bf16x8 a, bf16x8 b, f32x4 c) { return __builtin_amdgcn_mfma_f32_16x16x32_bf16(a, b, c, 0, 0, 0); }
; template <int MI, int NJ, bool SWAP, class AP, class BP>
; DI void gemm_main(f32x4 (&acc)[MI][NJ], const AP& ap, int a_kstep, const BP& bp, int b_kstep, int nk, bf16_t* smem) {
;     ...
;   auto gload = [&](int kt) {
;     const bf16_t* ab = ap.base + (size_t)kt * a_kstep; const bf16_t* bb = bp.base + (size_t)kt * b_kstep;
; #pragma unroll
;     for (int i = 0; i < CA; ++i) ra[i] = *(const u32x4*)(ab + pa[i]);
; #pragma unroll
;     for (int i = 0; i < CB; ++i) rb[i] = *(const u32x4*)(bb + pb[i]);
;   };
;   auto sstore = [&](int buf) {
;     bf16_t* As = smem + buf * L::STAGE; bf16_t* Bs = As + L::A_ELEMS;
; #pragma unroll
;     for (int i = 0; i < CA; ++i) { const int c = tid + NTHR * i; *(u32x4*)(As + (c >> 3) * LDT + (c & 7) * 8) = oka[i] ? ra[i] : (u32x4){0u, 0u, 0u, 0u}; }
; #pragma unroll
;     for (int i = 0; i < CB; ++i) { const int c = tid + NTHR * i; *(u32x4*)(Bs + (c >> 3) * LDT + (c & 7) * 8) = rb[i]; }
;   };
;   gload(0); sstore(0); gload(nk > 1 ? 1 : 0); __syncthreads();
; #pragma unroll 1
;   for (int kt = 0; kt < nk; ++kt) {
;     const int buf = kt & 1;
;     sstore(buf ^ 1);
;     gload(kt + 2 < nk ? kt + 2 : nk - 1);
;     __builtin_amdgcn_sched_barrier(0);
;     const bf16_t* As = smem + buf * L::STAGE + (wm * 16 * MI + l15) * LDT + quad * 8;
;     const bf16_t* Bs = smem + buf * L::STAGE + L::A_ELEMS + (wn * 16 * NJ + l15) * LDT + quad * 8;
; #pragma unroll
;     for (int ks = 0; ks < 2; ++ks) {
;       if (MI * NJ >= 32 && ks == 1) asm volatile("" ::: "memory");
;       bf16x8 b[NJ];
; #pragma unroll
;       for (int j = 0; j < NJ; ++j) b[j] = *(const bf16x8*)(Bs + j * 16 * LDT + ks * 32);
; #pragma unroll
;       for (int i = 0; i < MI; ++i) {
;         const bf16x8 a = *(const bf16x8*)(As + i * 16 * LDT + ks * 32);
; #pragma unroll
;         for (int j = 0; j < NJ; ++j) acc[i][j] = SWAP ? mfma16(b[j], a, acc[i][j]) : mfma16(a, b[j], acc[i][j]);
;       }
;     }
;     __syncthreads();
;   }
	ds_write_b128 v140, v[148:151] offset:36864
	v_mfma_f32_16x16x32_bf16 v[24:27], v[246:249], v[194:197], v[24:27]
	v_mfma_f32_16x16x32_bf16 v[20:23], v[246:249], v[198:201], v[20:23]
	v_mfma_f32_16x16x32_bf16 v[16:19], v[246:249], v[202:205], v[16:19]
	ds_read_b128 v[242:245], v210 offset:2368
	s_waitcnt lgkmcnt(4)
	v_mfma_f32_16x16x32_bf16 v[12:15], v[250:253], v[190:193], v[12:15]
	ds_read_b128 v[190:193], v211 offset:36928
	s_waitcnt vmcnt(1)
	ds_write_b128 v136, v[152:155] offset:36864
	v_mfma_f32_16x16x32_bf16 v[8:11], v[250:253], v[194:197], v[8:11]
	ds_read_b128 v[194:197], v211 offset:39232
	v_mfma_f32_16x16x32_bf16 v[4:7], v[250:253], v[198:201], v[4:7]
	ds_read_b128 v[198:201], v211 offset:41536
	v_mfma_f32_16x16x32_bf16 v[0:3], v[250:253], v[202:205], v[0:3]
	ds_read_b128 v[202:205], v211 offset:43840
	ds_read_b128 v[246:249], v210 offset:4672
	s_waitcnt lgkmcnt(5)
	v_mfma_f32_16x16x32_bf16 v[124:127], v[206:209], v[190:193], v[124:127]
	s_waitcnt lgkmcnt(3)
	v_mfma_f32_16x16x32_bf16 v[120:123], v[206:209], v[194:197], v[120:123]
	s_waitcnt vmcnt(0)
	ds_write_b128 v132, v[156:159] offset:36864
	s_waitcnt lgkmcnt(3)
	v_mfma_f32_16x16x32_bf16 v[116:119], v[206:209], v[198:201], v[116:119]
	s_waitcnt lgkmcnt(2)
	v_mfma_f32_16x16x32_bf16 v[112:115], v[206:209], v[202:205], v[112:115]
	v_lshl_add_u64 v[128:129], s[26:27], 0, v[162:163]
	global_load_dwordx4 v[140:143], v[128:129], off offset:256
	ds_read_b128 v[250:253], v210 offset:6976
	v_mfma_f32_16x16x32_bf16 v[108:111], v[242:245], v[190:193], v[108:111]
	v_mfma_f32_16x16x32_bf16 v[104:107], v[242:245], v[194:197], v[104:107]
	v_lshl_add_u64 v[128:129], s[26:27], 0, v[164:165]
	global_load_dwordx4 v[136:139], v[128:129], off offset:256
	v_mfma_f32_16x16x32_bf16 v[100:103], v[242:245], v[198:201], v[100:103]
	v_mfma_f32_16x16x32_bf16 v[96:99], v[242:245], v[202:205], v[96:99]
	ds_read_b128 v[206:209], v210 offset:9280
	s_waitcnt lgkmcnt(3)
	v_mfma_f32_16x16x32_bf16 v[92:95], v[246:249], v[190:193], v[92:95]
	v_lshl_add_u64 v[128:129], s[26:27], 0, v[166:167]
	global_load_dwordx4 v[132:135], v[128:129], off offset:256
	v_mfma_f32_16x16x32_bf16 v[88:91], v[246:249], v[194:197], v[88:91]
	v_mfma_f32_16x16x32_bf16 v[84:87], v[246:249], v[198:201], v[84:87]
	v_lshl_add_u64 v[128:129], s[26:27], 0, v[168:169]
	s_add_u32 s26, s2, s23
	s_addc_u32 s27, s3, 0
	v_lshl_add_u64 v[144:145], s[26:27], 0, v[162:163]
	v_lshl_add_u64 v[148:149], s[26:27], 0, v[164:165]
	v_lshl_add_u64 v[152:153], s[26:27], 0, v[166:167]
	v_lshl_add_u64 v[156:157], s[26:27], 0, v[168:169]
	global_load_dwordx4 v[128:131], v[128:129], off offset:256
	v_mfma_f32_16x16x32_bf16 v[80:83], v[246:249], v[202:205], v[80:83]
	ds_read_b128 v[242:245], v210 offset:11584
	s_waitcnt lgkmcnt(2)
	v_mfma_f32_16x16x32_bf16 v[76:79], v[250:253], v[190:193], v[76:79]
	v_mfma_f32_16x16x32_bf16 v[72:75], v[250:253], v[194:197], v[72:75]
	s_nop 0
	global_load_dwordx4 v[144:147], v[144:145], off offset:256
	v_mfma_f32_16x16x32_bf16 v[68:71], v[250:253], v[198:201], v[68:71]
	v_mfma_f32_16x16x32_bf16 v[64:67], v[250:253], v[202:205], v[64:67]
	s_nop 0
	global_load_dwordx4 v[148:151], v[148:149], off offset:256
	ds_read_b128 v[246:249], v210 offset:13888
	s_waitcnt lgkmcnt(2)
	v_mfma_f32_16x16x32_bf16 v[60:63], v[206:209], v[190:193], v[60:63]
	v_mfma_f32_16x16x32_bf16 v[56:59], v[206:209], v[194:197], v[56:59]
	v_mfma_f32_16x16x32_bf16 v[52:55], v[206:209], v[198:201], v[52:55]
	s_nop 0
	global_load_dwordx4 v[152:155], v[152:153], off offset:256
	v_mfma_f32_16x16x32_bf16 v[48:51], v[206:209], v[202:205], v[48:51]
	ds_read_b128 v[250:253], v210 offset:16192
	s_waitcnt lgkmcnt(2)
	v_mfma_f32_16x16x32_bf16 v[44:47], v[242:245], v[190:193], v[44:47]
	s_nop 0
	global_load_dwordx4 v[156:159], v[156:157], off offset:256
	v_mfma_f32_16x16x32_bf16 v[40:43], v[242:245], v[194:197], v[40:43]
	v_mfma_f32_16x16x32_bf16 v[36:39], v[242:245], v[198:201], v[36:39]
	v_mfma_f32_16x16x32_bf16 v[32:35], v[242:245], v[202:205], v[32:35]
	s_add_i32 s4, s4, 1
	s_and_b32 s98, s4, 1
	s_mul_i32 s98, s98, 0x12000
	v_add3_u32 v210, s98, v188, v189
	v_add3_u32 v211, s98, v183, v189
	s_cmp_lg_u32 s4, 16
	s_waitcnt lgkmcnt(0)
	s_barrier
	s_cbranch_scc1 .Lgm9_top

; DI f32x4 mfma16(bf16x8 a, bf16x8 b, f32x4 c) { return __builtin_amdgcn_mfma_f32_16x16x32_bf16(a, b, c, 0, 0, 0); }
; template <int MI, int NJ, bool SWAP, class AP, class BP>
; DI void gemm_main(f32x4 (&acc)[MI][NJ], const AP& ap, int a_kstep, const BP& bp, int b_kstep, int nk, bf16_t* smem) {
;     ...
;   for (int kt = 0; kt < nk; ++kt) {
;     const int buf = kt & 1;
;     sstore(buf ^ 1);
;     gload(kt + 2 < nk ? kt + 2 : nk - 1);
;     __builtin_amdgcn_sched_barrier(0);
;     const bf16_t* As = smem + buf * L::STAGE + (wm * 16 * MI + l15) * LDT + quad * 8;
;     const bf16_t* Bs = smem + buf * L::STAGE + L::A_ELEMS + (wn * 16 * NJ + l15) * LDT + quad * 8;
; #pragma unroll
;     for (int ks = 0; ks < 2; ++ks) {
;       if (MI * NJ >= 32 && ks == 1) asm volatile("" ::: "memory");
;       bf16x8 b[NJ];
; #pragma unroll
;       for (int j = 0; j < NJ; ++j) b[j] = *(const bf16x8*)(Bs + j * 16 * LDT + ks * 32);
; #pragma unroll
;       for (int i = 0; i < MI; ++i) {
;         const bf16x8 a = *(const bf16x8*)(As + i * 16 * LDT + ks * 32);
; #pragma unroll
;         for (int j = 0; j < NJ; ++j) acc[i][j] = SWAP ? mfma16(b[j], a, acc[i][j]) : mfma16(a, b[j], acc[i][j]);
;       }
;     }
;     __syncthreads();
;   }
.LBB0_1410:
	s_and_b32 s98, s8, 1
	s_mul_i32 s98, s98, 0x12000
	v_add3_u32 v198, s98, v172, v177
	v_add3_u32 v199, s98, v160, v177
	ds_read_b128 v[194:197], v198
	ds_read_b128 v[242:245], v198 offset:2304
	ds_read_b128 v[178:181], v199 offset:36864
	ds_read_b128 v[182:185], v199 offset:39168
	ds_read_b128 v[186:189], v199 offset:41472
	ds_read_b128 v[190:193], v199 offset:43776
	s_branch .Lgm10_main
.Lgm10_top:
	ds_read_b128 v[194:197], v198
	ds_read_b128 v[242:245], v198 offset:2304
	v_mfma_f32_16x16x32_bf16 v[28:31], v[178:181], v[246:249], v[28:31]
	v_mfma_f32_16x16x32_bf16 v[12:15], v[178:181], v[250:253], v[12:15]
	ds_read_b128 v[178:181], v199 offset:36864
	v_mfma_f32_16x16x32_bf16 v[24:27], v[182:185], v[246:249], v[24:27]
	v_mfma_f32_16x16x32_bf16 v[8:11], v[182:185], v[250:253], v[8:11]
	ds_read_b128 v[182:185], v199 offset:39168
	v_mfma_f32_16x16x32_bf16 v[20:23], v[186:189], v[246:249], v[20:23]
	v_mfma_f32_16x16x32_bf16 v[4:7], v[186:189], v[250:253], v[4:7]
	ds_read_b128 v[186:189], v199 offset:41472
	v_mfma_f32_16x16x32_bf16 v[16:19], v[190:193], v[246:249], v[16:19]
	v_mfma_f32_16x16x32_bf16 v[0:3], v[190:193], v[250:253], v[0:3]
	ds_read_b128 v[190:193], v199 offset:43776
.Lgm10_main:
	ds_read_b128 v[246:249], v198 offset:4608
	s_waitcnt lgkmcnt(4)
	v_mfma_f32_16x16x32_bf16 v[156:159], v[178:181], v[194:197], v[156:159]
	s_waitcnt lgkmcnt(3)
	v_mfma_f32_16x16x32_bf16 v[152:155], v[182:185], v[194:197], v[152:155]
	s_waitcnt lgkmcnt(2)
	v_mfma_f32_16x16x32_bf16 v[148:151], v[186:189], v[194:197], v[148:151]
	s_and_b32 s33, s8, 1
	s_xor_b32 s37, s33, 1
	s_mul_i32 s37, s37, 0x12000
	v_add3_u32 v254, s37, v173, v171
	s_waitcnt vmcnt(7)
	ds_write_b128 v254, v[112:115]
	s_waitcnt lgkmcnt(2)
	v_mfma_f32_16x16x32_bf16 v[144:147], v[190:193], v[194:197], v[144:147]
	ds_read_b128 v[250:253], v198 offset:6912
	v_mfma_f32_16x16x32_bf16 v[108:111], v[178:181], v[242:245], v[108:111]
	s_min_u32 s99, s8, 3
	s_lshl_b32 s99, s99, 7
	s_add_u32 s38, s0, s99
	s_addc_u32 s39, s1, 0
	v_lshl_add_u64 v[112:113], s[38:39], 0, v[162:163]
	s_nop 0
	global_load_dwordx4 v[112:115], v[112:113], off offset:256
	v_mfma_f32_16x16x32_bf16 v[104:107], v[182:185], v[242:245], v[104:107]
	v_mfma_f32_16x16x32_bf16 v[100:103], v[186:189], v[242:245], v[100:103]
	v_mfma_f32_16x16x32_bf16 v[96:99], v[190:193], v[242:245], v[96:99]
	ds_read_b128 v[194:197], v198 offset:9216
	s_waitcnt lgkmcnt(3)
	v_mfma_f32_16x16x32_bf16 v[92:95], v[178:181], v[246:249], v[92:95]
	v_add3_u32 v238, s37, v174, v171
	s_waitcnt vmcnt(6)
	ds_write_b128 v238, v[116:119]
	v_mfma_f32_16x16x32_bf16 v[88:91], v[182:185], v[246:249], v[88:91]
	v_mfma_f32_16x16x32_bf16 v[84:87], v[186:189], v[246:249], v[84:87]
	v_lshl_add_u64 v[116:117], s[38:39], 0, v[164:165]
	s_nop 0
	global_load_dwordx4 v[116:119], v[116:117], off offset:256
	v_mfma_f32_16x16x32_bf16 v[80:83], v[190:193], v[246:249], v[80:83]
	ds_read_b128 v[242:245], v198 offset:11520
	s_waitcnt lgkmcnt(3)
	v_mfma_f32_16x16x32_bf16 v[76:79], v[178:181], v[250:253], v[76:79]
	v_mfma_f32_16x16x32_bf16 v[72:75], v[182:185], v[250:253], v[72:75]
	v_mfma_f32_16x16x32_bf16 v[68:71], v[186:189], v[250:253], v[68:71]
	v_add3_u32 v239, s37, v175, v171
	s_waitcnt vmcnt(6)
	ds_write_b128 v239, v[120:123]
	v_mfma_f32_16x16x32_bf16 v[64:67], v[190:193], v[250:253], v[64:67]
	ds_read_b128 v[246:249], v198 offset:13824
	s_waitcnt lgkmcnt(4)
	v_mfma_f32_16x16x32_bf16 v[60:63], v[178:181], v[194:197], v[60:63]
	v_lshl_add_u64 v[120:121], s[38:39], 0, v[166:167]
	s_nop 0
	global_load_dwordx4 v[120:123], v[120:121], off offset:256
	v_mfma_f32_16x16x32_bf16 v[56:59], v[182:185], v[194:197], v[56:59]
	v_mfma_f32_16x16x32_bf16 v[52:55], v[186:189], v[194:197], v[52:55]
	v_mfma_f32_16x16x32_bf16 v[48:51], v[190:193], v[194:197], v[48:51]
	ds_read_b128 v[250:253], v198 offset:16128
	s_waitcnt lgkmcnt(3)
	v_mfma_f32_16x16x32_bf16 v[44:47], v[178:181], v[242:245], v[44:47]
	v_add3_u32 v255, s37, v176, v171
	s_waitcnt vmcnt(6)
; DI f32x4 mfma16(bf16x8 a, bf16x8 b, f32x4 c) { return __builtin_amdgcn_mfma_f32_16x16x32_bf16(a, b, c, 0, 0, 0); }
; template <int MI, int NJ, bool SWAP, class AP, class BP>
; DI void gemm_main(f32x4 (&acc)[MI][NJ], const AP& ap, int a_kstep, const BP& bp, int b_kstep, int nk, bf16_t* smem) {
;     ...
;   auto gload = [&](int kt) {
;     const bf16_t* ab = ap.base + (size_t)kt * a_kstep; const bf16_t* bb = bp.base + (size_t)kt * b_kstep;
; #pragma unroll
;     for (int i = 0; i < CA; ++i) ra[i] = *(const u32x4*)(ab + pa[i]);
; #pragma unroll
;     for (int i = 0; i < CB; ++i) rb[i] = *(const u32x4*)(bb + pb[i]);
;   };
;   auto sstore = [&](int buf) {
;     bf16_t* As = smem + buf * L::STAGE; bf16_t* Bs = As + L::A_ELEMS;
; #pragma unroll
;     for (int i = 0; i < CA; ++i) { const int c = tid + NTHR * i; *(u32x4*)(As + (c >> 3) * LDT + (c & 7) * 8) = oka[i] ? ra[i] : (u32x4){0u, 0u, 0u, 0u}; }
; #pragma unroll
;     for (int i = 0; i < CB; ++i) { const int c = tid + NTHR * i; *(u32x4*)(Bs + (c >> 3) * LDT + (c & 7) * 8) = rb[i]; }
;   };
;   gload(0); sstore(0); gload(nk > 1 ? 1 : 0); __syncthreads();
; #pragma unroll 1
;   for (int kt = 0; kt < nk; ++kt) {
;     const int buf = kt & 1;
;     sstore(buf ^ 1);
;     gload(kt + 2 < nk ? kt + 2 : nk - 1);
;     __builtin_amdgcn_sched_barrier(0);
;     const bf16_t* As = smem + buf * L::STAGE + (wm * 16 * MI + l15) * LDT + quad * 8;
;     const bf16_t* Bs = smem + buf * L::STAGE + L::A_ELEMS + (wn * 16 * NJ + l15) * LDT + quad * 8;
; #pragma unroll
;     for (int ks = 0; ks < 2; ++ks) {
;       if (MI * NJ >= 32 && ks == 1) asm volatile("" ::: "memory");
;       bf16x8 b[NJ];
; #pragma unroll
;       for (int j = 0; j < NJ; ++j) b[j] = *(const bf16x8*)(Bs + j * 16 * LDT + ks * 32);
; #pragma unroll
;       for (int i = 0; i < MI; ++i) {
;         const bf16x8 a = *(const bf16x8*)(As + i * 16 * LDT + ks * 32);
; #pragma unroll
;         for (int j = 0; j < NJ; ++j) acc[i][j] = SWAP ? mfma16(b[j], a, acc[i][j]) : mfma16(a, b[j], acc[i][j]);
;       }
;     }
;     __syncthreads();
;   }
	ds_write_b128 v255, v[124:127]
	v_mfma_f32_16x16x32_bf16 v[40:43], v[182:185], v[242:245], v[40:43]
	v_mfma_f32_16x16x32_bf16 v[36:39], v[186:189], v[242:245], v[36:39]
	v_lshl_add_u64 v[124:125], s[38:39], 0, v[168:169]
	s_nop 0
	global_load_dwordx4 v[124:127], v[124:125], off offset:256
	v_mfma_f32_16x16x32_bf16 v[32:35], v[190:193], v[242:245], v[32:35]
	ds_read_b128 v[194:197], v198 offset:64
	s_waitcnt lgkmcnt(3)
	v_mfma_f32_16x16x32_bf16 v[28:31], v[178:181], v[246:249], v[28:31]
	v_mfma_f32_16x16x32_bf16 v[24:27], v[182:185], v[246:249], v[24:27]
	v_mfma_f32_16x16x32_bf16 v[20:23], v[186:189], v[246:249], v[20:23]
	ds_write_b128 v254, v[128:131] offset:36864
	v_mfma_f32_16x16x32_bf16 v[16:19], v[190:193], v[246:249], v[16:19]
	ds_read_b128 v[242:245], v198 offset:2368
	s_waitcnt lgkmcnt(4)
	v_mfma_f32_16x16x32_bf16 v[12:15], v[178:181], v[250:253], v[12:15]
	ds_read_b128 v[178:181], v199 offset:36928
	s_add_u32 s38, s2, s99
	s_addc_u32 s39, s3, 0
	v_lshl_add_u64 v[128:129], s[38:39], 0, v[162:163]
	s_nop 0
	global_load_dwordx4 v[128:131], v[128:129], off offset:256
	v_mfma_f32_16x16x32_bf16 v[8:11], v[182:185], v[250:253], v[8:11]
	ds_read_b128 v[182:185], v199 offset:39232
	v_mfma_f32_16x16x32_bf16 v[4:7], v[186:189], v[250:253], v[4:7]
	ds_read_b128 v[186:189], v199 offset:41536
	v_mfma_f32_16x16x32_bf16 v[0:3], v[190:193], v[250:253], v[0:3]
	ds_read_b128 v[190:193], v199 offset:43840
	ds_read_b128 v[246:249], v198 offset:4672
	s_waitcnt lgkmcnt(4)
	v_mfma_f32_16x16x32_bf16 v[156:159], v[178:181], v[194:197], v[156:159]
	s_waitcnt vmcnt(7)
	ds_write_b128 v238, v[132:135] offset:36864
	s_waitcnt lgkmcnt(4)
	v_mfma_f32_16x16x32_bf16 v[152:155], v[182:185], v[194:197], v[152:155]
	s_waitcnt lgkmcnt(3)
	v_mfma_f32_16x16x32_bf16 v[148:151], v[186:189], v[194:197], v[148:151]
	v_lshl_add_u64 v[132:133], s[38:39], 0, v[164:165]
	s_nop 0
	global_load_dwordx4 v[132:135], v[132:133], off offset:256
	s_waitcnt lgkmcnt(2)
	v_mfma_f32_16x16x32_bf16 v[144:147], v[190:193], v[194:197], v[144:147]
	ds_read_b128 v[250:253], v198 offset:6976
	v_mfma_f32_16x16x32_bf16 v[108:111], v[178:181], v[242:245], v[108:111]
	v_mfma_f32_16x16x32_bf16 v[104:107], v[182:185], v[242:245], v[104:107]
	v_mfma_f32_16x16x32_bf16 v[100:103], v[186:189], v[242:245], v[100:103]
	s_waitcnt vmcnt(7)
	ds_write_b128 v239, v[136:139] offset:36864
	v_mfma_f32_16x16x32_bf16 v[96:99], v[190:193], v[242:245], v[96:99]
	ds_read_b128 v[194:197], v198 offset:9280
	s_waitcnt lgkmcnt(4)
	v_mfma_f32_16x16x32_bf16 v[92:95], v[178:181], v[246:249], v[92:95]
	v_lshl_add_u64 v[136:137], s[38:39], 0, v[166:167]
	s_nop 0
	global_load_dwordx4 v[136:139], v[136:137], off offset:256
	v_mfma_f32_16x16x32_bf16 v[88:91], v[182:185], v[246:249], v[88:91]
	v_mfma_f32_16x16x32_bf16 v[84:87], v[186:189], v[246:249], v[84:87]
	v_mfma_f32_16x16x32_bf16 v[80:83], v[190:193], v[246:249], v[80:83]
	ds_read_b128 v[242:245], v198 offset:11584
	s_waitcnt lgkmcnt(3)
	v_mfma_f32_16x16x32_bf16 v[76:79], v[178:181], v[250:253], v[76:79]
	s_waitcnt vmcnt(7)
	ds_write_b128 v255, v[140:143] offset:36864
	v_mfma_f32_16x16x32_bf16 v[72:75], v[182:185], v[250:253], v[72:75]
	v_mfma_f32_16x16x32_bf16 v[68:71], v[186:189], v[250:253], v[68:71]
	v_lshl_add_u64 v[140:141], s[38:39], 0, v[168:169]
	s_nop 0
	global_load_dwordx4 v[140:143], v[140:141], off offset:256
	v_mfma_f32_16x16x32_bf16 v[64:67], v[190:193], v[250:253], v[64:67]
	ds_read_b128 v[246:249], v198 offset:13888
	s_waitcnt lgkmcnt(3)
	v_mfma_f32_16x16x32_bf16 v[60:63], v[178:181], v[194:197], v[60:63]
	v_mfma_f32_16x16x32_bf16 v[56:59], v[182:185], v[194:197], v[56:59]
	v_mfma_f32_16x16x32_bf16 v[52:55], v[186:189], v[194:197], v[52:55]
	v_mfma_f32_16x16x32_bf16 v[48:51], v[190:193], v[194:197], v[48:51]
	ds_read_b128 v[250:253], v198 offset:16192
	s_waitcnt lgkmcnt(3)
	v_mfma_f32_16x16x32_bf16 v[44:47], v[178:181], v[242:245], v[44:47]
	v_mfma_f32_16x16x32_bf16 v[40:43], v[182:185], v[242:245], v[40:43]
	v_mfma_f32_16x16x32_bf16 v[36:39], v[186:189], v[242:245], v[36:39]
	v_mfma_f32_16x16x32_bf16 v[32:35], v[190:193], v[242:245], v[32:35]
	s_add_i32 s8, s8, 1
	s_and_b32 s98, s8, 1
	s_mul_i32 s98, s98, 0x12000
	v_add3_u32 v198, s98, v172, v177
	v_add3_u32 v199, s98, v160, v177
	s_cmp_lg_u32 s8, 6
	s_waitcnt lgkmcnt(0)
	s_barrier
	s_cbranch_scc1 .Lgm10_top

; DI f32x4 mfma16(bf16x8 a, bf16x8 b, f32x4 c) { return __builtin_amdgcn_mfma_f32_16x16x32_bf16(a, b, c, 0, 0, 0); }
; template <int MI, int NJ, bool SWAP, class AP, class BP>
; DI void gemm_main(f32x4 (&acc)[MI][NJ], const AP& ap, int a_kstep, const BP& bp, int b_kstep, int nk, bf16_t* smem) {
;     ...
;   for (int kt = 0; kt < nk; ++kt) {
;     const int buf = kt & 1;
;     sstore(buf ^ 1);
;     gload(kt + 2 < nk ? kt + 2 : nk - 1);
;     __builtin_amdgcn_sched_barrier(0);
;     const bf16_t* As = smem + buf * L::STAGE + (wm * 16 * MI + l15) * LDT + quad * 8;
;     const bf16_t* Bs = smem + buf * L::STAGE + L::A_ELEMS + (wn * 16 * NJ + l15) * LDT + quad * 8;
; #pragma unroll
;     for (int ks = 0; ks < 2; ++ks) {
;       if (MI * NJ >= 32 && ks == 1) asm volatile("" ::: "memory");
;       bf16x8 b[NJ];
; #pragma unroll
;       for (int j = 0; j < NJ; ++j) b[j] = *(const bf16x8*)(Bs + j * 16 * LDT + ks * 32);
; #pragma unroll
;       for (int i = 0; i < MI; ++i) {
;         const bf16x8 a = *(const bf16x8*)(As + i * 16 * LDT + ks * 32);
; #pragma unroll
;         for (int j = 0; j < NJ; ++j) acc[i][j] = SWAP ? mfma16(b[j], a, acc[i][j]) : mfma16(a, b[j], acc[i][j]);
.LBB0_1430:
	s_and_b32 s98, s33, 1
	s_mul_i32 s98, s98, 0x12000
	v_add3_u32 v198, s98, v176, v177
	v_add3_u32 v199, s98, v171, v177
	ds_read_b128 v[194:197], v198
	ds_read_b128 v[242:245], v198 offset:2304
	ds_read_b128 v[178:181], v199 offset:36864
	ds_read_b128 v[182:185], v199 offset:39168
	ds_read_b128 v[186:189], v199 offset:41472
	ds_read_b128 v[190:193], v199 offset:43776
	s_branch .Lgm11_main

; DI f32x4 mfma16(bf16x8 a, bf16x8 b, f32x4 c) { return __builtin_amdgcn_mfma_f32_16x16x32_bf16(a, b, c, 0, 0, 0); }
; template <int MI, int NJ, bool SWAP, class AP, class BP>
; DI void gemm_main(f32x4 (&acc)[MI][NJ], const AP& ap, int a_kstep, const BP& bp, int b_kstep, int nk, bf16_t* smem) {
;     ...
;   auto gload = [&](int kt) {
;     const bf16_t* ab = ap.base + (size_t)kt * a_kstep; const bf16_t* bb = bp.base + (size_t)kt * b_kstep;
; #pragma unroll
;     for (int i = 0; i < CA; ++i) ra[i] = *(const u32x4*)(ab + pa[i]);
; #pragma unroll
;     for (int i = 0; i < CB; ++i) rb[i] = *(const u32x4*)(bb + pb[i]);
;   };
;   auto sstore = [&](int buf) {
;     bf16_t* As = smem + buf * L::STAGE; bf16_t* Bs = As + L::A_ELEMS;
; #pragma unroll
;     for (int i = 0; i < CA; ++i) { const int c = tid + NTHR * i; *(u32x4*)(As + (c >> 3) * LDT + (c & 7) * 8) = oka[i] ? ra[i] : (u32x4){0u, 0u, 0u, 0u}; }
; #pragma unroll
;     for (int i = 0; i < CB; ++i) { const int c = tid + NTHR * i; *(u32x4*)(Bs + (c >> 3) * LDT + (c & 7) * 8) = rb[i]; }
;   };
;   gload(0); sstore(0); gload(nk > 1 ? 1 : 0); __syncthreads();
; #pragma unroll 1
;   for (int kt = 0; kt < nk; ++kt) {
;     const int buf = kt & 1;
;     sstore(buf ^ 1);
;     gload(kt + 2 < nk ? kt + 2 : nk - 1);
;     __builtin_amdgcn_sched_barrier(0);
;     const bf16_t* As = smem + buf * L::STAGE + (wm * 16 * MI + l15) * LDT + quad * 8;
;     const bf16_t* Bs = smem + buf * L::STAGE + L::A_ELEMS + (wn * 16 * NJ + l15) * LDT + quad * 8;
; #pragma unroll
;     for (int ks = 0; ks < 2; ++ks) {
;       if (MI * NJ >= 32 && ks == 1) asm volatile("" ::: "memory");
;       bf16x8 b[NJ];
; #pragma unroll
;       for (int j = 0; j < NJ; ++j) b[j] = *(const bf16x8*)(Bs + j * 16 * LDT + ks * 32);
; #pragma unroll
;       for (int i = 0; i < MI; ++i) {
;         const bf16x8 a = *(const bf16x8*)(As + i * 16 * LDT + ks * 32);
; #pragma unroll
;         for (int j = 0; j < NJ; ++j) acc[i][j] = SWAP ? mfma16(b[j], a, acc[i][j]) : mfma16(a, b[j], acc[i][j]);
.Lgm11_main:
	ds_read_b128 v[246:249], v198 offset:4608
	s_waitcnt lgkmcnt(4)
	v_mfma_f32_16x16x32_bf16 v[156:159], v[178:181], v[194:197], v[156:159]
	s_waitcnt lgkmcnt(3)
	v_mfma_f32_16x16x32_bf16 v[152:155], v[182:185], v[194:197], v[152:155]
	s_waitcnt lgkmcnt(2)
	v_mfma_f32_16x16x32_bf16 v[148:151], v[186:189], v[194:197], v[148:151]
	s_waitcnt lgkmcnt(1)
	v_mfma_f32_16x16x32_bf16 v[144:147], v[190:193], v[194:197], v[144:147]
	s_and_b32 s37, s33, 1
	s_xor_b32 s38, s37, 1
	s_mul_i32 s38, s38, 0x12000
	v_lshlrev_b32_e32 v254, 1, v160
	v_add3_u32 v254, s38, v254, v172
	s_waitcnt vmcnt(7)
	ds_write_b128 v254, v[124:127]
	ds_read_b128 v[250:253], v198 offset:6912
	v_mfma_f32_16x16x32_bf16 v[108:111], v[178:181], v[242:245], v[108:111]
	v_mfma_f32_16x16x32_bf16 v[104:107], v[182:185], v[242:245], v[104:107]
	v_mfma_f32_16x16x32_bf16 v[100:103], v[186:189], v[242:245], v[100:103]
	v_mfma_f32_16x16x32_bf16 v[96:99], v[190:193], v[242:245], v[96:99]
	v_lshlrev_b32_e32 v124, 1, v173
	v_add3_u32 v124, s38, v124, v172
	s_waitcnt vmcnt(6)
	ds_write_b128 v124, v[120:123]
	ds_read_b128 v[194:197], v198 offset:9216
	s_waitcnt lgkmcnt(4)
	v_mfma_f32_16x16x32_bf16 v[92:95], v[178:181], v[246:249], v[92:95]
	v_mfma_f32_16x16x32_bf16 v[88:91], v[182:185], v[246:249], v[88:91]
	v_mfma_f32_16x16x32_bf16 v[84:87], v[186:189], v[246:249], v[84:87]
	v_mfma_f32_16x16x32_bf16 v[80:83], v[190:193], v[246:249], v[80:83]
	ds_read_b128 v[242:245], v198 offset:11520
	s_waitcnt lgkmcnt(3)
	v_mfma_f32_16x16x32_bf16 v[76:79], v[178:181], v[250:253], v[76:79]
	v_lshlrev_b32_e32 v120, 1, v174
	v_add3_u32 v120, s38, v120, v172
	s_cmp_eq_u32 s33, 0
	s_waitcnt vmcnt(5)
	ds_write_b128 v120, v[116:119]
	v_mfma_f32_16x16x32_bf16 v[72:75], v[182:185], v[250:253], v[72:75]
	v_mfma_f32_16x16x32_bf16 v[68:71], v[186:189], v[250:253], v[68:71]
	v_mfma_f32_16x16x32_bf16 v[64:67], v[190:193], v[250:253], v[64:67]
	ds_read_b128 v[246:249], v198 offset:13824
	s_waitcnt lgkmcnt(3)
	v_mfma_f32_16x16x32_bf16 v[60:63], v[178:181], v[194:197], v[60:63]
	v_lshlrev_b32_e32 v116, 1, v175
	s_cselect_b32 s40, s31, 0x180
	v_add3_u32 v116, s38, v116, v172
	s_add_u32 s38, s0, s40
	s_addc_u32 s39, s1, 0
	s_waitcnt vmcnt(4)
	ds_write_b128 v116, v[112:115]
	v_mfma_f32_16x16x32_bf16 v[56:59], v[182:185], v[194:197], v[56:59]
	v_mfma_f32_16x16x32_bf16 v[52:55], v[186:189], v[194:197], v[52:55]
	v_mfma_f32_16x16x32_bf16 v[48:51], v[190:193], v[194:197], v[48:51]
	ds_read_b128 v[250:253], v198 offset:16128
	s_waitcnt lgkmcnt(4)
	v_mfma_f32_16x16x32_bf16 v[44:47], v[178:181], v[242:245], v[44:47]
	s_waitcnt vmcnt(3)
	ds_write_b128 v254, v[128:131] offset:36864
	v_mfma_f32_16x16x32_bf16 v[40:43], v[182:185], v[242:245], v[40:43]
	v_mfma_f32_16x16x32_bf16 v[36:39], v[186:189], v[242:245], v[36:39]
	v_mfma_f32_16x16x32_bf16 v[32:35], v[190:193], v[242:245], v[32:35]
	ds_read_b128 v[194:197], v198 offset:64
	s_waitcnt lgkmcnt(4)
	v_mfma_f32_16x16x32_bf16 v[28:31], v[178:181], v[246:249], v[28:31]
	s_waitcnt vmcnt(2)
	ds_write_b128 v124, v[132:135] offset:36864
	v_mfma_f32_16x16x32_bf16 v[24:27], v[182:185], v[246:249], v[24:27]
	v_mfma_f32_16x16x32_bf16 v[20:23], v[186:189], v[246:249], v[20:23]
	v_mfma_f32_16x16x32_bf16 v[16:19], v[190:193], v[246:249], v[16:19]
	ds_read_b128 v[242:245], v198 offset:2368
	s_waitcnt lgkmcnt(4)
	v_mfma_f32_16x16x32_bf16 v[12:15], v[178:181], v[250:253], v[12:15]
	ds_read_b128 v[178:181], v199 offset:36928
	s_waitcnt vmcnt(1)
; DI f32x4 mfma16(bf16x8 a, bf16x8 b, f32x4 c) { return __builtin_amdgcn_mfma_f32_16x16x32_bf16(a, b, c, 0, 0, 0); }
; template <int MI, int NJ, bool SWAP, class AP, class BP>
; DI void gemm_main(f32x4 (&acc)[MI][NJ], const AP& ap, int a_kstep, const BP& bp, int b_kstep, int nk, bf16_t* smem) {
;     ...
;   auto gload = [&](int kt) {
;     const bf16_t* ab = ap.base + (size_t)kt * a_kstep; const bf16_t* bb = bp.base + (size_t)kt * b_kstep;
; #pragma unroll
;     for (int i = 0; i < CA; ++i) ra[i] = *(const u32x4*)(ab + pa[i]);
; #pragma unroll
;     for (int i = 0; i < CB; ++i) rb[i] = *(const u32x4*)(bb + pb[i]);
;   };
;   auto sstore = [&](int buf) {
;     bf16_t* As = smem + buf * L::STAGE; bf16_t* Bs = As + L::A_ELEMS;
; #pragma unroll
;     for (int i = 0; i < CA; ++i) { const int c = tid + NTHR * i; *(u32x4*)(As + (c >> 3) * LDT + (c & 7) * 8) = oka[i] ? ra[i] : (u32x4){0u, 0u, 0u, 0u}; }
; #pragma unroll
;     for (int i = 0; i < CB; ++i) { const int c = tid + NTHR * i; *(u32x4*)(Bs + (c >> 3) * LDT + (c & 7) * 8) = rb[i]; }
;   };
;   gload(0); sstore(0); gload(nk > 1 ? 1 : 0); __syncthreads();
; #pragma unroll 1
;   for (int kt = 0; kt < nk; ++kt) {
;     const int buf = kt & 1;
;     sstore(buf ^ 1);
;     gload(kt + 2 < nk ? kt + 2 : nk - 1);
;     __builtin_amdgcn_sched_barrier(0);
;     const bf16_t* As = smem + buf * L::STAGE + (wm * 16 * MI + l15) * LDT + quad * 8;
;     const bf16_t* Bs = smem + buf * L::STAGE + L::A_ELEMS + (wn * 16 * NJ + l15) * LDT + quad * 8;
; #pragma unroll
;     for (int ks = 0; ks < 2; ++ks) {
;       if (MI * NJ >= 32 && ks == 1) asm volatile("" ::: "memory");
;       bf16x8 b[NJ];
; #pragma unroll
;       for (int j = 0; j < NJ; ++j) b[j] = *(const bf16x8*)(Bs + j * 16 * LDT + ks * 32);
; #pragma unroll
;       for (int i = 0; i < MI; ++i) {
;         const bf16x8 a = *(const bf16x8*)(As + i * 16 * LDT + ks * 32);
; #pragma unroll
;         for (int j = 0; j < NJ; ++j) acc[i][j] = SWAP ? mfma16(b[j], a, acc[i][j]) : mfma16(a, b[j], acc[i][j]);
;       }
;     }
;     __syncthreads();
;   }
	ds_write_b128 v120, v[136:139] offset:36864
	v_mfma_f32_16x16x32_bf16 v[8:11], v[182:185], v[250:253], v[8:11]
	ds_read_b128 v[182:185], v199 offset:39232
	v_mfma_f32_16x16x32_bf16 v[4:7], v[186:189], v[250:253], v[4:7]
	ds_read_b128 v[186:189], v199 offset:41536
	v_mfma_f32_16x16x32_bf16 v[0:3], v[190:193], v[250:253], v[0:3]
	ds_read_b128 v[190:193], v199 offset:43840
	ds_read_b128 v[246:249], v198 offset:4672
	s_waitcnt lgkmcnt(5)
	v_mfma_f32_16x16x32_bf16 v[156:159], v[178:181], v[194:197], v[156:159]
	s_waitcnt lgkmcnt(3)
	v_mfma_f32_16x16x32_bf16 v[152:155], v[182:185], v[194:197], v[152:155]
	s_waitcnt vmcnt(0)
	ds_write_b128 v116, v[140:143] offset:36864
	s_waitcnt lgkmcnt(3)
	v_mfma_f32_16x16x32_bf16 v[148:151], v[186:189], v[194:197], v[148:151]
	s_waitcnt lgkmcnt(2)
	v_mfma_f32_16x16x32_bf16 v[144:147], v[190:193], v[194:197], v[144:147]
	v_lshl_add_u64 v[112:113], s[38:39], 0, v[162:163]
	global_load_dwordx4 v[124:127], v[112:113], off
	ds_read_b128 v[250:253], v198 offset:6976
	v_mfma_f32_16x16x32_bf16 v[108:111], v[178:181], v[242:245], v[108:111]
	v_mfma_f32_16x16x32_bf16 v[104:107], v[182:185], v[242:245], v[104:107]
	v_lshl_add_u64 v[112:113], s[38:39], 0, v[164:165]
	global_load_dwordx4 v[120:123], v[112:113], off
	v_mfma_f32_16x16x32_bf16 v[100:103], v[186:189], v[242:245], v[100:103]
	v_mfma_f32_16x16x32_bf16 v[96:99], v[190:193], v[242:245], v[96:99]
	ds_read_b128 v[194:197], v198 offset:9280
	s_waitcnt lgkmcnt(3)
	v_mfma_f32_16x16x32_bf16 v[92:95], v[178:181], v[246:249], v[92:95]
	v_lshl_add_u64 v[112:113], s[38:39], 0, v[166:167]
	global_load_dwordx4 v[116:119], v[112:113], off
	v_mfma_f32_16x16x32_bf16 v[88:91], v[182:185], v[246:249], v[88:91]
	v_mfma_f32_16x16x32_bf16 v[84:87], v[186:189], v[246:249], v[84:87]
	v_lshl_add_u64 v[112:113], s[38:39], 0, v[168:169]
	s_add_u32 s38, s2, s40
	s_addc_u32 s39, s3, 0
	v_lshl_add_u64 v[128:129], s[38:39], 0, v[162:163]
	v_lshl_add_u64 v[132:133], s[38:39], 0, v[164:165]
	v_lshl_add_u64 v[136:137], s[38:39], 0, v[166:167]
	v_lshl_add_u64 v[140:141], s[38:39], 0, v[168:169]
	global_load_dwordx4 v[112:115], v[112:113], off
	v_mfma_f32_16x16x32_bf16 v[80:83], v[190:193], v[246:249], v[80:83]
	ds_read_b128 v[242:245], v198 offset:11584
	s_waitcnt lgkmcnt(2)
	v_mfma_f32_16x16x32_bf16 v[76:79], v[178:181], v[250:253], v[76:79]
	v_mfma_f32_16x16x32_bf16 v[72:75], v[182:185], v[250:253], v[72:75]
	s_nop 0
	global_load_dwordx4 v[128:131], v[128:129], off
	v_mfma_f32_16x16x32_bf16 v[68:71], v[186:189], v[250:253], v[68:71]
	v_mfma_f32_16x16x32_bf16 v[64:67], v[190:193], v[250:253], v[64:67]
	s_nop 0
	global_load_dwordx4 v[132:135], v[132:133], off
	ds_read_b128 v[246:249], v198 offset:13888
	s_waitcnt lgkmcnt(2)
	v_mfma_f32_16x16x32_bf16 v[60:63], v[178:181], v[194:197], v[60:63]
	v_mfma_f32_16x16x32_bf16 v[56:59], v[182:185], v[194:197], v[56:59]
	v_mfma_f32_16x16x32_bf16 v[52:55], v[186:189], v[194:197], v[52:55]
	s_nop 0
	global_load_dwordx4 v[136:139], v[136:137], off
	v_mfma_f32_16x16x32_bf16 v[48:51], v[190:193], v[194:197], v[48:51]
	ds_read_b128 v[250:253], v198 offset:16192
	s_waitcnt lgkmcnt(2)
	v_mfma_f32_16x16x32_bf16 v[44:47], v[178:181], v[242:245], v[44:47]
	s_nop 0
	global_load_dwordx4 v[140:143], v[140:141], off
	v_mfma_f32_16x16x32_bf16 v[40:43], v[182:185], v[242:245], v[40:43]
	v_mfma_f32_16x16x32_bf16 v[36:39], v[186:189], v[242:245], v[36:39]
	v_mfma_f32_16x16x32_bf16 v[32:35], v[190:193], v[242:245], v[32:35]
	s_add_i32 s33, s33, 1
	s_and_b32 s98, s33, 1
	s_mul_i32 s98, s98, 0x12000
	v_add3_u32 v198, s98, v176, v177
	v_add3_u32 v199, s98, v171, v177
	s_cmp_lg_u32 s33, 4
	s_waitcnt lgkmcnt(0)
	s_barrier
	s_cbranch_scc1 .Lgm11_top

; DI f32x4 mfma16(bf16x8 a, bf16x8 b, f32x4 c) { return __builtin_amdgcn_mfma_f32_16x16x32_bf16(a, b, c, 0, 0, 0); }
; template <int MI, int NJ, bool SWAP, class AP, class BP>
; DI void gemm_main(f32x4 (&acc)[MI][NJ], const AP& ap, int a_kstep, const BP& bp, int b_kstep, int nk, bf16_t* smem) {
;     ...
;   for (int kt = 0; kt < nk; ++kt) {
;     const int buf = kt & 1;
;     sstore(buf ^ 1);
;     gload(kt + 2 < nk ? kt + 2 : nk - 1);
;     __builtin_amdgcn_sched_barrier(0);
;     const bf16_t* As = smem + buf * L::STAGE + (wm * 16 * MI + l15) * LDT + quad * 8;
;     const bf16_t* Bs = smem + buf * L::STAGE + L::A_ELEMS + (wn * 16 * NJ + l15) * LDT + quad * 8;
; #pragma unroll
;     for (int ks = 0; ks < 2; ++ks) {
;       if (MI * NJ >= 32 && ks == 1) asm volatile("" ::: "memory");
;       bf16x8 b[NJ];
; #pragma unroll
;       for (int j = 0; j < NJ; ++j) b[j] = *(const bf16x8*)(Bs + j * 16 * LDT + ks * 32);
; #pragma unroll
;       for (int i = 0; i < MI; ++i) {
;         const bf16x8 a = *(const bf16x8*)(As + i * 16 * LDT + ks * 32);
; #pragma unroll
;         for (int j = 0; j < NJ; ++j) acc[i][j] = SWAP ? mfma16(b[j], a, acc[i][j]) : mfma16(a, b[j], acc[i][j]);
;       }
;     }
;     __syncthreads();
;   }
.LBB0_1434:
	s_and_b32 s98, s8, 1
	s_mul_i32 s98, s98, 0x12000
	v_add3_u32 v198, s98, v176, v177
	v_add3_u32 v199, s98, v171, v177
	ds_read_b128 v[194:197], v198
	ds_read_b128 v[242:245], v198 offset:2304
	ds_read_b128 v[178:181], v199 offset:36864
	ds_read_b128 v[182:185], v199 offset:39168
	ds_read_b128 v[186:189], v199 offset:41472
	ds_read_b128 v[190:193], v199 offset:43776
	s_branch .Lgm12_main
.Lgm12_top:
	ds_read_b128 v[194:197], v198
	ds_read_b128 v[242:245], v198 offset:2304
	v_mfma_f32_16x16x32_bf16 v[28:31], v[246:249], v[178:181], v[28:31]
	v_mfma_f32_16x16x32_bf16 v[12:15], v[250:253], v[178:181], v[12:15]
	ds_read_b128 v[178:181], v199 offset:36864
	v_mfma_f32_16x16x32_bf16 v[24:27], v[246:249], v[182:185], v[24:27]
	v_mfma_f32_16x16x32_bf16 v[8:11], v[250:253], v[182:185], v[8:11]
	ds_read_b128 v[182:185], v199 offset:39168
	v_mfma_f32_16x16x32_bf16 v[20:23], v[246:249], v[186:189], v[20:23]
	v_mfma_f32_16x16x32_bf16 v[4:7], v[250:253], v[186:189], v[4:7]
	ds_read_b128 v[186:189], v199 offset:41472
	v_mfma_f32_16x16x32_bf16 v[16:19], v[246:249], v[190:193], v[16:19]
	v_mfma_f32_16x16x32_bf16 v[0:3], v[250:253], v[190:193], v[0:3]
	ds_read_b128 v[190:193], v199 offset:43776
.Lgm12_main:
	ds_read_b128 v[246:249], v198 offset:4608
	s_waitcnt lgkmcnt(4)
	v_mfma_f32_16x16x32_bf16 v[124:127], v[194:197], v[178:181], v[124:127]
	s_waitcnt lgkmcnt(3)
	v_mfma_f32_16x16x32_bf16 v[120:123], v[194:197], v[182:185], v[120:123]
	s_waitcnt lgkmcnt(2)
	v_mfma_f32_16x16x32_bf16 v[116:119], v[194:197], v[186:189], v[116:119]
	s_waitcnt lgkmcnt(1)
	v_mfma_f32_16x16x32_bf16 v[112:115], v[194:197], v[190:193], v[112:115]
	s_and_b32 s17, s8, 1
	s_xor_b32 s33, s17, 1
	s_mul_i32 s33, s33, 0x12000
	v_lshlrev_b32_e32 v254, 1, v160
	v_add3_u32 v254, s33, v254, v172
	s_waitcnt vmcnt(7)
	ds_write_b128 v254, v[140:143]
	ds_read_b128 v[250:253], v198 offset:6912
	v_mfma_f32_16x16x32_bf16 v[108:111], v[242:245], v[178:181], v[108:111]
	v_mfma_f32_16x16x32_bf16 v[104:107], v[242:245], v[182:185], v[104:107]
	v_mfma_f32_16x16x32_bf16 v[100:103], v[242:245], v[186:189], v[100:103]
	v_mfma_f32_16x16x32_bf16 v[96:99], v[242:245], v[190:193], v[96:99]
	v_lshlrev_b32_e32 v140, 1, v173
	v_add3_u32 v140, s33, v140, v172
	s_waitcnt vmcnt(6)
	ds_write_b128 v140, v[136:139]
	ds_read_b128 v[194:197], v198 offset:9216
	s_waitcnt lgkmcnt(4)
	v_mfma_f32_16x16x32_bf16 v[92:95], v[246:249], v[178:181], v[92:95]
	v_mfma_f32_16x16x32_bf16 v[88:91], v[246:249], v[182:185], v[88:91]
	v_mfma_f32_16x16x32_bf16 v[84:87], v[246:249], v[186:189], v[84:87]
	v_mfma_f32_16x16x32_bf16 v[80:83], v[246:249], v[190:193], v[80:83]
	ds_read_b128 v[242:245], v198 offset:11520
	s_waitcnt lgkmcnt(3)
	v_mfma_f32_16x16x32_bf16 v[76:79], v[250:253], v[178:181], v[76:79]
	v_lshlrev_b32_e32 v136, 1, v174
	v_add3_u32 v136, s33, v136, v172
	s_waitcnt vmcnt(5)
	ds_write_b128 v136, v[132:135]
	v_mfma_f32_16x16x32_bf16 v[72:75], v[250:253], v[182:185], v[72:75]
	v_mfma_f32_16x16x32_bf16 v[68:71], v[250:253], v[186:189], v[68:71]
	v_mfma_f32_16x16x32_bf16 v[64:67], v[250:253], v[190:193], v[64:67]
	ds_read_b128 v[246:249], v198 offset:13824
	s_waitcnt lgkmcnt(3)
	v_mfma_f32_16x16x32_bf16 v[60:63], v[194:197], v[178:181], v[60:63]
	v_lshlrev_b32_e32 v132, 1, v175
	s_cmp_eq_u32 s8, 0
	v_add3_u32 v132, s33, v132, v172
	s_cselect_b32 s33, s31, 0x180
	s_add_u32 s38, s0, s33
	s_addc_u32 s39, s1, 0
	s_waitcnt vmcnt(4)
	ds_write_b128 v132, v[128:131]
	v_mfma_f32_16x16x32_bf16 v[56:59], v[194:197], v[182:185], v[56:59]
	v_mfma_f32_16x16x32_bf16 v[52:55], v[194:197], v[186:189], v[52:55]
	v_mfma_f32_16x16x32_bf16 v[48:51], v[194:197], v[190:193], v[48:51]
	ds_read_b128 v[250:253], v198 offset:16128
	s_waitcnt lgkmcnt(4)
	v_mfma_f32_16x16x32_bf16 v[44:47], v[242:245], v[178:181], v[44:47]
	s_waitcnt vmcnt(3)
	ds_write_b128 v254, v[144:147] offset:36864
	v_mfma_f32_16x16x32_bf16 v[40:43], v[242:245], v[182:185], v[40:43]
	v_mfma_f32_16x16x32_bf16 v[36:39], v[242:245], v[186:189], v[36:39]
	v_mfma_f32_16x16x32_bf16 v[32:35], v[242:245], v[190:193], v[32:35]
	ds_read_b128 v[194:197], v198 offset:64
	s_waitcnt lgkmcnt(4)
	v_mfma_f32_16x16x32_bf16 v[28:31], v[246:249], v[178:181], v[28:31]
	s_waitcnt vmcnt(2)
; DI f32x4 mfma16(bf16x8 a, bf16x8 b, f32x4 c) { return __builtin_amdgcn_mfma_f32_16x16x32_bf16(a, b, c, 0, 0, 0); }
; template <int MI, int NJ, bool SWAP, class AP, class BP>
; DI void gemm_main(f32x4 (&acc)[MI][NJ], const AP& ap, int a_kstep, const BP& bp, int b_kstep, int nk, bf16_t* smem) {
;     ...
;   auto gload = [&](int kt) {
;     const bf16_t* ab = ap.base + (size_t)kt * a_kstep; const bf16_t* bb = bp.base + (size_t)kt * b_kstep;
; #pragma unroll
;     for (int i = 0; i < CA; ++i) ra[i] = *(const u32x4*)(ab + pa[i]);
; #pragma unroll
;     for (int i = 0; i < CB; ++i) rb[i] = *(const u32x4*)(bb + pb[i]);
;   };
;   auto sstore = [&](int buf) {
;     bf16_t* As = smem + buf * L::STAGE; bf16_t* Bs = As + L::A_ELEMS;
; #pragma unroll
;     for (int i = 0; i < CA; ++i) { const int c = tid + NTHR * i; *(u32x4*)(As + (c >> 3) * LDT + (c & 7) * 8) = oka[i] ? ra[i] : (u32x4){0u, 0u, 0u, 0u}; }
; #pragma unroll
;     for (int i = 0; i < CB; ++i) { const int c = tid + NTHR * i; *(u32x4*)(Bs + (c >> 3) * LDT + (c & 7) * 8) = rb[i]; }
;   };
;   gload(0); sstore(0); gload(nk > 1 ? 1 : 0); __syncthreads();
; #pragma unroll 1
;   for (int kt = 0; kt < nk; ++kt) {
;     const int buf = kt & 1;
;     sstore(buf ^ 1);
;     gload(kt + 2 < nk ? kt + 2 : nk - 1);
;     __builtin_amdgcn_sched_barrier(0);
;     const bf16_t* As = smem + buf * L::STAGE + (wm * 16 * MI + l15) * LDT + quad * 8;
;     const bf16_t* Bs = smem + buf * L::STAGE + L::A_ELEMS + (wn * 16 * NJ + l15) * LDT + quad * 8;
; #pragma unroll
;     for (int ks = 0; ks < 2; ++ks) {
;       if (MI * NJ >= 32 && ks == 1) asm volatile("" ::: "memory");
;       bf16x8 b[NJ];
; #pragma unroll
;       for (int j = 0; j < NJ; ++j) b[j] = *(const bf16x8*)(Bs + j * 16 * LDT + ks * 32);
; #pragma unroll
;       for (int i = 0; i < MI; ++i) {
;         const bf16x8 a = *(const bf16x8*)(As + i * 16 * LDT + ks * 32);
; #pragma unroll
;         for (int j = 0; j < NJ; ++j) acc[i][j] = SWAP ? mfma16(b[j], a, acc[i][j]) : mfma16(a, b[j], acc[i][j]);
;       }
;     }
;     __syncthreads();
;   }
	ds_write_b128 v140, v[148:151] offset:36864
	v_mfma_f32_16x16x32_bf16 v[24:27], v[246:249], v[182:185], v[24:27]
	v_mfma_f32_16x16x32_bf16 v[20:23], v[246:249], v[186:189], v[20:23]
	v_mfma_f32_16x16x32_bf16 v[16:19], v[246:249], v[190:193], v[16:19]
	ds_read_b128 v[242:245], v198 offset:2368
	s_waitcnt lgkmcnt(4)
	v_mfma_f32_16x16x32_bf16 v[12:15], v[250:253], v[178:181], v[12:15]
	ds_read_b128 v[178:181], v199 offset:36928
	s_waitcnt vmcnt(1)
	ds_write_b128 v136, v[152:155] offset:36864
	v_mfma_f32_16x16x32_bf16 v[8:11], v[250:253], v[182:185], v[8:11]
	ds_read_b128 v[182:185], v199 offset:39232
	v_mfma_f32_16x16x32_bf16 v[4:7], v[250:253], v[186:189], v[4:7]
	ds_read_b128 v[186:189], v199 offset:41536
	v_mfma_f32_16x16x32_bf16 v[0:3], v[250:253], v[190:193], v[0:3]
	ds_read_b128 v[190:193], v199 offset:43840
	ds_read_b128 v[246:249], v198 offset:4672
	s_waitcnt lgkmcnt(5)
	v_mfma_f32_16x16x32_bf16 v[124:127], v[194:197], v[178:181], v[124:127]
	s_waitcnt lgkmcnt(3)
	v_mfma_f32_16x16x32_bf16 v[120:123], v[194:197], v[182:185], v[120:123]
	s_waitcnt vmcnt(0)
	ds_write_b128 v132, v[156:159] offset:36864
	s_waitcnt lgkmcnt(3)
	v_mfma_f32_16x16x32_bf16 v[116:119], v[194:197], v[186:189], v[116:119]
	s_waitcnt lgkmcnt(2)
	v_mfma_f32_16x16x32_bf16 v[112:115], v[194:197], v[190:193], v[112:115]
	v_lshl_add_u64 v[128:129], s[38:39], 0, v[162:163]
	global_load_dwordx4 v[140:143], v[128:129], off
	ds_read_b128 v[250:253], v198 offset:6976
	v_mfma_f32_16x16x32_bf16 v[108:111], v[242:245], v[178:181], v[108:111]
	v_mfma_f32_16x16x32_bf16 v[104:107], v[242:245], v[182:185], v[104:107]
	v_lshl_add_u64 v[128:129], s[38:39], 0, v[164:165]
	global_load_dwordx4 v[136:139], v[128:129], off
	v_mfma_f32_16x16x32_bf16 v[100:103], v[242:245], v[186:189], v[100:103]
	v_mfma_f32_16x16x32_bf16 v[96:99], v[242:245], v[190:193], v[96:99]
	ds_read_b128 v[194:197], v198 offset:9280
	s_waitcnt lgkmcnt(3)
	v_mfma_f32_16x16x32_bf16 v[92:95], v[246:249], v[178:181], v[92:95]
	v_lshl_add_u64 v[128:129], s[38:39], 0, v[166:167]
	global_load_dwordx4 v[132:135], v[128:129], off
	v_mfma_f32_16x16x32_bf16 v[88:91], v[246:249], v[182:185], v[88:91]
	v_mfma_f32_16x16x32_bf16 v[84:87], v[246:249], v[186:189], v[84:87]
	v_lshl_add_u64 v[128:129], s[38:39], 0, v[168:169]
	s_add_u32 s38, s2, s33
	s_addc_u32 s39, s3, 0
	v_lshl_add_u64 v[144:145], s[38:39], 0, v[162:163]
	v_lshl_add_u64 v[148:149], s[38:39], 0, v[164:165]
	v_lshl_add_u64 v[152:153], s[38:39], 0, v[166:167]
	v_lshl_add_u64 v[156:157], s[38:39], 0, v[168:169]
	global_load_dwordx4 v[128:131], v[128:129], off
	v_mfma_f32_16x16x32_bf16 v[80:83], v[246:249], v[190:193], v[80:83]
	ds_read_b128 v[242:245], v198 offset:11584
	s_waitcnt lgkmcnt(2)
	v_mfma_f32_16x16x32_bf16 v[76:79], v[250:253], v[178:181], v[76:79]
	v_mfma_f32_16x16x32_bf16 v[72:75], v[250:253], v[182:185], v[72:75]
	s_nop 0
	global_load_dwordx4 v[144:147], v[144:145], off
	v_mfma_f32_16x16x32_bf16 v[68:71], v[250:253], v[186:189], v[68:71]
	v_mfma_f32_16x16x32_bf16 v[64:67], v[250:253], v[190:193], v[64:67]
	s_nop 0
	global_load_dwordx4 v[148:151], v[148:149], off
	ds_read_b128 v[246:249], v198 offset:13888
	s_waitcnt lgkmcnt(2)
	v_mfma_f32_16x16x32_bf16 v[60:63], v[194:197], v[178:181], v[60:63]
	v_mfma_f32_16x16x32_bf16 v[56:59], v[194:197], v[182:185], v[56:59]
	v_mfma_f32_16x16x32_bf16 v[52:55], v[194:197], v[186:189], v[52:55]
	s_nop 0
	global_load_dwordx4 v[152:155], v[152:153], off
	v_mfma_f32_16x16x32_bf16 v[48:51], v[194:197], v[190:193], v[48:51]
	ds_read_b128 v[250:253], v198 offset:16192
	s_waitcnt lgkmcnt(2)
	v_mfma_f32_16x16x32_bf16 v[44:47], v[242:245], v[178:181], v[44:47]
	s_nop 0
	global_load_dwordx4 v[156:159], v[156:157], off
	v_mfma_f32_16x16x32_bf16 v[40:43], v[242:245], v[182:185], v[40:43]
	v_mfma_f32_16x16x32_bf16 v[36:39], v[242:245], v[186:189], v[36:39]
	v_mfma_f32_16x16x32_bf16 v[32:35], v[242:245], v[190:193], v[32:35]
	s_add_i32 s8, s8, 1
	s_and_b32 s98, s8, 1
	s_mul_i32 s98, s98, 0x12000
	v_add3_u32 v198, s98, v176, v177
	v_add3_u32 v199, s98, v171, v177
	s_cmp_lg_u32 s8, 4
	s_waitcnt lgkmcnt(0)
	s_barrier
	s_cbranch_scc1 .Lgm12_top

; DI void merge_tile(const Params& p, int layer, int tm, int tn, bf16_t* smem) {
;     ...
;     for (int kt = 0; kt < nk; ++kt) {
;       sstore(buf ^ 1);
;       gload_next();
;       __builtin_amdgcn_sched_barrier(0);
;       const bf16_t* As = smem + buf * L::STAGE + (wm * 128 + l15) * LDT + quad * 8;
;       const bf16_t* Bs = smem + buf * L::STAGE + L::A_ELEMS + (wn * 32 + l15) * LDT + quad * 8;
; #pragma unroll
;       for (int ks = 0; ks < 2; ++ks) {
;         if (ks == 1) asm volatile("" ::: "memory");
;         bf16x8 b[2];
; #pragma unroll
;         for (int j = 0; j < 2; ++j) b[j] = *(const bf16x8*)(Bs + j * 16 * LDT + ks * 32);
; #pragma unroll
;         for (int i = 0; i < 8; ++i) {
;           const bf16x8 a = *(const bf16x8*)(As + i * 16 * LDT + ks * 32);
.LBB0_1870:
	s_mul_i32 s98, s57, 0xd800
	v_add3_u32 v164, s98, v231, v236
	v_add3_u32 v168, s98, v230, v236
	ds_read_b128 v[156:159], v168
	ds_read_b128 v[170:173], v168 offset:2304
	ds_read_b128 v[174:177], v168 offset:4608
	ds_read_b128 v[178:181], v168 offset:6912
	ds_read_b128 v[152:155], v164 offset:36864
	ds_read_b128 v[160:163], v164 offset:39168
	s_branch .Lmg1_main
.Lmg1_top:
	ds_read_b128 v[156:159], v168
	ds_read_b128 v[170:173], v168 offset:2304
	ds_read_b128 v[174:177], v168 offset:4608
	ds_read_b128 v[178:181], v168 offset:6912
	ds_read_b128 v[152:155], v164 offset:36864
	ds_read_b128 v[160:163], v164 offset:39168
	v_mfma_f32_16x16x32_bf16 v[116:119], v[198:201], v[182:185], v[116:119]
	v_mfma_f32_16x16x32_bf16 v[108:111], v[198:201], v[186:189], v[108:111]
	v_mfma_f32_16x16x32_bf16 v[100:103], v[198:201], v[190:193], v[100:103]
	v_mfma_f32_16x16x32_bf16 v[92:95], v[198:201], v[194:197], v[92:95]
	v_mfma_f32_16x16x32_bf16 v[112:115], v[202:205], v[182:185], v[112:115]
	v_mfma_f32_16x16x32_bf16 v[104:107], v[202:205], v[186:189], v[104:107]
	v_mfma_f32_16x16x32_bf16 v[96:99], v[202:205], v[190:193], v[96:99]
	v_mfma_f32_16x16x32_bf16 v[88:91], v[202:205], v[194:197], v[88:91]

; DI f32x4 mfma16(bf16x8 a, bf16x8 b, f32x4 c) { return __builtin_amdgcn_mfma_f32_16x16x32_bf16(a, b, c, 0, 0, 0); }
; DI void merge_tile(const Params& p, int layer, int tm, int tn, bf16_t* smem) {
;     ...
;     for (int kt = 0; kt < nk; ++kt) {
;       sstore(buf ^ 1);
;       gload_next();
;       __builtin_amdgcn_sched_barrier(0);
;       const bf16_t* As = smem + buf * L::STAGE + (wm * 128 + l15) * LDT + quad * 8;
;       const bf16_t* Bs = smem + buf * L::STAGE + L::A_ELEMS + (wn * 32 + l15) * LDT + quad * 8;
; #pragma unroll
;       for (int ks = 0; ks < 2; ++ks) {
;         if (ks == 1) asm volatile("" ::: "memory");
;         bf16x8 b[2];
; #pragma unroll
;         for (int j = 0; j < 2; ++j) b[j] = *(const bf16x8*)(Bs + j * 16 * LDT + ks * 32);
; #pragma unroll
;         for (int i = 0; i < 8; ++i) {
;           const bf16x8 a = *(const bf16x8*)(As + i * 16 * LDT + ks * 32);
; #pragma unroll
;           for (int j = 0; j < 2; ++j) acc[i][j] = mfma16(b[j], a, acc[i][j]);
;         }
;       }
;       __syncthreads();
;       buf ^= 1;
;     }
.LBB0_1879:
	s_add_i32 s56, s56, -1
	s_mov_b32 s57, s55
	s_mul_i32 s98, s57, 0xd800
	v_add3_u32 v164, s98, v231, v236
	v_add3_u32 v168, s98, v230, v236
	s_cmp_eq_u32 s56, 0
	s_waitcnt lgkmcnt(0)
	s_barrier
	s_cbranch_scc0 .Lmg1_top

; DI f32x4 mfma16(bf16x8 a, bf16x8 b, f32x4 c) { return __builtin_amdgcn_mfma_f32_16x16x32_bf16(a, b, c, 0, 0, 0); }
; template <int MI, int NJ, bool SWAP, class AP, class BP>
; DI void gemm_main(f32x4 (&acc)[MI][NJ], const AP& ap, int a_kstep, const BP& bp, int b_kstep, int nk, bf16_t* smem) {
;     ...
;   auto gload = [&](int kt) {
;     const bf16_t* ab = ap.base + (size_t)kt * a_kstep; const bf16_t* bb = bp.base + (size_t)kt * b_kstep;
; #pragma unroll
;     for (int i = 0; i < CA; ++i) ra[i] = *(const u32x4*)(ab + pa[i]);
; #pragma unroll
;     for (int i = 0; i < CB; ++i) rb[i] = *(const u32x4*)(bb + pb[i]);
;   };
;   auto sstore = [&](int buf) {
;     bf16_t* As = smem + buf * L::STAGE; bf16_t* Bs = As + L::A_ELEMS;
; #pragma unroll
;     for (int i = 0; i < CA; ++i) { const int c = tid + NTHR * i; *(u32x4*)(As + (c >> 3) * LDT + (c & 7) * 8) = oka[i] ? ra[i] : (u32x4){0u, 0u, 0u, 0u}; }
; #pragma unroll
;     for (int i = 0; i < CB; ++i) { const int c = tid + NTHR * i; *(u32x4*)(Bs + (c >> 3) * LDT + (c & 7) * 8) = rb[i]; }
;   };
;   gload(0); sstore(0); gload(nk > 1 ? 1 : 0); __syncthreads();
; #pragma unroll 1
;   for (int kt = 0; kt < nk; ++kt) {
;     const int buf = kt & 1;
;     sstore(buf ^ 1);
;     gload(kt + 2 < nk ? kt + 2 : nk - 1);
;     __builtin_amdgcn_sched_barrier(0);
;     const bf16_t* As = smem + buf * L::STAGE + (wm * 16 * MI + l15) * LDT + quad * 8;
;     const bf16_t* Bs = smem + buf * L::STAGE + L::A_ELEMS + (wn * 16 * NJ + l15) * LDT + quad * 8;
; #pragma unroll
;     for (int ks = 0; ks < 2; ++ks) {
;       if (MI * NJ >= 32 && ks == 1) asm volatile("" ::: "memory");
;       bf16x8 b[NJ];
; #pragma unroll
;       for (int j = 0; j < NJ; ++j) b[j] = *(const bf16x8*)(Bs + j * 16 * LDT + ks * 32);
; #pragma unroll
;       for (int i = 0; i < MI; ++i) {
;         const bf16x8 a = *(const bf16x8*)(As + i * 16 * LDT + ks * 32);
; #pragma unroll
;         for (int j = 0; j < NJ; ++j) acc[i][j] = SWAP ? mfma16(b[j], a, acc[i][j]) : mfma16(a, b[j], acc[i][j]);
.Lgm13_main:
	ds_read_b128 v[242:245], v177 offset:4608
	s_waitcnt lgkmcnt(4)
	v_mfma_f32_16x16x32_bf16 v[156:159], v[178:181], v[194:197], v[156:159]
	s_waitcnt lgkmcnt(3)
	v_mfma_f32_16x16x32_bf16 v[152:155], v[182:185], v[194:197], v[152:155]
	s_waitcnt lgkmcnt(2)
	v_mfma_f32_16x16x32_bf16 v[148:151], v[186:189], v[194:197], v[148:151]
	s_and_b32 s15, s1, 1
	s_min_u32 s16, s1, 13
	s_xor_b32 s17, s15, 1
	s_mul_i32 s17, s17, 0x12000
	v_add3_u32 v250, s17, v172, v170
	s_waitcnt vmcnt(7)
	ds_write_b128 v250, v[112:115]
	s_waitcnt lgkmcnt(2)
	v_mfma_f32_16x16x32_bf16 v[144:147], v[190:193], v[194:197], v[144:147]
	ds_read_b128 v[246:249], v177 offset:6912
	v_mfma_f32_16x16x32_bf16 v[108:111], v[178:181], v[198:201], v[108:111]
	s_lshl_b32 s26, s16, 7
	s_add_u32 s16, s2, s26
	v_add3_u32 v251, s17, v174, v170
	v_add3_u32 v252, s17, v175, v170
	v_add3_u32 v253, s17, v176, v170
	s_addc_u32 s17, s3, 0
	v_lshl_add_u64 v[112:113], s[16:17], 0, v[162:163]
	s_nop 0
	global_load_dwordx4 v[112:115], v[112:113], off offset:256
	v_mfma_f32_16x16x32_bf16 v[104:107], v[182:185], v[198:201], v[104:107]
	v_mfma_f32_16x16x32_bf16 v[100:103], v[186:189], v[198:201], v[100:103]
	v_mfma_f32_16x16x32_bf16 v[96:99], v[190:193], v[198:201], v[96:99]
	ds_read_b128 v[194:197], v177 offset:9216
	s_waitcnt lgkmcnt(3)
	v_mfma_f32_16x16x32_bf16 v[92:95], v[178:181], v[242:245], v[92:95]
	s_waitcnt vmcnt(7)
	ds_write_b128 v251, v[116:119]
	v_mfma_f32_16x16x32_bf16 v[88:91], v[182:185], v[242:245], v[88:91]
	v_mfma_f32_16x16x32_bf16 v[84:87], v[186:189], v[242:245], v[84:87]
	v_lshl_add_u64 v[116:117], s[16:17], 0, v[164:165]
	s_nop 0
	global_load_dwordx4 v[116:119], v[116:117], off offset:256
	v_mfma_f32_16x16x32_bf16 v[80:83], v[190:193], v[242:245], v[80:83]
	ds_read_b128 v[198:201], v177 offset:11520
	s_waitcnt lgkmcnt(3)
	v_mfma_f32_16x16x32_bf16 v[76:79], v[178:181], v[246:249], v[76:79]
	v_mfma_f32_16x16x32_bf16 v[72:75], v[182:185], v[246:249], v[72:75]
	v_mfma_f32_16x16x32_bf16 v[68:71], v[186:189], v[246:249], v[68:71]
	s_waitcnt vmcnt(7)
	ds_write_b128 v252, v[120:123]
	v_mfma_f32_16x16x32_bf16 v[64:67], v[190:193], v[246:249], v[64:67]
	ds_read_b128 v[242:245], v177 offset:13824
	s_waitcnt lgkmcnt(4)
	v_mfma_f32_16x16x32_bf16 v[60:63], v[178:181], v[194:197], v[60:63]
	v_lshl_add_u64 v[120:121], s[16:17], 0, v[166:167]
	s_nop 0
	global_load_dwordx4 v[120:123], v[120:121], off offset:256
	v_mfma_f32_16x16x32_bf16 v[56:59], v[182:185], v[194:197], v[56:59]
	v_mfma_f32_16x16x32_bf16 v[52:55], v[186:189], v[194:197], v[52:55]
	v_mfma_f32_16x16x32_bf16 v[48:51], v[190:193], v[194:197], v[48:51]
	ds_read_b128 v[246:249], v177 offset:16128
	s_waitcnt lgkmcnt(3)
	v_mfma_f32_16x16x32_bf16 v[44:47], v[178:181], v[198:201], v[44:47]
	s_waitcnt vmcnt(7)
	ds_write_b128 v253, v[124:127]
	v_mfma_f32_16x16x32_bf16 v[40:43], v[182:185], v[198:201], v[40:43]
	v_mfma_f32_16x16x32_bf16 v[36:39], v[186:189], v[198:201], v[36:39]
	v_lshl_add_u64 v[124:125], s[16:17], 0, v[168:169]
	s_nop 0
	global_load_dwordx4 v[124:127], v[124:125], off offset:256
	v_mfma_f32_16x16x32_bf16 v[32:35], v[190:193], v[198:201], v[32:35]
	ds_read_b128 v[194:197], v177 offset:64
	s_waitcnt lgkmcnt(3)
	v_mfma_f32_16x16x32_bf16 v[28:31], v[178:181], v[242:245], v[28:31]
	v_mfma_f32_16x16x32_bf16 v[24:27], v[182:185], v[242:245], v[24:27]
	v_mfma_f32_16x16x32_bf16 v[20:23], v[186:189], v[242:245], v[20:23]
	s_waitcnt vmcnt(7)
	ds_write_b128 v250, v[128:131] offset:36864
	v_mfma_f32_16x16x32_bf16 v[16:19], v[190:193], v[242:245], v[16:19]
	ds_read_b128 v[198:201], v177 offset:2368
	s_waitcnt lgkmcnt(4)
; DI f32x4 mfma16(bf16x8 a, bf16x8 b, f32x4 c) { return __builtin_amdgcn_mfma_f32_16x16x32_bf16(a, b, c, 0, 0, 0); }
; template <int MI, int NJ, bool SWAP, class AP, class BP>
; DI void gemm_main(f32x4 (&acc)[MI][NJ], const AP& ap, int a_kstep, const BP& bp, int b_kstep, int nk, bf16_t* smem) {
;     ...
;   for (int kt = 0; kt < nk; ++kt) {
;     const int buf = kt & 1;
;     sstore(buf ^ 1);
;     gload(kt + 2 < nk ? kt + 2 : nk - 1);
;     __builtin_amdgcn_sched_barrier(0);
;     const bf16_t* As = smem + buf * L::STAGE + (wm * 16 * MI + l15) * LDT + quad * 8;
;     const bf16_t* Bs = smem + buf * L::STAGE + L::A_ELEMS + (wn * 16 * NJ + l15) * LDT + quad * 8;
; #pragma unroll
;     for (int ks = 0; ks < 2; ++ks) {
;       if (MI * NJ >= 32 && ks == 1) asm volatile("" ::: "memory");
;       bf16x8 b[NJ];
; #pragma unroll
;       for (int j = 0; j < NJ; ++j) b[j] = *(const bf16x8*)(Bs + j * 16 * LDT + ks * 32);
; #pragma unroll
;       for (int i = 0; i < MI; ++i) {
;         const bf16x8 a = *(const bf16x8*)(As + i * 16 * LDT + ks * 32);
; #pragma unroll
;         for (int j = 0; j < NJ; ++j) acc[i][j] = SWAP ? mfma16(b[j], a, acc[i][j]) : mfma16(a, b[j], acc[i][j]);
;       }
;     }
;     __syncthreads();
;   }
	v_mfma_f32_16x16x32_bf16 v[8:11], v[178:181], v[246:249], v[8:11]
	ds_read_b128 v[178:181], v202 offset:36928
	s_add_u32 s16, s12, s26
	s_addc_u32 s17, s13, 0
	v_lshl_add_u64 v[128:129], s[16:17], 0, v[162:163]
	s_nop 0
	global_load_dwordx4 v[128:131], v[128:129], off offset:256
	v_mfma_f32_16x16x32_bf16 v[4:7], v[182:185], v[246:249], v[4:7]
	ds_read_b128 v[182:185], v202 offset:39232
	v_mfma_f32_16x16x32_bf16 v[0:3], v[186:189], v[246:249], v[0:3]
	ds_read_b128 v[186:189], v202 offset:41536
	v_mfma_f32_16x16x32_bf16 v[12:15], v[190:193], v[246:249], v[12:15]
	ds_read_b128 v[190:193], v202 offset:43840
	ds_read_b128 v[242:245], v177 offset:4672
	s_waitcnt lgkmcnt(4)
	v_mfma_f32_16x16x32_bf16 v[156:159], v[178:181], v[194:197], v[156:159]
	s_waitcnt vmcnt(7)
	ds_write_b128 v251, v[132:135] offset:36864
	s_waitcnt lgkmcnt(4)
	v_mfma_f32_16x16x32_bf16 v[152:155], v[182:185], v[194:197], v[152:155]
	s_waitcnt lgkmcnt(3)
	v_mfma_f32_16x16x32_bf16 v[148:151], v[186:189], v[194:197], v[148:151]
	v_lshl_add_u64 v[132:133], s[16:17], 0, v[164:165]
	s_nop 0
	global_load_dwordx4 v[132:135], v[132:133], off offset:256
	s_waitcnt lgkmcnt(2)
	v_mfma_f32_16x16x32_bf16 v[144:147], v[190:193], v[194:197], v[144:147]
	ds_read_b128 v[246:249], v177 offset:6976
	v_mfma_f32_16x16x32_bf16 v[108:111], v[178:181], v[198:201], v[108:111]
	v_mfma_f32_16x16x32_bf16 v[104:107], v[182:185], v[198:201], v[104:107]
	v_mfma_f32_16x16x32_bf16 v[100:103], v[186:189], v[198:201], v[100:103]
	s_waitcnt vmcnt(7)
	ds_write_b128 v252, v[136:139] offset:36864
	v_mfma_f32_16x16x32_bf16 v[96:99], v[190:193], v[198:201], v[96:99]
	ds_read_b128 v[194:197], v177 offset:9280
	s_waitcnt lgkmcnt(4)
	v_mfma_f32_16x16x32_bf16 v[92:95], v[178:181], v[242:245], v[92:95]
	v_lshl_add_u64 v[136:137], s[16:17], 0, v[166:167]
	s_nop 0
	global_load_dwordx4 v[136:139], v[136:137], off offset:256
	v_mfma_f32_16x16x32_bf16 v[88:91], v[182:185], v[242:245], v[88:91]
	v_mfma_f32_16x16x32_bf16 v[84:87], v[186:189], v[242:245], v[84:87]
	v_mfma_f32_16x16x32_bf16 v[80:83], v[190:193], v[242:245], v[80:83]
	ds_read_b128 v[198:201], v177 offset:11584
	s_waitcnt lgkmcnt(3)
	v_mfma_f32_16x16x32_bf16 v[76:79], v[178:181], v[246:249], v[76:79]
	s_waitcnt vmcnt(7)
	ds_write_b128 v253, v[140:143] offset:36864
	v_mfma_f32_16x16x32_bf16 v[72:75], v[182:185], v[246:249], v[72:75]
	v_mfma_f32_16x16x32_bf16 v[68:71], v[186:189], v[246:249], v[68:71]
	v_lshl_add_u64 v[140:141], s[16:17], 0, v[168:169]
	s_nop 0
	global_load_dwordx4 v[140:143], v[140:141], off offset:256
	v_mfma_f32_16x16x32_bf16 v[64:67], v[190:193], v[246:249], v[64:67]
	ds_read_b128 v[242:245], v177 offset:13888
	s_waitcnt lgkmcnt(3)
	v_mfma_f32_16x16x32_bf16 v[60:63], v[178:181], v[194:197], v[60:63]
	v_mfma_f32_16x16x32_bf16 v[56:59], v[182:185], v[194:197], v[56:59]
	v_mfma_f32_16x16x32_bf16 v[52:55], v[186:189], v[194:197], v[52:55]
	v_mfma_f32_16x16x32_bf16 v[48:51], v[190:193], v[194:197], v[48:51]
	ds_read_b128 v[246:249], v177 offset:16192
	s_waitcnt lgkmcnt(3)
	v_mfma_f32_16x16x32_bf16 v[44:47], v[178:181], v[198:201], v[44:47]
	v_mfma_f32_16x16x32_bf16 v[40:43], v[182:185], v[198:201], v[40:43]
	v_mfma_f32_16x16x32_bf16 v[36:39], v[186:189], v[198:201], v[36:39]
	v_mfma_f32_16x16x32_bf16 v[32:35], v[190:193], v[198:201], v[32:35]
	s_add_i32 s1, s1, 1
	s_and_b32 s98, s1, 1
	s_mul_i32 s98, s98, 0x12000
	v_add3_u32 v202, s98, v160, v173
	v_add3_u32 v177, s98, v171, v173
	s_cmp_lg_u32 s1, 16
	s_waitcnt lgkmcnt(0)
	s_barrier
	s_cbranch_scc1 .Lgm13_top

; DI f32x4 mfma16(bf16x8 a, bf16x8 b, f32x4 c) { return __builtin_amdgcn_mfma_f32_16x16x32_bf16(a, b, c, 0, 0, 0); }
; template <int MI, int NJ, bool SWAP, class AP, class BP>
; DI void gemm_main(f32x4 (&acc)[MI][NJ], const AP& ap, int a_kstep, const BP& bp, int b_kstep, int nk, bf16_t* smem) {
;     ...
;   auto gload = [&](int kt) {
;     const bf16_t* ab = ap.base + (size_t)kt * a_kstep; const bf16_t* bb = bp.base + (size_t)kt * b_kstep;
; #pragma unroll
;     for (int i = 0; i < CA; ++i) ra[i] = *(const u32x4*)(ab + pa[i]);
; #pragma unroll
;     for (int i = 0; i < CB; ++i) rb[i] = *(const u32x4*)(bb + pb[i]);
;   };
;   auto sstore = [&](int buf) {
;     bf16_t* As = smem + buf * L::STAGE; bf16_t* Bs = As + L::A_ELEMS;
; #pragma unroll
;     for (int i = 0; i < CA; ++i) { const int c = tid + NTHR * i; *(u32x4*)(As + (c >> 3) * LDT + (c & 7) * 8) = oka[i] ? ra[i] : (u32x4){0u, 0u, 0u, 0u}; }
; #pragma unroll
;     for (int i = 0; i < CB; ++i) { const int c = tid + NTHR * i; *(u32x4*)(Bs + (c >> 3) * LDT + (c & 7) * 8) = rb[i]; }
;   };
;   gload(0); sstore(0); gload(nk > 1 ? 1 : 0); __syncthreads();
; #pragma unroll 1
;   for (int kt = 0; kt < nk; ++kt) {
;     const int buf = kt & 1;
;     sstore(buf ^ 1);
;     gload(kt + 2 < nk ? kt + 2 : nk - 1);
;     __builtin_amdgcn_sched_barrier(0);
;     const bf16_t* As = smem + buf * L::STAGE + (wm * 16 * MI + l15) * LDT + quad * 8;
;     const bf16_t* Bs = smem + buf * L::STAGE + L::A_ELEMS + (wn * 16 * NJ + l15) * LDT + quad * 8;
; #pragma unroll
;     for (int ks = 0; ks < 2; ++ks) {
;       if (MI * NJ >= 32 && ks == 1) asm volatile("" ::: "memory");
;       bf16x8 b[NJ];
; #pragma unroll
;       for (int j = 0; j < NJ; ++j) b[j] = *(const bf16x8*)(Bs + j * 16 * LDT + ks * 32);
; #pragma unroll
;       for (int i = 0; i < MI; ++i) {
;         const bf16x8 a = *(const bf16x8*)(As + i * 16 * LDT + ks * 32);
; #pragma unroll
;         for (int j = 0; j < NJ; ++j) acc[i][j] = SWAP ? mfma16(b[j], a, acc[i][j]) : mfma16(a, b[j], acc[i][j]);
.LBB0_2083:
	s_cmp_eq_u32 s42, 0xfde
	s_cbranch_scc1 .Lgm14r_main
	s_and_b32 s98, s43, 1
	s_mul_i32 s98, s98, 0x12000
	v_add3_u32 v206, s98, v171, v180
	v_add3_u32 v181, s98, v170, v180
	ds_read_b128 v[198:201], v181
	ds_read_b128 v[202:205], v181 offset:2304
	ds_read_b128 v[182:185], v206 offset:36864
	ds_read_b128 v[186:189], v206 offset:39168
	ds_read_b128 v[190:193], v206 offset:41472
	ds_read_b128 v[194:197], v206 offset:43776
	s_branch .Lgm14_main
.Lgm14_top:
	ds_read_b128 v[198:201], v181
	ds_read_b128 v[202:205], v181 offset:2304
	v_mfma_f32_16x16x32_bf16 v[28:31], v[182:185], v[242:245], v[28:31]
	v_mfma_f32_16x16x32_bf16 v[8:11], v[182:185], v[246:249], v[8:11]
	ds_read_b128 v[182:185], v206 offset:36864
	v_mfma_f32_16x16x32_bf16 v[24:27], v[186:189], v[242:245], v[24:27]
	v_mfma_f32_16x16x32_bf16 v[4:7], v[186:189], v[246:249], v[4:7]
	ds_read_b128 v[186:189], v206 offset:39168
	v_mfma_f32_16x16x32_bf16 v[20:23], v[190:193], v[242:245], v[20:23]
	v_mfma_f32_16x16x32_bf16 v[0:3], v[190:193], v[246:249], v[0:3]
	ds_read_b128 v[190:193], v206 offset:41472
	v_mfma_f32_16x16x32_bf16 v[12:15], v[194:197], v[242:245], v[12:15]
	v_mfma_f32_16x16x32_bf16 v[16:19], v[194:197], v[246:249], v[16:19]
	ds_read_b128 v[194:197], v206 offset:43776
.Lgm14_main:
	ds_read_b128 v[242:245], v181 offset:4608
	s_waitcnt lgkmcnt(4)
	v_mfma_f32_16x16x32_bf16 v[156:159], v[182:185], v[198:201], v[156:159]
	s_waitcnt lgkmcnt(3)
	v_mfma_f32_16x16x32_bf16 v[152:155], v[186:189], v[198:201], v[152:155]
	s_waitcnt lgkmcnt(2)
	v_mfma_f32_16x16x32_bf16 v[148:151], v[190:193], v[198:201], v[148:151]
	s_waitcnt vmcnt(7)
	v_cndmask_b32_e32 v143, 0, v143, vcc
	v_cndmask_b32_e32 v142, 0, v142, vcc
	v_cndmask_b32_e32 v141, 0, v141, vcc
	v_cndmask_b32_e32 v140, 0, v140, vcc
	s_and_b32 s46, s43, 1
	s_min_u32 s44, s43, 13
	s_xor_b32 s45, s46, 1
	s_mul_i32 s45, s45, 0x12000
	v_add3_u32 v250, s45, v172, v169
	ds_write_b128 v250, v[140:143]
	s_waitcnt lgkmcnt(2)
	v_mfma_f32_16x16x32_bf16 v[144:147], v[194:197], v[198:201], v[144:147]
	ds_read_b128 v[246:249], v181 offset:6912
	v_mfma_f32_16x16x32_bf16 v[108:111], v[182:185], v[202:205], v[108:111]
	s_lshl_b32 s47, s44, 7
	s_add_u32 s44, s18, s47
	v_add3_u32 v251, s45, v173, v169
	v_add3_u32 v252, s45, v174, v169
	v_add3_u32 v253, s45, v175, v169
	s_addc_u32 s45, s19, 0
	s_nop 0
	global_load_dwordx4 v[140:143], v176, s[44:45] offset:256
	v_mfma_f32_16x16x32_bf16 v[104:107], v[186:189], v[202:205], v[104:107]
	v_mfma_f32_16x16x32_bf16 v[100:103], v[190:193], v[202:205], v[100:103]
	v_mfma_f32_16x16x32_bf16 v[96:99], v[194:197], v[202:205], v[96:99]
	ds_read_b128 v[198:201], v181 offset:9216
	s_waitcnt lgkmcnt(3)
	v_mfma_f32_16x16x32_bf16 v[92:95], v[182:185], v[242:245], v[92:95]
	s_waitcnt vmcnt(7)
	v_cndmask_b32_e64 v131, 0, v131, s[0:1]
	v_cndmask_b32_e64 v130, 0, v130, s[0:1]
	v_cndmask_b32_e64 v129, 0, v129, s[0:1]
	v_cndmask_b32_e64 v128, 0, v128, s[0:1]
	ds_write_b128 v251, v[128:131]
	v_mfma_f32_16x16x32_bf16 v[88:91], v[186:189], v[242:245], v[88:91]
	v_mfma_f32_16x16x32_bf16 v[84:87], v[190:193], v[242:245], v[84:87]
	s_nop 0
	global_load_dwordx4 v[128:131], v177, s[44:45] offset:256
	v_mfma_f32_16x16x32_bf16 v[80:83], v[194:197], v[242:245], v[80:83]
	ds_read_b128 v[202:205], v181 offset:11520
	s_waitcnt lgkmcnt(3)
	v_mfma_f32_16x16x32_bf16 v[76:79], v[182:185], v[246:249], v[76:79]
	v_mfma_f32_16x16x32_bf16 v[72:75], v[186:189], v[246:249], v[72:75]
	v_mfma_f32_16x16x32_bf16 v[68:71], v[190:193], v[246:249], v[68:71]
	s_waitcnt vmcnt(7)
	v_cndmask_b32_e64 v115, 0, v115, s[2:3]
	v_cndmask_b32_e64 v114, 0, v114, s[2:3]
	v_cndmask_b32_e64 v113, 0, v113, s[2:3]
	v_cndmask_b32_e64 v112, 0, v112, s[2:3]
	ds_write_b128 v252, v[112:115]
	v_mfma_f32_16x16x32_bf16 v[64:67], v[194:197], v[246:249], v[64:67]
	ds_read_b128 v[242:245], v181 offset:13824
	s_waitcnt lgkmcnt(4)
	v_mfma_f32_16x16x32_bf16 v[60:63], v[182:185], v[198:201], v[60:63]
	s_nop 0
	global_load_dwordx4 v[112:115], v178, s[44:45] offset:256
	v_mfma_f32_16x16x32_bf16 v[56:59], v[186:189], v[198:201], v[56:59]
	v_mfma_f32_16x16x32_bf16 v[52:55], v[190:193], v[198:201], v[52:55]
	v_mfma_f32_16x16x32_bf16 v[48:51], v[194:197], v[198:201], v[48:51]
	ds_read_b128 v[246:249], v181 offset:16128
	s_waitcnt lgkmcnt(3)
	v_mfma_f32_16x16x32_bf16 v[44:47], v[182:185], v[202:205], v[44:47]
	s_waitcnt vmcnt(7)
; DI f32x4 mfma16(bf16x8 a, bf16x8 b, f32x4 c) { return __builtin_amdgcn_mfma_f32_16x16x32_bf16(a, b, c, 0, 0, 0); }
; template <int MI, int NJ, bool SWAP, class AP, class BP>
; DI void gemm_main(f32x4 (&acc)[MI][NJ], const AP& ap, int a_kstep, const BP& bp, int b_kstep, int nk, bf16_t* smem) {
;     ...
;   auto gload = [&](int kt) {
;     const bf16_t* ab = ap.base + (size_t)kt * a_kstep; const bf16_t* bb = bp.base + (size_t)kt * b_kstep;
; #pragma unroll
;     for (int i = 0; i < CA; ++i) ra[i] = *(const u32x4*)(ab + pa[i]);
; #pragma unroll
;     for (int i = 0; i < CB; ++i) rb[i] = *(const u32x4*)(bb + pb[i]);
;   };
;   auto sstore = [&](int buf) {
;     bf16_t* As = smem + buf * L::STAGE; bf16_t* Bs = As + L::A_ELEMS;
; #pragma unroll
;     for (int i = 0; i < CA; ++i) { const int c = tid + NTHR * i; *(u32x4*)(As + (c >> 3) * LDT + (c & 7) * 8) = oka[i] ? ra[i] : (u32x4){0u, 0u, 0u, 0u}; }
; #pragma unroll
;     for (int i = 0; i < CB; ++i) { const int c = tid + NTHR * i; *(u32x4*)(Bs + (c >> 3) * LDT + (c & 7) * 8) = rb[i]; }
;   };
;   gload(0); sstore(0); gload(nk > 1 ? 1 : 0); __syncthreads();
; #pragma unroll 1
;   for (int kt = 0; kt < nk; ++kt) {
;     const int buf = kt & 1;
;     sstore(buf ^ 1);
;     gload(kt + 2 < nk ? kt + 2 : nk - 1);
;     __builtin_amdgcn_sched_barrier(0);
;     const bf16_t* As = smem + buf * L::STAGE + (wm * 16 * MI + l15) * LDT + quad * 8;
;     const bf16_t* Bs = smem + buf * L::STAGE + L::A_ELEMS + (wn * 16 * NJ + l15) * LDT + quad * 8;
; #pragma unroll
;     for (int ks = 0; ks < 2; ++ks) {
;       if (MI * NJ >= 32 && ks == 1) asm volatile("" ::: "memory");
;       bf16x8 b[NJ];
; #pragma unroll
;       for (int j = 0; j < NJ; ++j) b[j] = *(const bf16x8*)(Bs + j * 16 * LDT + ks * 32);
; #pragma unroll
;       for (int i = 0; i < MI; ++i) {
;         const bf16x8 a = *(const bf16x8*)(As + i * 16 * LDT + ks * 32);
; #pragma unroll
;         for (int j = 0; j < NJ; ++j) acc[i][j] = SWAP ? mfma16(b[j], a, acc[i][j]) : mfma16(a, b[j], acc[i][j]);
;       }
;     }
;     __syncthreads();
;   }
	v_cndmask_b32_e64 v135, 0, v135, s[4:5]
	v_cndmask_b32_e64 v134, 0, v134, s[4:5]
	v_cndmask_b32_e64 v133, 0, v133, s[4:5]
	v_cndmask_b32_e64 v132, 0, v132, s[4:5]
	ds_write_b128 v253, v[132:135]
	v_mfma_f32_16x16x32_bf16 v[40:43], v[186:189], v[202:205], v[40:43]
	v_mfma_f32_16x16x32_bf16 v[36:39], v[190:193], v[202:205], v[36:39]
	s_nop 0
	global_load_dwordx4 v[132:135], v179, s[44:45] offset:256
	v_mfma_f32_16x16x32_bf16 v[32:35], v[194:197], v[202:205], v[32:35]
	ds_read_b128 v[198:201], v181 offset:64
	s_waitcnt lgkmcnt(3)
	v_mfma_f32_16x16x32_bf16 v[28:31], v[182:185], v[242:245], v[28:31]
	v_mfma_f32_16x16x32_bf16 v[24:27], v[186:189], v[242:245], v[24:27]
	v_mfma_f32_16x16x32_bf16 v[20:23], v[190:193], v[242:245], v[20:23]
	s_waitcnt vmcnt(7)
	ds_write_b128 v250, v[116:119] offset:36864
	v_mfma_f32_16x16x32_bf16 v[12:15], v[194:197], v[242:245], v[12:15]
	ds_read_b128 v[202:205], v181 offset:2368
	s_waitcnt lgkmcnt(4)
	v_mfma_f32_16x16x32_bf16 v[8:11], v[182:185], v[246:249], v[8:11]
	ds_read_b128 v[182:185], v206 offset:36928
	s_add_u32 s44, s20, s47
	s_addc_u32 s45, s21, 0
	v_lshl_add_u64 v[116:117], v[160:161], 1, s[44:45]
	s_nop 0
	global_load_dwordx4 v[116:119], v[116:117], off offset:256
	v_mfma_f32_16x16x32_bf16 v[4:7], v[186:189], v[246:249], v[4:7]
	ds_read_b128 v[186:189], v206 offset:39232
	v_mfma_f32_16x16x32_bf16 v[0:3], v[190:193], v[246:249], v[0:3]
	ds_read_b128 v[190:193], v206 offset:41536
	v_mfma_f32_16x16x32_bf16 v[16:19], v[194:197], v[246:249], v[16:19]
	ds_read_b128 v[194:197], v206 offset:43840
	ds_read_b128 v[242:245], v181 offset:4672
	s_waitcnt lgkmcnt(4)
	v_mfma_f32_16x16x32_bf16 v[156:159], v[182:185], v[198:201], v[156:159]
	s_waitcnt vmcnt(7)
	ds_write_b128 v251, v[120:123] offset:36864
	s_waitcnt lgkmcnt(4)
	v_mfma_f32_16x16x32_bf16 v[152:155], v[186:189], v[198:201], v[152:155]
	s_waitcnt lgkmcnt(3)
	v_mfma_f32_16x16x32_bf16 v[148:151], v[190:193], v[198:201], v[148:151]
	v_lshl_add_u64 v[120:121], v[162:163], 1, s[44:45]
	s_nop 0
	global_load_dwordx4 v[120:123], v[120:121], off offset:256
	s_waitcnt lgkmcnt(2)
	v_mfma_f32_16x16x32_bf16 v[144:147], v[194:197], v[198:201], v[144:147]
	ds_read_b128 v[246:249], v181 offset:6976
	v_mfma_f32_16x16x32_bf16 v[108:111], v[182:185], v[202:205], v[108:111]
	v_mfma_f32_16x16x32_bf16 v[104:107], v[186:189], v[202:205], v[104:107]
	v_mfma_f32_16x16x32_bf16 v[100:103], v[190:193], v[202:205], v[100:103]
	s_waitcnt vmcnt(7)
	ds_write_b128 v252, v[124:127] offset:36864
	v_mfma_f32_16x16x32_bf16 v[96:99], v[194:197], v[202:205], v[96:99]
	ds_read_b128 v[198:201], v181 offset:9280
	s_waitcnt lgkmcnt(4)
	v_mfma_f32_16x16x32_bf16 v[92:95], v[182:185], v[242:245], v[92:95]
	v_lshl_add_u64 v[124:125], v[164:165], 1, s[44:45]
	s_nop 0
	global_load_dwordx4 v[124:127], v[124:125], off offset:256
	v_mfma_f32_16x16x32_bf16 v[88:91], v[186:189], v[242:245], v[88:91]
	v_mfma_f32_16x16x32_bf16 v[84:87], v[190:193], v[242:245], v[84:87]
	v_mfma_f32_16x16x32_bf16 v[80:83], v[194:197], v[242:245], v[80:83]
	ds_read_b128 v[202:205], v181 offset:11584
	s_waitcnt lgkmcnt(3)
	v_mfma_f32_16x16x32_bf16 v[76:79], v[182:185], v[246:249], v[76:79]
	s_waitcnt vmcnt(7)
	ds_write_b128 v253, v[136:139] offset:36864
	v_mfma_f32_16x16x32_bf16 v[72:75], v[186:189], v[246:249], v[72:75]
	v_mfma_f32_16x16x32_bf16 v[68:71], v[190:193], v[246:249], v[68:71]
	v_lshl_add_u64 v[136:137], v[166:167], 1, s[44:45]
	s_nop 0
	global_load_dwordx4 v[136:139], v[136:137], off offset:256
	v_mfma_f32_16x16x32_bf16 v[64:67], v[194:197], v[246:249], v[64:67]
	ds_read_b128 v[242:245], v181 offset:13888
	s_waitcnt lgkmcnt(3)
	v_mfma_f32_16x16x32_bf16 v[60:63], v[182:185], v[198:201], v[60:63]
	v_mfma_f32_16x16x32_bf16 v[56:59], v[186:189], v[198:201], v[56:59]
	v_mfma_f32_16x16x32_bf16 v[52:55], v[190:193], v[198:201], v[52:55]
	v_mfma_f32_16x16x32_bf16 v[48:51], v[194:197], v[198:201], v[48:51]
	ds_read_b128 v[246:249], v181 offset:16192
	s_waitcnt lgkmcnt(3)
	v_mfma_f32_16x16x32_bf16 v[44:47], v[182:185], v[202:205], v[44:47]
	v_mfma_f32_16x16x32_bf16 v[40:43], v[186:189], v[202:205], v[40:43]
	v_mfma_f32_16x16x32_bf16 v[36:39], v[190:193], v[202:205], v[36:39]
	v_mfma_f32_16x16x32_bf16 v[32:35], v[194:197], v[202:205], v[32:35]
	s_add_i32 s43, s43, 1
	s_and_b32 s98, s43, 1
	s_mul_i32 s98, s98, 0x12000
	v_add3_u32 v206, s98, v171, v180
	v_add3_u32 v181, s98, v170, v180
	s_cmp_lg_u32 s43, 16
	s_waitcnt lgkmcnt(0)
	s_barrier
	s_cbranch_scc1 .Lgm14_top

; DI f32x4 mfma16(bf16x8 a, bf16x8 b, f32x4 c) { return __builtin_amdgcn_mfma_f32_16x16x32_bf16(a, b, c, 0, 0, 0); }
; template <int MI, int NJ, bool SWAP, class AP, class BP>
; DI void gemm_main(f32x4 (&acc)[MI][NJ], const AP& ap, int a_kstep, const BP& bp, int b_kstep, int nk, bf16_t* smem) {
;     ...
;   for (int kt = 0; kt < nk; ++kt) {
;     const int buf = kt & 1;
;     sstore(buf ^ 1);
;     gload(kt + 2 < nk ? kt + 2 : nk - 1);
;     __builtin_amdgcn_sched_barrier(0);
;     const bf16_t* As = smem + buf * L::STAGE + (wm * 16 * MI + l15) * LDT + quad * 8;
;     const bf16_t* Bs = smem + buf * L::STAGE + L::A_ELEMS + (wn * 16 * NJ + l15) * LDT + quad * 8;
; #pragma unroll
;     for (int ks = 0; ks < 2; ++ks) {
;       if (MI * NJ >= 32 && ks == 1) asm volatile("" ::: "memory");
;       bf16x8 b[NJ];
; #pragma unroll
;       for (int j = 0; j < NJ; ++j) b[j] = *(const bf16x8*)(Bs + j * 16 * LDT + ks * 32);
; #pragma unroll
;       for (int i = 0; i < MI; ++i) {
;         const bf16x8 a = *(const bf16x8*)(As + i * 16 * LDT + ks * 32);
; #pragma unroll
;         for (int j = 0; j < NJ; ++j) acc[i][j] = SWAP ? mfma16(b[j], a, acc[i][j]) : mfma16(a, b[j], acc[i][j]);
.LBB0_2163:
	s_and_b32 s98, s16, 1
	s_mul_i32 s98, s98, 0x12000
	v_add3_u32 v202, s98, v160, v176
	v_add3_u32 v177, s98, v171, v176
	ds_read_b128 v[194:197], v177
	ds_read_b128 v[198:201], v177 offset:2304
	ds_read_b128 v[178:181], v202 offset:36864
	ds_read_b128 v[182:185], v202 offset:39168
	ds_read_b128 v[186:189], v202 offset:41472
	ds_read_b128 v[190:193], v202 offset:43776
	s_branch .Lgm15_main

; DI f32x4 mfma16(bf16x8 a, bf16x8 b, f32x4 c) { return __builtin_amdgcn_mfma_f32_16x16x32_bf16(a, b, c, 0, 0, 0); }
; template <int MI, int NJ, bool SWAP, class AP, class BP>
; DI void gemm_main(f32x4 (&acc)[MI][NJ], const AP& ap, int a_kstep, const BP& bp, int b_kstep, int nk, bf16_t* smem) {
;     ...
;   auto gload = [&](int kt) {
;     const bf16_t* ab = ap.base + (size_t)kt * a_kstep; const bf16_t* bb = bp.base + (size_t)kt * b_kstep;
; #pragma unroll
;     for (int i = 0; i < CA; ++i) ra[i] = *(const u32x4*)(ab + pa[i]);
; #pragma unroll
;     for (int i = 0; i < CB; ++i) rb[i] = *(const u32x4*)(bb + pb[i]);
;   };
;   auto sstore = [&](int buf) {
;     bf16_t* As = smem + buf * L::STAGE; bf16_t* Bs = As + L::A_ELEMS;
; #pragma unroll
;     for (int i = 0; i < CA; ++i) { const int c = tid + NTHR * i; *(u32x4*)(As + (c >> 3) * LDT + (c & 7) * 8) = oka[i] ? ra[i] : (u32x4){0u, 0u, 0u, 0u}; }
; #pragma unroll
;     for (int i = 0; i < CB; ++i) { const int c = tid + NTHR * i; *(u32x4*)(Bs + (c >> 3) * LDT + (c & 7) * 8) = rb[i]; }
;   };
;   gload(0); sstore(0); gload(nk > 1 ? 1 : 0); __syncthreads();
; #pragma unroll 1
;   for (int kt = 0; kt < nk; ++kt) {
;     const int buf = kt & 1;
;     sstore(buf ^ 1);
;     gload(kt + 2 < nk ? kt + 2 : nk - 1);
;     __builtin_amdgcn_sched_barrier(0);
;     const bf16_t* As = smem + buf * L::STAGE + (wm * 16 * MI + l15) * LDT + quad * 8;
;     const bf16_t* Bs = smem + buf * L::STAGE + L::A_ELEMS + (wn * 16 * NJ + l15) * LDT + quad * 8;
; #pragma unroll
;     for (int ks = 0; ks < 2; ++ks) {
;       if (MI * NJ >= 32 && ks == 1) asm volatile("" ::: "memory");
;       bf16x8 b[NJ];
; #pragma unroll
;       for (int j = 0; j < NJ; ++j) b[j] = *(const bf16x8*)(Bs + j * 16 * LDT + ks * 32);
; #pragma unroll
;       for (int i = 0; i < MI; ++i) {
;         const bf16x8 a = *(const bf16x8*)(As + i * 16 * LDT + ks * 32);
; #pragma unroll
;         for (int j = 0; j < NJ; ++j) acc[i][j] = SWAP ? mfma16(b[j], a, acc[i][j]) : mfma16(a, b[j], acc[i][j]);
.Lgm15_main:
	ds_read_b128 v[242:245], v177 offset:4608
	s_waitcnt lgkmcnt(4)
	v_mfma_f32_16x16x32_bf16 v[156:159], v[178:181], v[194:197], v[156:159]
	s_waitcnt lgkmcnt(3)
	v_mfma_f32_16x16x32_bf16 v[152:155], v[182:185], v[194:197], v[152:155]
	s_waitcnt lgkmcnt(2)
	v_mfma_f32_16x16x32_bf16 v[148:151], v[186:189], v[194:197], v[148:151]
	s_and_b32 s17, s16, 1
	s_min_u32 s18, s16, 41
	s_xor_b32 s19, s17, 1
	s_mul_i32 s19, s19, 0x12000
	v_add3_u32 v250, s19, v172, v170
	s_waitcnt vmcnt(7)
	ds_write_b128 v250, v[112:115]
	s_waitcnt lgkmcnt(2)
	v_mfma_f32_16x16x32_bf16 v[144:147], v[190:193], v[194:197], v[144:147]
	ds_read_b128 v[246:249], v177 offset:6912
	v_mfma_f32_16x16x32_bf16 v[108:111], v[178:181], v[198:201], v[108:111]
	s_lshl_b32 s20, s18, 7
	s_add_u32 s18, s2, s20
	v_add3_u32 v251, s19, v173, v170
	v_add3_u32 v252, s19, v174, v170
	v_add3_u32 v253, s19, v175, v170
	s_addc_u32 s19, s3, 0
	v_lshl_add_u64 v[112:113], s[18:19], 0, v[162:163]
	s_nop 0
	global_load_dwordx4 v[112:115], v[112:113], off offset:256
	v_mfma_f32_16x16x32_bf16 v[104:107], v[182:185], v[198:201], v[104:107]
	v_mfma_f32_16x16x32_bf16 v[100:103], v[186:189], v[198:201], v[100:103]
	v_mfma_f32_16x16x32_bf16 v[96:99], v[190:193], v[198:201], v[96:99]
	ds_read_b128 v[194:197], v177 offset:9216
	s_waitcnt lgkmcnt(3)
	v_mfma_f32_16x16x32_bf16 v[92:95], v[178:181], v[242:245], v[92:95]
	s_waitcnt vmcnt(7)
	ds_write_b128 v251, v[116:119]
	v_mfma_f32_16x16x32_bf16 v[88:91], v[182:185], v[242:245], v[88:91]
	v_mfma_f32_16x16x32_bf16 v[84:87], v[186:189], v[242:245], v[84:87]
	v_lshl_add_u64 v[116:117], s[18:19], 0, v[164:165]
	s_nop 0
	global_load_dwordx4 v[116:119], v[116:117], off offset:256
	v_mfma_f32_16x16x32_bf16 v[80:83], v[190:193], v[242:245], v[80:83]
	ds_read_b128 v[198:201], v177 offset:11520
	s_waitcnt lgkmcnt(3)
	v_mfma_f32_16x16x32_bf16 v[76:79], v[178:181], v[246:249], v[76:79]
	v_mfma_f32_16x16x32_bf16 v[72:75], v[182:185], v[246:249], v[72:75]
	v_mfma_f32_16x16x32_bf16 v[68:71], v[186:189], v[246:249], v[68:71]
	s_waitcnt vmcnt(7)
	ds_write_b128 v252, v[120:123]
	v_mfma_f32_16x16x32_bf16 v[64:67], v[190:193], v[246:249], v[64:67]
	ds_read_b128 v[242:245], v177 offset:13824
	s_waitcnt lgkmcnt(4)
	v_mfma_f32_16x16x32_bf16 v[60:63], v[178:181], v[194:197], v[60:63]
	v_lshl_add_u64 v[120:121], s[18:19], 0, v[166:167]
	s_nop 0
	global_load_dwordx4 v[120:123], v[120:121], off offset:256
	v_mfma_f32_16x16x32_bf16 v[56:59], v[182:185], v[194:197], v[56:59]
	v_mfma_f32_16x16x32_bf16 v[52:55], v[186:189], v[194:197], v[52:55]
	v_mfma_f32_16x16x32_bf16 v[48:51], v[190:193], v[194:197], v[48:51]
	ds_read_b128 v[246:249], v177 offset:16128
	s_waitcnt lgkmcnt(3)
	v_mfma_f32_16x16x32_bf16 v[44:47], v[178:181], v[198:201], v[44:47]
	s_waitcnt vmcnt(7)
	ds_write_b128 v253, v[124:127]
	v_mfma_f32_16x16x32_bf16 v[40:43], v[182:185], v[198:201], v[40:43]
	v_mfma_f32_16x16x32_bf16 v[36:39], v[186:189], v[198:201], v[36:39]
	v_lshl_add_u64 v[124:125], s[18:19], 0, v[168:169]
	s_nop 0
	global_load_dwordx4 v[124:127], v[124:125], off offset:256
	v_mfma_f32_16x16x32_bf16 v[32:35], v[190:193], v[198:201], v[32:35]
	ds_read_b128 v[194:197], v177 offset:64
	s_waitcnt lgkmcnt(3)
	v_mfma_f32_16x16x32_bf16 v[28:31], v[178:181], v[242:245], v[28:31]
	v_mfma_f32_16x16x32_bf16 v[24:27], v[182:185], v[242:245], v[24:27]
	v_mfma_f32_16x16x32_bf16 v[20:23], v[186:189], v[242:245], v[20:23]
	s_waitcnt vmcnt(7)
	ds_write_b128 v250, v[128:131] offset:36864
	v_mfma_f32_16x16x32_bf16 v[16:19], v[190:193], v[242:245], v[16:19]
	ds_read_b128 v[198:201], v177 offset:2368
	s_waitcnt lgkmcnt(4)
; DI f32x4 mfma16(bf16x8 a, bf16x8 b, f32x4 c) { return __builtin_amdgcn_mfma_f32_16x16x32_bf16(a, b, c, 0, 0, 0); }
; template <int MI, int NJ, bool SWAP, class AP, class BP>
; DI void gemm_main(f32x4 (&acc)[MI][NJ], const AP& ap, int a_kstep, const BP& bp, int b_kstep, int nk, bf16_t* smem) {
;     ...
;   for (int kt = 0; kt < nk; ++kt) {
;     const int buf = kt & 1;
;     sstore(buf ^ 1);
;     gload(kt + 2 < nk ? kt + 2 : nk - 1);
;     __builtin_amdgcn_sched_barrier(0);
;     const bf16_t* As = smem + buf * L::STAGE + (wm * 16 * MI + l15) * LDT + quad * 8;
;     const bf16_t* Bs = smem + buf * L::STAGE + L::A_ELEMS + (wn * 16 * NJ + l15) * LDT + quad * 8;
; #pragma unroll
;     for (int ks = 0; ks < 2; ++ks) {
;       if (MI * NJ >= 32 && ks == 1) asm volatile("" ::: "memory");
;       bf16x8 b[NJ];
; #pragma unroll
;       for (int j = 0; j < NJ; ++j) b[j] = *(const bf16x8*)(Bs + j * 16 * LDT + ks * 32);
; #pragma unroll
;       for (int i = 0; i < MI; ++i) {
;         const bf16x8 a = *(const bf16x8*)(As + i * 16 * LDT + ks * 32);
; #pragma unroll
;         for (int j = 0; j < NJ; ++j) acc[i][j] = SWAP ? mfma16(b[j], a, acc[i][j]) : mfma16(a, b[j], acc[i][j]);
;       }
;     }
;     __syncthreads();
;   }
	v_mfma_f32_16x16x32_bf16 v[8:11], v[178:181], v[246:249], v[8:11]
	ds_read_b128 v[178:181], v202 offset:36928
	s_add_u32 s18, s4, s20
	s_addc_u32 s19, s5, 0
	v_lshl_add_u64 v[128:129], s[18:19], 0, v[162:163]
	s_nop 0
	global_load_dwordx4 v[128:131], v[128:129], off offset:256
	v_mfma_f32_16x16x32_bf16 v[4:7], v[182:185], v[246:249], v[4:7]
	ds_read_b128 v[182:185], v202 offset:39232
	v_mfma_f32_16x16x32_bf16 v[0:3], v[186:189], v[246:249], v[0:3]
	ds_read_b128 v[186:189], v202 offset:41536
	v_mfma_f32_16x16x32_bf16 v[12:15], v[190:193], v[246:249], v[12:15]
	ds_read_b128 v[190:193], v202 offset:43840
	ds_read_b128 v[242:245], v177 offset:4672
	s_waitcnt lgkmcnt(4)
	v_mfma_f32_16x16x32_bf16 v[156:159], v[178:181], v[194:197], v[156:159]
	s_waitcnt vmcnt(7)
	ds_write_b128 v251, v[132:135] offset:36864
	s_waitcnt lgkmcnt(4)
	v_mfma_f32_16x16x32_bf16 v[152:155], v[182:185], v[194:197], v[152:155]
	s_waitcnt lgkmcnt(3)
	v_mfma_f32_16x16x32_bf16 v[148:151], v[186:189], v[194:197], v[148:151]
	v_lshl_add_u64 v[132:133], s[18:19], 0, v[164:165]
	s_nop 0
	global_load_dwordx4 v[132:135], v[132:133], off offset:256
	s_waitcnt lgkmcnt(2)
	v_mfma_f32_16x16x32_bf16 v[144:147], v[190:193], v[194:197], v[144:147]
	ds_read_b128 v[246:249], v177 offset:6976
	v_mfma_f32_16x16x32_bf16 v[108:111], v[178:181], v[198:201], v[108:111]
	v_mfma_f32_16x16x32_bf16 v[104:107], v[182:185], v[198:201], v[104:107]
	v_mfma_f32_16x16x32_bf16 v[100:103], v[186:189], v[198:201], v[100:103]
	s_waitcnt vmcnt(7)
	ds_write_b128 v252, v[136:139] offset:36864
	v_mfma_f32_16x16x32_bf16 v[96:99], v[190:193], v[198:201], v[96:99]
	ds_read_b128 v[194:197], v177 offset:9280
	s_waitcnt lgkmcnt(4)
	v_mfma_f32_16x16x32_bf16 v[92:95], v[178:181], v[242:245], v[92:95]
	v_lshl_add_u64 v[136:137], s[18:19], 0, v[166:167]
	s_nop 0
	global_load_dwordx4 v[136:139], v[136:137], off offset:256
	v_mfma_f32_16x16x32_bf16 v[88:91], v[182:185], v[242:245], v[88:91]
	v_mfma_f32_16x16x32_bf16 v[84:87], v[186:189], v[242:245], v[84:87]
	v_mfma_f32_16x16x32_bf16 v[80:83], v[190:193], v[242:245], v[80:83]
	ds_read_b128 v[198:201], v177 offset:11584
	s_waitcnt lgkmcnt(3)
	v_mfma_f32_16x16x32_bf16 v[76:79], v[178:181], v[246:249], v[76:79]
	s_waitcnt vmcnt(7)
	ds_write_b128 v253, v[140:143] offset:36864
	v_mfma_f32_16x16x32_bf16 v[72:75], v[182:185], v[246:249], v[72:75]
	v_mfma_f32_16x16x32_bf16 v[68:71], v[186:189], v[246:249], v[68:71]
	v_lshl_add_u64 v[140:141], s[18:19], 0, v[168:169]
	s_nop 0
	global_load_dwordx4 v[140:143], v[140:141], off offset:256
	v_mfma_f32_16x16x32_bf16 v[64:67], v[190:193], v[246:249], v[64:67]
	ds_read_b128 v[242:245], v177 offset:13888
	s_waitcnt lgkmcnt(3)
	v_mfma_f32_16x16x32_bf16 v[60:63], v[178:181], v[194:197], v[60:63]
	v_mfma_f32_16x16x32_bf16 v[56:59], v[182:185], v[194:197], v[56:59]
	v_mfma_f32_16x16x32_bf16 v[52:55], v[186:189], v[194:197], v[52:55]
	v_mfma_f32_16x16x32_bf16 v[48:51], v[190:193], v[194:197], v[48:51]
	ds_read_b128 v[246:249], v177 offset:16192
	s_waitcnt lgkmcnt(3)
	v_mfma_f32_16x16x32_bf16 v[44:47], v[178:181], v[198:201], v[44:47]
	v_mfma_f32_16x16x32_bf16 v[40:43], v[182:185], v[198:201], v[40:43]
	v_mfma_f32_16x16x32_bf16 v[36:39], v[186:189], v[198:201], v[36:39]
	v_mfma_f32_16x16x32_bf16 v[32:35], v[190:193], v[198:201], v[32:35]
	s_add_i32 s16, s16, 1
	s_and_b32 s98, s16, 1
	s_mul_i32 s98, s98, 0x12000
	v_add3_u32 v202, s98, v160, v176
	v_add3_u32 v177, s98, v171, v176
	s_cmp_lg_u32 s16, 44
	s_waitcnt lgkmcnt(0)
	s_barrier
	s_cbranch_scc1 .Lgm15_top
